# DSA attention gathers: one counted LDS wait per four row-offset reads instead of one per gather (48 fewer wait instructions per token), on the full-nsel fast-path version
# baseline (speedup 1.0000x reference)
;   __device__ __forceinline__ half_t* mm() const { return (half_t*)(ws() + OFF_mm); }
; __device__ __forceinline__ void dsa_item(const KP& p, int b, int tile, char* smem) {
;     ...
;     const int nsel = min(cnt[tk], 256);
;     const half_t* urow = ub + (size_t)t * NU;
;     const int col = lane & 15;
;     h8 q0, q1;
; #pragma unroll
;     for (int e = 0; e < 8; ++e) { q0[e] = (half_t)0.f; q1[e] = (half_t)0.f; }
;     if (col < 8) {
;       q0 = *(const h8*)(urow + C_BQ + col * 64 + hq * 8);
;       q1 = *(const h8*)(urow + C_BQ + col * 64 + 32 + hq * 8);
;     }
;     float mx = NEGF;
; #pragma unroll 1
;     for (int mg = 0; mg < 2; ++mg) {
; #pragma unroll
;       for (int mm = 0; mm < 8; ++mm) {
;         const int m = mg * 8 + mm;
;         const int pos = m * 16 + col;
;         const int s = (pos < nsel) ? (int)sel[tk * 256 + pos] : 0;
;         const half_t* kp = ub + (size_t)s * NU + C_BK + hq * 8;
.LBB0_1427:
	s_or_b64 exec, exec, s[2:3]
	s_waitcnt lgkmcnt(0)
	v_min_i32_e32 v85, 0x100, v11
	v_lshlrev_b32_e32 v14, 9, v10
	v_mov_b32_e32 v15, 0xf149f2ca
	s_add_u32 s14, s78, 0x3800
	s_addc_u32 s15, s79, 0
	v_add_u32_e32 v203, v126, v157
	v_lshl_add_u32 v80, v203, 1, v14
	ds_read_u16 v172, v80 offset:32768
	ds_read_u16 v173, v80 offset:32896
	ds_read_u16 v174, v80 offset:33024
	ds_read_u16 v175, v80 offset:33152
	v_and_b32_e32 v200, 7, v157
	v_lshlrev_b32_e32 v200, 4, v200
	v_mul_u32_u24_e32 v201, 0x240, v159
	v_add_u32_e32 v201, 0xa800, v201
	v_mul_u32_u24_e32 v198, 0x90, v165
	v_add3_u32 v198, v198, v200, v201
	v_mul_u32_u24_e32 v199, 0x90, v157
	v_add3_u32 v199, v199, v126, v201
	v_lshlrev_b32_e32 v202, 8, v159
	v_add_u32_e32 v202, 0xcc00, v202
	v_lshl_add_u32 v81, v203, 2, v202
	v_add_u32_e32 v171, -1, v85
	v_add_u32_e32 v156, -2, v85
	v_add_u32_e32 v158, -3, v85
	v_cmp_lt_i32_e32 vcc, v203, v85
	s_waitcnt lgkmcnt(3)
	s_nop 0
	v_cndmask_b32_e32 v172, 0, v172, vcc
	v_mul_u32_u24_e32 v172, 0x3a00, v172
	ds_write_b32 v81, v172
	v_add_u32_e32 v201, 64, v203
	v_cmp_lt_i32_e32 vcc, v201, v85
	s_waitcnt lgkmcnt(2)
	s_nop 0
	v_cndmask_b32_e32 v173, 0, v173, vcc
	v_mul_u32_u24_e32 v173, 0x3a00, v173
	ds_write_b32 v81, v173 offset:256
	v_add_u32_e32 v201, 0x80, v203
	v_cmp_lt_i32_e32 vcc, v201, v85
	s_waitcnt lgkmcnt(1)
	s_nop 0
	v_cndmask_b32_e32 v174, 0, v174, vcc
	v_mul_u32_u24_e32 v174, 0x3a00, v174
	ds_write_b32 v81, v174 offset:512
	v_add_u32_e32 v201, 0xc0, v203
	v_cmp_lt_i32_e32 vcc, v201, v85
	s_waitcnt lgkmcnt(0)
	s_nop 0
	v_cndmask_b32_e32 v175, 0, v175, vcc
	v_mul_u32_u24_e32 v175, 0x3a00, v175
	ds_write_b32 v81, v175 offset:768
	v_lshl_add_u32 v202, v165, 2, v202
	ds_read_b32 v172, v202
	ds_read_b32 v173, v202 offset:64
	ds_read_b32 v174, v202 offset:128
	ds_read_b32 v175, v202 offset:192
	ds_read_b32 v176, v202 offset:256
	ds_read_b32 v177, v202 offset:320
	ds_read_b32 v178, v202 offset:384
	ds_read_b32 v179, v202 offset:448
	ds_read_b32 v180, v202 offset:512
	ds_read_b32 v181, v202 offset:576
	ds_read_b32 v188, v202 offset:640
	ds_read_b32 v189, v202 offset:704
	ds_read_b32 v190, v202 offset:768
	ds_read_b32 v191, v202 offset:832
	ds_read_b32 v192, v202 offset:896
	ds_read_b32 v193, v202 offset:960
	s_waitcnt lgkmcnt(12)
	v_add_u32_e32 v172, v172, v200
	global_load_dwordx4 v[16:19], v172, s[14:15]
	v_add_u32_e32 v173, v173, v200
	global_load_dwordx4 v[24:27], v173, s[14:15]
	v_add_u32_e32 v174, v174, v200
	global_load_dwordx4 v[32:35], v174, s[14:15]
	v_add_u32_e32 v175, v175, v200
	global_load_dwordx4 v[40:43], v175, s[14:15]
	s_waitcnt lgkmcnt(8)
	v_add_u32_e32 v176, v176, v200
	global_load_dwordx4 v[48:51], v176, s[14:15]
	v_add_u32_e32 v177, v177, v200
	global_load_dwordx4 v[56:59], v177, s[14:15]
	v_add_u32_e32 v178, v178, v200
	global_load_dwordx4 v[64:67], v178, s[14:15]
	v_add_u32_e32 v179, v179, v200
	global_load_dwordx4 v[72:75], v179, s[14:15]
	s_waitcnt lgkmcnt(4)
	v_add_u32_e32 v180, v180, v200
	global_load_dwordx4 v[90:93], v180, s[14:15]
	v_add_u32_e32 v181, v181, v200
	global_load_dwordx4 v[98:101], v181, s[14:15]
	v_add_u32_e32 v188, v188, v200
	global_load_dwordx4 v[106:109], v188, s[14:15]
	v_add_u32_e32 v189, v189, v200
	global_load_dwordx4 v[114:117], v189, s[14:15]
	s_waitcnt lgkmcnt(0)
	v_add_u32_e32 v190, v190, v200
	global_load_dwordx4 v[122:125], v190, s[14:15]
	v_add_u32_e32 v191, v191, v200
	global_load_dwordx4 v[132:135], v191, s[14:15]
	v_add_u32_e32 v192, v192, v200
	global_load_dwordx4 v[140:143], v192, s[14:15]
	v_add_u32_e32 v193, v193, v200
	global_load_dwordx4 v[148:151], v193, s[14:15]
	ds_read_b32 v172, v202 offset:32
	ds_read_b32 v173, v202 offset:96
	ds_read_b32 v174, v202 offset:160
	ds_read_b32 v175, v202 offset:224
	ds_read_b32 v176, v202 offset:288
	ds_read_b32 v177, v202 offset:352
	ds_read_b32 v178, v202 offset:416
	ds_read_b32 v179, v202 offset:480
	ds_read_b32 v180, v202 offset:544
	ds_read_b32 v181, v202 offset:608
	ds_read_b32 v188, v202 offset:672
	ds_read_b32 v189, v202 offset:736
	ds_read_b32 v190, v202 offset:800
	ds_read_b32 v191, v202 offset:864
	ds_read_b32 v192, v202 offset:928
	ds_read_b32 v193, v202 offset:992
	s_waitcnt lgkmcnt(12)
	v_add_u32_e32 v172, v172, v200
	global_load_dwordx4 v[20:23], v172, s[14:15]
	v_add_u32_e32 v173, v173, v200
	global_load_dwordx4 v[28:31], v173, s[14:15]
	v_add_u32_e32 v174, v174, v200
	global_load_dwordx4 v[36:39], v174, s[14:15]
	v_add_u32_e32 v175, v175, v200
	global_load_dwordx4 v[44:47], v175, s[14:15]
	s_waitcnt lgkmcnt(8)
	v_add_u32_e32 v176, v176, v200
	global_load_dwordx4 v[52:55], v176, s[14:15]
	v_add_u32_e32 v177, v177, v200
	global_load_dwordx4 v[60:63], v177, s[14:15]
	v_add_u32_e32 v178, v178, v200
	global_load_dwordx4 v[68:71], v178, s[14:15]
	v_add_u32_e32 v179, v179, v200
	global_load_dwordx4 v[76:79], v179, s[14:15]
	s_waitcnt lgkmcnt(4)
	v_add_u32_e32 v180, v180, v200
	global_load_dwordx4 v[94:97], v180, s[14:15]
	v_add_u32_e32 v181, v181, v200
	global_load_dwordx4 v[102:105], v181, s[14:15]
	v_add_u32_e32 v188, v188, v200
	global_load_dwordx4 v[110:113], v188, s[14:15]
	v_add_u32_e32 v189, v189, v200
	global_load_dwordx4 v[118:121], v189, s[14:15]
	s_waitcnt lgkmcnt(0)
	v_add_u32_e32 v190, v190, v200
	global_load_dwordx4 v[128:131], v190, s[14:15]
	v_add_u32_e32 v191, v191, v200
	global_load_dwordx4 v[136:139], v191, s[14:15]
	v_add_u32_e32 v192, v192, v200
	global_load_dwordx4 v[144:147], v192, s[14:15]
	v_add_u32_e32 v193, v193, v200
	global_load_dwordx4 v[152:155], v193, s[14:15]
	v_readfirstlane_b32 s2, v85
	s_nop 1
	s_cmp_eq_u32 s2, 0x100
	s_cbranch_scc1 .Lqk_full
;   __device__ __forceinline__ half_t* mm() const { return (half_t*)(ws() + OFF_mm); }
; __device__ __forceinline__ void dsa_item(const KP& p, int b, int tile, char* smem) {
;     ...
;     for (int mg = 0; mg < 2; ++mg) {
; #pragma unroll
;       for (int mm = 0; mm < 8; ++mm) {
;         const int m = mg * 8 + mm;
;         const int pos = m * 16 + col;
;         const int s = (pos < nsel) ? (int)sel[tk * 256 + pos] : 0;
;         const half_t* kp = ub + (size_t)s * NU + C_BK + hq * 8;
;         const h8 a0 = *(const h8*)kp, a1 = *(const h8*)(kp + 32);
;         f32x4 d = {0.f, 0.f, 0.f, 0.f};
;         d = __builtin_amdgcn_mfma_f32_16x16x32_f16(a0, q0, d, 0, 0, 0);
;         d = __builtin_amdgcn_mfma_f32_16x16x32_f16(a1, q1, d, 0, 0, 0);
; #pragma unroll
;         for (int r = 0; r < 4; ++r) {
;           const int pp = m * 16 + hq * 4 + r;
;           const float v = (pp < nsel) ? d[r] * 0.125f : NEGF;
;           mx = fmaxf(mx, v);
;           if (col < 8) pbuf[pp * 8 + col] = v;
;         }
;       }
	s_waitcnt vmcnt(15)
	ds_write_b128 v198, v[16:19]
	ds_write_b128 v198, v[20:23] offset:1152
	ds_read_b128 v[16:19], v199
	ds_read_b128 v[20:23], v199 offset:64
	s_waitcnt vmcnt(14)
	ds_write_b128 v198, v[24:27]
	ds_write_b128 v198, v[28:31] offset:1152
	ds_read_b128 v[24:27], v199
	ds_read_b128 v[28:31], v199 offset:64
	s_waitcnt lgkmcnt(4)
	v_mfma_f32_16x16x32_f16 v[10:13], v[16:19], v[6:9], 0
	v_mfma_f32_16x16x32_f16 v[10:13], v[20:23], v[2:5], v[10:13]
	s_nop 4
	s_waitcnt vmcnt(13)
	ds_write_b128 v198, v[32:35]
	ds_write_b128 v198, v[36:39] offset:1152
	ds_read_b128 v[32:35], v199
	ds_read_b128 v[36:39], v199 offset:64
	s_waitcnt lgkmcnt(4)
	v_mfma_f32_16x16x32_f16 v[194:197], v[24:27], v[6:9], 0
	v_mfma_f32_16x16x32_f16 v[194:197], v[28:31], v[2:5], v[194:197]
	v_or_b32_e32 v80, 0, v160
	v_mul_f32_e32 v10, 0x3e000000, v10
	v_mul_f32_e32 v11, 0x3e000000, v11
	v_mul_f32_e32 v12, 0x3e000000, v12
	v_mul_f32_e32 v13, 0x3e000000, v13
	v_cmp_lt_i32_e32 vcc, v80, v85
	v_cmp_lt_i32_e64 s[46:47], v80, v171
	v_lshl_add_u32 v81, v80, 5, v167
	s_nop 0
	v_cndmask_b32_e32 v10, v242, v10, vcc
	v_cndmask_b32_e64 v11, v242, v11, s[46:47]
	v_cmp_lt_i32_e32 vcc, v80, v156
	v_cmp_lt_i32_e64 s[46:47], v80, v158
	v_max3_f32 v15, v15, v10, v11
	s_nop 0
	v_cndmask_b32_e32 v12, v242, v12, vcc
	v_cndmask_b32_e64 v13, v242, v13, s[46:47]
	v_max3_f32 v15, v15, v12, v13
	s_and_saveexec_b64 s[2:3], s[38:39]
	ds_write_b32 v81, v10
	ds_write_b32 v81, v11 offset:32
	ds_write_b32 v81, v12 offset:64
	ds_write_b32 v81, v13 offset:96
	s_or_b64 exec, exec, s[2:3]
	s_waitcnt vmcnt(12)
	ds_write_b128 v198, v[40:43]
	ds_write_b128 v198, v[44:47] offset:1152
	ds_read_b128 v[40:43], v199
	ds_read_b128 v[44:47], v199 offset:64
	s_waitcnt lgkmcnt(8)
	v_mfma_f32_16x16x32_f16 v[10:13], v[32:35], v[6:9], 0
	v_mfma_f32_16x16x32_f16 v[10:13], v[36:39], v[2:5], v[10:13]
	v_or_b32_e32 v80, 16, v160
	v_mul_f32_e32 v194, 0x3e000000, v194
	v_mul_f32_e32 v195, 0x3e000000, v195
	v_mul_f32_e32 v196, 0x3e000000, v196
	v_mul_f32_e32 v197, 0x3e000000, v197
	v_cmp_lt_i32_e32 vcc, v80, v85
	v_cmp_lt_i32_e64 s[46:47], v80, v171
	v_lshl_add_u32 v81, v80, 5, v167
	s_nop 0
	v_cndmask_b32_e32 v194, v242, v194, vcc
	v_cndmask_b32_e64 v195, v242, v195, s[46:47]
	v_cmp_lt_i32_e32 vcc, v80, v156
	v_cmp_lt_i32_e64 s[46:47], v80, v158
	v_max3_f32 v15, v15, v194, v195
	s_nop 0
	v_cndmask_b32_e32 v196, v242, v196, vcc
	v_cndmask_b32_e64 v197, v242, v197, s[46:47]
	v_max3_f32 v15, v15, v196, v197
	s_and_saveexec_b64 s[2:3], s[38:39]
	ds_write_b32 v81, v194
	ds_write_b32 v81, v195 offset:32
	ds_write_b32 v81, v196 offset:64
	ds_write_b32 v81, v197 offset:96
	s_or_b64 exec, exec, s[2:3]
	s_waitcnt vmcnt(11)
	ds_write_b128 v198, v[48:51]
	ds_write_b128 v198, v[52:55] offset:1152
	ds_read_b128 v[48:51], v199
	ds_read_b128 v[52:55], v199 offset:64
	s_waitcnt lgkmcnt(8)
	v_mfma_f32_16x16x32_f16 v[194:197], v[40:43], v[6:9], 0
	v_mfma_f32_16x16x32_f16 v[194:197], v[44:47], v[2:5], v[194:197]
	v_or_b32_e32 v80, 32, v160
	v_mul_f32_e32 v10, 0x3e000000, v10
	v_mul_f32_e32 v11, 0x3e000000, v11
	v_mul_f32_e32 v12, 0x3e000000, v12
	v_mul_f32_e32 v13, 0x3e000000, v13
	v_cmp_lt_i32_e32 vcc, v80, v85
	v_cmp_lt_i32_e64 s[46:47], v80, v171
	v_lshl_add_u32 v81, v80, 5, v167
	s_nop 0
	v_cndmask_b32_e32 v10, v242, v10, vcc
	v_cndmask_b32_e64 v11, v242, v11, s[46:47]
	v_cmp_lt_i32_e32 vcc, v80, v156
	v_cmp_lt_i32_e64 s[46:47], v80, v158
	v_max3_f32 v15, v15, v10, v11
	s_nop 0
	v_cndmask_b32_e32 v12, v242, v12, vcc
	v_cndmask_b32_e64 v13, v242, v13, s[46:47]
	v_max3_f32 v15, v15, v12, v13
	s_and_saveexec_b64 s[2:3], s[38:39]
	ds_write_b32 v81, v10
	ds_write_b32 v81, v11 offset:32
	ds_write_b32 v81, v12 offset:64
	ds_write_b32 v81, v13 offset:96
	s_or_b64 exec, exec, s[2:3]
	s_waitcnt vmcnt(10)
	ds_write_b128 v198, v[56:59]
	ds_write_b128 v198, v[60:63] offset:1152
	ds_read_b128 v[56:59], v199
	ds_read_b128 v[60:63], v199 offset:64
	s_waitcnt lgkmcnt(8)
	v_mfma_f32_16x16x32_f16 v[10:13], v[48:51], v[6:9], 0
	v_mfma_f32_16x16x32_f16 v[10:13], v[52:55], v[2:5], v[10:13]
	v_or_b32_e32 v80, 48, v160
	v_mul_f32_e32 v194, 0x3e000000, v194
	v_mul_f32_e32 v195, 0x3e000000, v195
	v_mul_f32_e32 v196, 0x3e000000, v196
	v_mul_f32_e32 v197, 0x3e000000, v197
	v_cmp_lt_i32_e32 vcc, v80, v85
	v_cmp_lt_i32_e64 s[46:47], v80, v171
	v_lshl_add_u32 v81, v80, 5, v167
	s_nop 0
	v_cndmask_b32_e32 v194, v242, v194, vcc
	v_cndmask_b32_e64 v195, v242, v195, s[46:47]
	v_cmp_lt_i32_e32 vcc, v80, v156
	v_cmp_lt_i32_e64 s[46:47], v80, v158
	v_max3_f32 v15, v15, v194, v195
	s_nop 0
	v_cndmask_b32_e32 v196, v242, v196, vcc
	v_cndmask_b32_e64 v197, v242, v197, s[46:47]
	v_max3_f32 v15, v15, v196, v197
	s_and_saveexec_b64 s[2:3], s[38:39]
	ds_write_b32 v81, v194
	ds_write_b32 v81, v195 offset:32
	ds_write_b32 v81, v196 offset:64
	ds_write_b32 v81, v197 offset:96
	s_or_b64 exec, exec, s[2:3]
	s_waitcnt vmcnt(9)
	ds_write_b128 v198, v[64:67]
	ds_write_b128 v198, v[68:71] offset:1152
	ds_read_b128 v[64:67], v199
	ds_read_b128 v[68:71], v199 offset:64
	s_waitcnt lgkmcnt(8)
	v_mfma_f32_16x16x32_f16 v[194:197], v[56:59], v[6:9], 0
	v_mfma_f32_16x16x32_f16 v[194:197], v[60:63], v[2:5], v[194:197]
	v_or_b32_e32 v80, 64, v160
	v_mul_f32_e32 v10, 0x3e000000, v10
	v_mul_f32_e32 v11, 0x3e000000, v11
	v_mul_f32_e32 v12, 0x3e000000, v12
	v_mul_f32_e32 v13, 0x3e000000, v13
	v_cmp_lt_i32_e32 vcc, v80, v85
	v_cmp_lt_i32_e64 s[46:47], v80, v171
	v_lshl_add_u32 v81, v80, 5, v167
	s_nop 0
	v_cndmask_b32_e32 v10, v242, v10, vcc
	v_cndmask_b32_e64 v11, v242, v11, s[46:47]
	v_cmp_lt_i32_e32 vcc, v80, v156
	v_cmp_lt_i32_e64 s[46:47], v80, v158
	v_max3_f32 v15, v15, v10, v11
	s_nop 0
	v_cndmask_b32_e32 v12, v242, v12, vcc
	v_cndmask_b32_e64 v13, v242, v13, s[46:47]
	v_max3_f32 v15, v15, v12, v13
	s_and_saveexec_b64 s[2:3], s[38:39]
	ds_write_b32 v81, v10
	ds_write_b32 v81, v11 offset:32
	ds_write_b32 v81, v12 offset:64
	ds_write_b32 v81, v13 offset:96
	s_or_b64 exec, exec, s[2:3]
	s_waitcnt vmcnt(8)
;   __device__ __forceinline__ half_t* mm() const { return (half_t*)(ws() + OFF_mm); }
; __device__ __forceinline__ void dsa_item(const KP& p, int b, int tile, char* smem) {
;     ...
;     for (int mg = 0; mg < 2; ++mg) {
; #pragma unroll
;       for (int mm = 0; mm < 8; ++mm) {
;         const int m = mg * 8 + mm;
;         const int pos = m * 16 + col;
;         const int s = (pos < nsel) ? (int)sel[tk * 256 + pos] : 0;
;         const half_t* kp = ub + (size_t)s * NU + C_BK + hq * 8;
;         const h8 a0 = *(const h8*)kp, a1 = *(const h8*)(kp + 32);
;         f32x4 d = {0.f, 0.f, 0.f, 0.f};
;         d = __builtin_amdgcn_mfma_f32_16x16x32_f16(a0, q0, d, 0, 0, 0);
;         d = __builtin_amdgcn_mfma_f32_16x16x32_f16(a1, q1, d, 0, 0, 0);
; #pragma unroll
;         for (int r = 0; r < 4; ++r) {
;           const int pp = m * 16 + hq * 4 + r;
;           const float v = (pp < nsel) ? d[r] * 0.125f : NEGF;
;           mx = fmaxf(mx, v);
;           if (col < 8) pbuf[pp * 8 + col] = v;
;         }
;       }
	ds_write_b128 v198, v[72:75]
	ds_write_b128 v198, v[76:79] offset:1152
	ds_read_b128 v[72:75], v199
	ds_read_b128 v[76:79], v199 offset:64
	s_waitcnt lgkmcnt(8)
	v_mfma_f32_16x16x32_f16 v[10:13], v[64:67], v[6:9], 0
	v_mfma_f32_16x16x32_f16 v[10:13], v[68:71], v[2:5], v[10:13]
	v_or_b32_e32 v80, 0x50, v160
	v_mul_f32_e32 v194, 0x3e000000, v194
	v_mul_f32_e32 v195, 0x3e000000, v195
	v_mul_f32_e32 v196, 0x3e000000, v196
	v_mul_f32_e32 v197, 0x3e000000, v197
	v_cmp_lt_i32_e32 vcc, v80, v85
	v_cmp_lt_i32_e64 s[46:47], v80, v171
	v_lshl_add_u32 v81, v80, 5, v167
	s_nop 0
	v_cndmask_b32_e32 v194, v242, v194, vcc
	v_cndmask_b32_e64 v195, v242, v195, s[46:47]
	v_cmp_lt_i32_e32 vcc, v80, v156
	v_cmp_lt_i32_e64 s[46:47], v80, v158
	v_max3_f32 v15, v15, v194, v195
	s_nop 0
	v_cndmask_b32_e32 v196, v242, v196, vcc
	v_cndmask_b32_e64 v197, v242, v197, s[46:47]
	v_max3_f32 v15, v15, v196, v197
	s_and_saveexec_b64 s[2:3], s[38:39]
	ds_write_b32 v81, v194
	ds_write_b32 v81, v195 offset:32
	ds_write_b32 v81, v196 offset:64
	ds_write_b32 v81, v197 offset:96
	s_or_b64 exec, exec, s[2:3]
	s_waitcnt vmcnt(7)
	ds_write_b128 v198, v[90:93]
	ds_write_b128 v198, v[94:97] offset:1152
	ds_read_b128 v[90:93], v199
	ds_read_b128 v[94:97], v199 offset:64
	s_waitcnt lgkmcnt(8)
	v_mfma_f32_16x16x32_f16 v[194:197], v[72:75], v[6:9], 0
	v_mfma_f32_16x16x32_f16 v[194:197], v[76:79], v[2:5], v[194:197]
	v_or_b32_e32 v80, 0x60, v160
	v_mul_f32_e32 v10, 0x3e000000, v10
	v_mul_f32_e32 v11, 0x3e000000, v11
	v_mul_f32_e32 v12, 0x3e000000, v12
	v_mul_f32_e32 v13, 0x3e000000, v13
	v_cmp_lt_i32_e32 vcc, v80, v85
	v_cmp_lt_i32_e64 s[46:47], v80, v171
	v_lshl_add_u32 v81, v80, 5, v167
	s_nop 0
	v_cndmask_b32_e32 v10, v242, v10, vcc
	v_cndmask_b32_e64 v11, v242, v11, s[46:47]
	v_cmp_lt_i32_e32 vcc, v80, v156
	v_cmp_lt_i32_e64 s[46:47], v80, v158
	v_max3_f32 v15, v15, v10, v11
	s_nop 0
	v_cndmask_b32_e32 v12, v242, v12, vcc
	v_cndmask_b32_e64 v13, v242, v13, s[46:47]
	v_max3_f32 v15, v15, v12, v13
	s_and_saveexec_b64 s[2:3], s[38:39]
	ds_write_b32 v81, v10
	ds_write_b32 v81, v11 offset:32
	ds_write_b32 v81, v12 offset:64
	ds_write_b32 v81, v13 offset:96
	s_or_b64 exec, exec, s[2:3]
	s_waitcnt vmcnt(6)
	ds_write_b128 v198, v[98:101]
	ds_write_b128 v198, v[102:105] offset:1152
	ds_read_b128 v[98:101], v199
	ds_read_b128 v[102:105], v199 offset:64
	s_waitcnt lgkmcnt(8)
	v_mfma_f32_16x16x32_f16 v[10:13], v[90:93], v[6:9], 0
	v_mfma_f32_16x16x32_f16 v[10:13], v[94:97], v[2:5], v[10:13]
	v_or_b32_e32 v80, 0x70, v160
	v_mul_f32_e32 v194, 0x3e000000, v194
	v_mul_f32_e32 v195, 0x3e000000, v195
	v_mul_f32_e32 v196, 0x3e000000, v196
	v_mul_f32_e32 v197, 0x3e000000, v197
	v_cmp_lt_i32_e32 vcc, v80, v85
	v_cmp_lt_i32_e64 s[46:47], v80, v171
	v_lshl_add_u32 v81, v80, 5, v167
	s_nop 0
	v_cndmask_b32_e32 v194, v242, v194, vcc
	v_cndmask_b32_e64 v195, v242, v195, s[46:47]
	v_cmp_lt_i32_e32 vcc, v80, v156
	v_cmp_lt_i32_e64 s[46:47], v80, v158
	v_max3_f32 v15, v15, v194, v195
	s_nop 0
	v_cndmask_b32_e32 v196, v242, v196, vcc
	v_cndmask_b32_e64 v197, v242, v197, s[46:47]
	v_max3_f32 v15, v15, v196, v197
	s_and_saveexec_b64 s[2:3], s[38:39]
	ds_write_b32 v81, v194
	ds_write_b32 v81, v195 offset:32
	ds_write_b32 v81, v196 offset:64
	ds_write_b32 v81, v197 offset:96
	s_or_b64 exec, exec, s[2:3]
	s_waitcnt vmcnt(5)
	ds_write_b128 v198, v[106:109]
	ds_write_b128 v198, v[110:113] offset:1152
	ds_read_b128 v[106:109], v199
	ds_read_b128 v[110:113], v199 offset:64
	s_waitcnt lgkmcnt(8)
	v_mfma_f32_16x16x32_f16 v[194:197], v[98:101], v[6:9], 0
	v_mfma_f32_16x16x32_f16 v[194:197], v[102:105], v[2:5], v[194:197]
	v_or_b32_e32 v80, 0x80, v160
	v_mul_f32_e32 v10, 0x3e000000, v10
	v_mul_f32_e32 v11, 0x3e000000, v11
	v_mul_f32_e32 v12, 0x3e000000, v12
	v_mul_f32_e32 v13, 0x3e000000, v13
	v_cmp_lt_i32_e32 vcc, v80, v85
	v_cmp_lt_i32_e64 s[46:47], v80, v171
	v_lshl_add_u32 v81, v80, 5, v167
	s_nop 0
	v_cndmask_b32_e32 v10, v242, v10, vcc
	v_cndmask_b32_e64 v11, v242, v11, s[46:47]
	v_cmp_lt_i32_e32 vcc, v80, v156
	v_cmp_lt_i32_e64 s[46:47], v80, v158
	v_max3_f32 v15, v15, v10, v11
	s_nop 0
	v_cndmask_b32_e32 v12, v242, v12, vcc
	v_cndmask_b32_e64 v13, v242, v13, s[46:47]
	v_max3_f32 v15, v15, v12, v13
	s_and_saveexec_b64 s[2:3], s[38:39]
	ds_write_b32 v81, v10
	ds_write_b32 v81, v11 offset:32
	ds_write_b32 v81, v12 offset:64
	ds_write_b32 v81, v13 offset:96
	s_or_b64 exec, exec, s[2:3]
	s_waitcnt vmcnt(4)
	ds_write_b128 v198, v[114:117]
	ds_write_b128 v198, v[118:121] offset:1152
	ds_read_b128 v[114:117], v199
	ds_read_b128 v[118:121], v199 offset:64
	s_waitcnt lgkmcnt(8)
	v_mfma_f32_16x16x32_f16 v[10:13], v[106:109], v[6:9], 0
	v_mfma_f32_16x16x32_f16 v[10:13], v[110:113], v[2:5], v[10:13]
	v_or_b32_e32 v80, 0x90, v160
	v_mul_f32_e32 v194, 0x3e000000, v194
	v_mul_f32_e32 v195, 0x3e000000, v195
	v_mul_f32_e32 v196, 0x3e000000, v196
	v_mul_f32_e32 v197, 0x3e000000, v197
	v_cmp_lt_i32_e32 vcc, v80, v85
	v_cmp_lt_i32_e64 s[46:47], v80, v171
	v_lshl_add_u32 v81, v80, 5, v167
	s_nop 0
	v_cndmask_b32_e32 v194, v242, v194, vcc
	v_cndmask_b32_e64 v195, v242, v195, s[46:47]
	v_cmp_lt_i32_e32 vcc, v80, v156
	v_cmp_lt_i32_e64 s[46:47], v80, v158
	v_max3_f32 v15, v15, v194, v195
	s_nop 0
	v_cndmask_b32_e32 v196, v242, v196, vcc
	v_cndmask_b32_e64 v197, v242, v197, s[46:47]
	v_max3_f32 v15, v15, v196, v197
	s_and_saveexec_b64 s[2:3], s[38:39]
	ds_write_b32 v81, v194
	ds_write_b32 v81, v195 offset:32
	ds_write_b32 v81, v196 offset:64
	ds_write_b32 v81, v197 offset:96
	s_or_b64 exec, exec, s[2:3]
	s_waitcnt vmcnt(3)
	ds_write_b128 v198, v[122:125]
	ds_write_b128 v198, v[128:131] offset:1152
	ds_read_b128 v[122:125], v199
	ds_read_b128 v[128:131], v199 offset:64
	s_waitcnt lgkmcnt(8)
;   __device__ __forceinline__ half_t* mm() const { return (half_t*)(ws() + OFF_mm); }
; __device__ __forceinline__ void dsa_item(const KP& p, int b, int tile, char* smem) {
;     ...
;     for (int mg = 0; mg < 2; ++mg) {
; #pragma unroll
;       for (int mm = 0; mm < 8; ++mm) {
;         const int m = mg * 8 + mm;
;         const int pos = m * 16 + col;
;         const int s = (pos < nsel) ? (int)sel[tk * 256 + pos] : 0;
;         const half_t* kp = ub + (size_t)s * NU + C_BK + hq * 8;
;         const h8 a0 = *(const h8*)kp, a1 = *(const h8*)(kp + 32);
;         f32x4 d = {0.f, 0.f, 0.f, 0.f};
;         d = __builtin_amdgcn_mfma_f32_16x16x32_f16(a0, q0, d, 0, 0, 0);
;         d = __builtin_amdgcn_mfma_f32_16x16x32_f16(a1, q1, d, 0, 0, 0);
; #pragma unroll
;         for (int r = 0; r < 4; ++r) {
;           const int pp = m * 16 + hq * 4 + r;
;           const float v = (pp < nsel) ? d[r] * 0.125f : NEGF;
;           mx = fmaxf(mx, v);
;           if (col < 8) pbuf[pp * 8 + col] = v;
;         }
;       }
	v_mfma_f32_16x16x32_f16 v[194:197], v[114:117], v[6:9], 0
	v_mfma_f32_16x16x32_f16 v[194:197], v[118:121], v[2:5], v[194:197]
	v_or_b32_e32 v80, 0xa0, v160
	v_mul_f32_e32 v10, 0x3e000000, v10
	v_mul_f32_e32 v11, 0x3e000000, v11
	v_mul_f32_e32 v12, 0x3e000000, v12
	v_mul_f32_e32 v13, 0x3e000000, v13
	v_cmp_lt_i32_e32 vcc, v80, v85
	v_cmp_lt_i32_e64 s[46:47], v80, v171
	v_lshl_add_u32 v81, v80, 5, v167
	s_nop 0
	v_cndmask_b32_e32 v10, v242, v10, vcc
	v_cndmask_b32_e64 v11, v242, v11, s[46:47]
	v_cmp_lt_i32_e32 vcc, v80, v156
	v_cmp_lt_i32_e64 s[46:47], v80, v158
	v_max3_f32 v15, v15, v10, v11
	s_nop 0
	v_cndmask_b32_e32 v12, v242, v12, vcc
	v_cndmask_b32_e64 v13, v242, v13, s[46:47]
	v_max3_f32 v15, v15, v12, v13
	s_and_saveexec_b64 s[2:3], s[38:39]
	ds_write_b32 v81, v10
	ds_write_b32 v81, v11 offset:32
	ds_write_b32 v81, v12 offset:64
	ds_write_b32 v81, v13 offset:96
	s_or_b64 exec, exec, s[2:3]
	s_waitcnt vmcnt(2)
	ds_write_b128 v198, v[132:135]
	ds_write_b128 v198, v[136:139] offset:1152
	ds_read_b128 v[132:135], v199
	ds_read_b128 v[136:139], v199 offset:64
	s_waitcnt lgkmcnt(8)
	v_mfma_f32_16x16x32_f16 v[10:13], v[122:125], v[6:9], 0
	v_mfma_f32_16x16x32_f16 v[10:13], v[128:131], v[2:5], v[10:13]
	v_or_b32_e32 v80, 0xb0, v160
	v_mul_f32_e32 v194, 0x3e000000, v194
	v_mul_f32_e32 v195, 0x3e000000, v195
	v_mul_f32_e32 v196, 0x3e000000, v196
	v_mul_f32_e32 v197, 0x3e000000, v197
	v_cmp_lt_i32_e32 vcc, v80, v85
	v_cmp_lt_i32_e64 s[46:47], v80, v171
	v_lshl_add_u32 v81, v80, 5, v167
	s_nop 0
	v_cndmask_b32_e32 v194, v242, v194, vcc
	v_cndmask_b32_e64 v195, v242, v195, s[46:47]
	v_cmp_lt_i32_e32 vcc, v80, v156
	v_cmp_lt_i32_e64 s[46:47], v80, v158
	v_max3_f32 v15, v15, v194, v195
	s_nop 0
	v_cndmask_b32_e32 v196, v242, v196, vcc
	v_cndmask_b32_e64 v197, v242, v197, s[46:47]
	v_max3_f32 v15, v15, v196, v197
	s_and_saveexec_b64 s[2:3], s[38:39]
	ds_write_b32 v81, v194
	ds_write_b32 v81, v195 offset:32
	ds_write_b32 v81, v196 offset:64
	ds_write_b32 v81, v197 offset:96
	s_or_b64 exec, exec, s[2:3]
	s_waitcnt vmcnt(1)
	ds_write_b128 v198, v[140:143]
	ds_write_b128 v198, v[144:147] offset:1152
	ds_read_b128 v[140:143], v199
	ds_read_b128 v[144:147], v199 offset:64
	s_waitcnt lgkmcnt(8)
	v_mfma_f32_16x16x32_f16 v[194:197], v[132:135], v[6:9], 0
	v_mfma_f32_16x16x32_f16 v[194:197], v[136:139], v[2:5], v[194:197]
	v_or_b32_e32 v80, 0xc0, v160
	v_mul_f32_e32 v10, 0x3e000000, v10
	v_mul_f32_e32 v11, 0x3e000000, v11
	v_mul_f32_e32 v12, 0x3e000000, v12
	v_mul_f32_e32 v13, 0x3e000000, v13
	v_cmp_lt_i32_e32 vcc, v80, v85
	v_cmp_lt_i32_e64 s[46:47], v80, v171
	v_lshl_add_u32 v81, v80, 5, v167
	s_nop 0
	v_cndmask_b32_e32 v10, v242, v10, vcc
	v_cndmask_b32_e64 v11, v242, v11, s[46:47]
	v_cmp_lt_i32_e32 vcc, v80, v156
	v_cmp_lt_i32_e64 s[46:47], v80, v158
	v_max3_f32 v15, v15, v10, v11
	s_nop 0
	v_cndmask_b32_e32 v12, v242, v12, vcc
	v_cndmask_b32_e64 v13, v242, v13, s[46:47]
	v_max3_f32 v15, v15, v12, v13
	s_and_saveexec_b64 s[2:3], s[38:39]
	ds_write_b32 v81, v10
	ds_write_b32 v81, v11 offset:32
	ds_write_b32 v81, v12 offset:64
	ds_write_b32 v81, v13 offset:96
	s_or_b64 exec, exec, s[2:3]
	s_waitcnt vmcnt(0)
	ds_write_b128 v198, v[148:151]
	ds_write_b128 v198, v[152:155] offset:1152
	ds_read_b128 v[148:151], v199
	ds_read_b128 v[152:155], v199 offset:64
	s_waitcnt lgkmcnt(8)
	v_mfma_f32_16x16x32_f16 v[10:13], v[140:143], v[6:9], 0
	v_mfma_f32_16x16x32_f16 v[10:13], v[144:147], v[2:5], v[10:13]
	v_or_b32_e32 v80, 0xd0, v160
	v_mul_f32_e32 v194, 0x3e000000, v194
	v_mul_f32_e32 v195, 0x3e000000, v195
	v_mul_f32_e32 v196, 0x3e000000, v196
	v_mul_f32_e32 v197, 0x3e000000, v197
	v_cmp_lt_i32_e32 vcc, v80, v85
	v_cmp_lt_i32_e64 s[46:47], v80, v171
	v_lshl_add_u32 v81, v80, 5, v167
	s_nop 0
	v_cndmask_b32_e32 v194, v242, v194, vcc
	v_cndmask_b32_e64 v195, v242, v195, s[46:47]
	v_cmp_lt_i32_e32 vcc, v80, v156
	v_cmp_lt_i32_e64 s[46:47], v80, v158
	v_max3_f32 v15, v15, v194, v195
	s_nop 0
	v_cndmask_b32_e32 v196, v242, v196, vcc
	v_cndmask_b32_e64 v197, v242, v197, s[46:47]
	v_max3_f32 v15, v15, v196, v197
	s_and_saveexec_b64 s[2:3], s[38:39]
	ds_write_b32 v81, v194
	ds_write_b32 v81, v195 offset:32
	ds_write_b32 v81, v196 offset:64
	ds_write_b32 v81, v197 offset:96
	s_or_b64 exec, exec, s[2:3]
	s_waitcnt lgkmcnt(4)
	v_mfma_f32_16x16x32_f16 v[194:197], v[148:151], v[6:9], 0
	v_mfma_f32_16x16x32_f16 v[194:197], v[152:155], v[2:5], v[194:197]
	v_or_b32_e32 v80, 0xe0, v160
	v_mul_f32_e32 v10, 0x3e000000, v10
	v_mul_f32_e32 v11, 0x3e000000, v11
	v_mul_f32_e32 v12, 0x3e000000, v12
	v_mul_f32_e32 v13, 0x3e000000, v13
	v_cmp_lt_i32_e32 vcc, v80, v85
	v_cmp_lt_i32_e64 s[46:47], v80, v171
	v_lshl_add_u32 v81, v80, 5, v167
	s_nop 0
	v_cndmask_b32_e32 v10, v242, v10, vcc
	v_cndmask_b32_e64 v11, v242, v11, s[46:47]
	v_cmp_lt_i32_e32 vcc, v80, v156
	v_cmp_lt_i32_e64 s[46:47], v80, v158
	v_max3_f32 v15, v15, v10, v11
	s_nop 0
	v_cndmask_b32_e32 v12, v242, v12, vcc
	v_cndmask_b32_e64 v13, v242, v13, s[46:47]
	v_max3_f32 v15, v15, v12, v13
	s_and_saveexec_b64 s[2:3], s[38:39]
	ds_write_b32 v81, v10
	ds_write_b32 v81, v11 offset:32
	ds_write_b32 v81, v12 offset:64
	ds_write_b32 v81, v13 offset:96
	s_or_b64 exec, exec, s[2:3]
	s_nop 7
	v_or_b32_e32 v80, 0xf0, v160
	v_mul_f32_e32 v194, 0x3e000000, v194
	v_mul_f32_e32 v195, 0x3e000000, v195
	v_mul_f32_e32 v196, 0x3e000000, v196
	v_mul_f32_e32 v197, 0x3e000000, v197
	v_cmp_lt_i32_e32 vcc, v80, v85
	v_cmp_lt_i32_e64 s[46:47], v80, v171
	v_lshl_add_u32 v81, v80, 5, v167
	s_nop 0
	v_cndmask_b32_e32 v194, v242, v194, vcc
	v_cndmask_b32_e64 v195, v242, v195, s[46:47]
	v_cmp_lt_i32_e32 vcc, v80, v156
	v_cmp_lt_i32_e64 s[46:47], v80, v158
	v_max3_f32 v15, v15, v194, v195
	s_nop 0
	v_cndmask_b32_e32 v196, v242, v196, vcc
	v_cndmask_b32_e64 v197, v242, v197, s[46:47]
	v_max3_f32 v15, v15, v196, v197
	s_and_saveexec_b64 s[2:3], s[38:39]
	ds_write_b32 v81, v194
	ds_write_b32 v81, v195 offset:32
	ds_write_b32 v81, v196 offset:64
	ds_write_b32 v81, v197 offset:96
	s_or_b64 exec, exec, s[2:3]
	s_branch .LBB0_1509

; __device__ __forceinline__ void dsa_item(const KP& p, int b, int tile, char* smem) {
;     ...
; #pragma unroll 1
;       for (int g8 = 0; g8 < 4; ++g8) {
;         h8 vv[8];
; #pragma unroll
;         for (int i = 0; i < 8; ++i) {
;           const int pos = (g8 * 8 + i) * 8 + rs;
;           const int s = (pos < nsel) ? (int)sel[tk * 256 + pos] : 0;
;           vv[i] = *(const h8*)(ub + (size_t)s * NU + C_BV + dc * 8);
;         }
; #pragma unroll
;         for (int i = 0; i < 8; ++i) {
;           const int pos = (g8 * 8 + i) * 8 + rs;
;           const f32x4 pa = *(const f32x4*)&pbuf[pos * 8];
;           const f32x4 pb = *(const f32x4*)&pbuf[pos * 8 + 4];
;           float vf[8];
; #pragma unroll
;           for (int e = 0; e < 8; ++e) vf[e] = (float)vv[i][e];
; #pragma unroll
;           for (int e = 0; e < 8; ++e) {
;             acc[0][e] += pa[0] * vf[e]; acc[1][e] += pa[1] * vf[e]; acc[2][e] += pa[2] * vf[e]; acc[3][e] += pa[3] * vf[e];
.LBB0_1513:
	s_add_u32 s2, s78, 0x3880
	s_addc_u32 s3, s79, 0
	v_lshlrev_b32_e32 v35, 8, v159
	v_lshl_add_u32 v35, v165, 2, v35
	v_add_u32_e32 v35, 0xcc00, v35
	ds_read_b32 v2, v35
	ds_read_b32 v6, v35 offset:32
	ds_read_b32 v10, v35 offset:64
	ds_read_b32 v14, v35 offset:96
	ds_read_b32 v22, v35 offset:128
	ds_read_b32 v26, v35 offset:160
	ds_read_b32 v18, v35 offset:192
	ds_read_b32 v30, v35 offset:224
	s_waitcnt lgkmcnt(4)
	v_add_u32_e32 v2, v2, v0
	global_load_dwordx4 v[2:5], v2, s[2:3]
	v_add_u32_e32 v6, v6, v0
	global_load_dwordx4 v[6:9], v6, s[2:3]
	v_add_u32_e32 v10, v10, v0
	global_load_dwordx4 v[10:13], v10, s[2:3]
	v_add_u32_e32 v14, v14, v0
	global_load_dwordx4 v[14:17], v14, s[2:3]
	s_waitcnt lgkmcnt(0)
	v_add_u32_e32 v22, v22, v0
	global_load_dwordx4 v[22:25], v22, s[2:3]
	v_add_u32_e32 v26, v26, v0
	global_load_dwordx4 v[26:29], v26, s[2:3]
	v_add_u32_e32 v18, v18, v0
	global_load_dwordx4 v[18:21], v18, s[2:3]
	v_add_u32_e32 v30, v30, v0
	global_load_dwordx4 v[30:33], v30, s[2:3]
	v_lshlrev_b32_e32 v35, 8, v159
	v_lshl_add_u32 v35, v165, 2, v35
	v_add_u32_e32 v35, 0xcc00, v35
	ds_read_b32 v204, v35 offset:256
	ds_read_b32 v208, v35 offset:288
	ds_read_b32 v212, v35 offset:320
	ds_read_b32 v216, v35 offset:352
	ds_read_b32 v224, v35 offset:384
	ds_read_b32 v228, v35 offset:416
	ds_read_b32 v220, v35 offset:448
	ds_read_b32 v232, v35 offset:480
	s_waitcnt lgkmcnt(4)
	v_add_u32_e32 v204, v204, v0
	global_load_dwordx4 v[204:207], v204, s[2:3]
	v_add_u32_e32 v208, v208, v0
	global_load_dwordx4 v[208:211], v208, s[2:3]
	v_add_u32_e32 v212, v212, v0
	global_load_dwordx4 v[212:215], v212, s[2:3]
	v_add_u32_e32 v216, v216, v0
	global_load_dwordx4 v[216:219], v216, s[2:3]
	s_waitcnt lgkmcnt(0)
	v_add_u32_e32 v224, v224, v0
	global_load_dwordx4 v[224:227], v224, s[2:3]
	v_add_u32_e32 v228, v228, v0
	global_load_dwordx4 v[228:231], v228, s[2:3]
	v_add_u32_e32 v220, v220, v0
	global_load_dwordx4 v[220:223], v220, s[2:3]
	v_add_u32_e32 v232, v232, v0
	global_load_dwordx4 v[232:235], v232, s[2:3]
	s_waitcnt vmcnt(15)
	v_cvt_f32_f16_sdwa v175, v2 dst_sel:DWORD dst_unused:UNUSED_PAD src0_sel:WORD_1
	v_cvt_f32_f16_e32 v174, v2
	s_waitcnt vmcnt(14)
	v_cvt_f32_f16_sdwa v177, v6 dst_sel:DWORD dst_unused:UNUSED_PAD src0_sel:WORD_1
	v_cvt_f32_f16_e32 v176, v6
	ds_read_b128 v[58:61], v172
	ds_read_b128 v[34:37], v172 offset:16
	ds_read_b128 v[62:65], v172 offset:256
	ds_read_b128 v[38:41], v172 offset:272
	ds_read_b128 v[66:69], v172 offset:512
	ds_read_b128 v[42:45], v172 offset:528
	ds_read_b128 v[70:73], v172 offset:768
	ds_read_b128 v[46:49], v172 offset:784
	ds_read_b128 v[74:77], v172 offset:1024
	ds_read_b128 v[50:53], v172 offset:1040
	s_waitcnt vmcnt(13)
	v_cvt_f32_f16_sdwa v179, v10 dst_sel:DWORD dst_unused:UNUSED_PAD src0_sel:WORD_1
	v_cvt_f32_f16_e32 v178, v10
	s_waitcnt lgkmcnt(8)
	v_mov_b32_e32 v156, v37
	s_waitcnt vmcnt(12)
	v_cvt_f32_f16_sdwa v181, v14 dst_sel:DWORD dst_unused:UNUSED_PAD src0_sel:WORD_1
	v_cvt_f32_f16_e32 v180, v14
	v_pk_fma_f32 v[148:149], v[156:157], v[174:175], v[148:149] op_sel_hi:[0,1,1]
	s_waitcnt lgkmcnt(6)
	v_mov_b32_e32 v6, v41
	s_waitcnt vmcnt(11)
	v_cvt_f32_f16_sdwa v189, v22 dst_sel:DWORD dst_unused:UNUSED_PAD src0_sel:WORD_1
	v_cvt_f32_f16_e32 v188, v22
	v_pk_fma_f32 v[148:149], v[6:7], v[176:177], v[148:149] op_sel_hi:[0,1,1]
	s_waitcnt lgkmcnt(4)
	v_mov_b32_e32 v10, v45
	v_pk_fma_f32 v[148:149], v[10:11], v[178:179], v[148:149] op_sel_hi:[0,1,1]
	s_waitcnt lgkmcnt(2)
	v_mov_b32_e32 v22, v49
	v_pk_fma_f32 v[148:149], v[22:23], v[180:181], v[148:149] op_sel_hi:[0,1,1]
	s_waitcnt lgkmcnt(0)
	v_mov_b32_e32 v158, v53
	ds_read_b128 v[78:81], v172 offset:1280
	ds_read_b128 v[54:57], v172 offset:1296
	v_pk_fma_f32 v[190:191], v[158:159], v[188:189], v[148:149] op_sel_hi:[0,1,1]
	v_pk_fma_f32 v[148:149], v[58:59], v[174:175], v[154:155] op_sel_hi:[0,1,1]
	v_mov_b32_e32 v154, v61
	v_pk_fma_f32 v[152:153], v[58:59], v[174:175], v[152:153] op_sel:[1,0,0]
	v_pk_fma_f32 v[146:147], v[60:61], v[174:175], v[146:147] op_sel_hi:[0,1,1]
	v_pk_fma_f32 v[140:141], v[154:155], v[174:175], v[140:141] op_sel_hi:[0,1,1]
	v_mov_b32_e32 v194, v65
	v_pk_fma_f32 v[150:151], v[34:35], v[174:175], v[150:151] op_sel_hi:[0,1,1]
	v_pk_fma_f32 v[144:145], v[34:35], v[174:175], v[144:145] op_sel:[1,0,0]
	v_pk_fma_f32 v[138:139], v[36:37], v[174:175], v[138:139] op_sel_hi:[0,1,1]
	s_waitcnt vmcnt(10)
; __device__ __forceinline__ void dsa_item(const KP& p, int b, int tile, char* smem) {
;     ...
; #pragma unroll
;         for (int i = 0; i < 8; ++i) {
;           const int pos = (g8 * 8 + i) * 8 + rs;
;           const f32x4 pa = *(const f32x4*)&pbuf[pos * 8];
;           const f32x4 pb = *(const f32x4*)&pbuf[pos * 8 + 4];
;           float vf[8];
; #pragma unroll
;           for (int e = 0; e < 8; ++e) vf[e] = (float)vv[i][e];
; #pragma unroll
;           for (int e = 0; e < 8; ++e) {
;             acc[0][e] += pa[0] * vf[e]; acc[1][e] += pa[1] * vf[e]; acc[2][e] += pa[2] * vf[e]; acc[3][e] += pa[3] * vf[e];
;             acc[4][e] += pb[0] * vf[e]; acc[5][e] += pb[1] * vf[e]; acc[6][e] += pb[2] * vf[e]; acc[7][e] += pb[3] * vf[e];
;           }
	v_cvt_f32_f16_sdwa v193, v26 dst_sel:DWORD dst_unused:UNUSED_PAD src0_sel:WORD_1
	v_cvt_f32_f16_e32 v192, v26
	v_pk_fma_f32 v[148:149], v[62:63], v[176:177], v[148:149] op_sel_hi:[0,1,1]
	v_pk_fma_f32 v[152:153], v[62:63], v[176:177], v[152:153] op_sel:[1,0,0]
	v_pk_fma_f32 v[146:147], v[64:65], v[176:177], v[146:147] op_sel_hi:[0,1,1]
	v_pk_fma_f32 v[140:141], v[194:195], v[176:177], v[140:141] op_sel_hi:[0,1,1]
	v_mov_b32_e32 v196, v69
	v_pk_fma_f32 v[150:151], v[38:39], v[176:177], v[150:151] op_sel_hi:[0,1,1]
	v_pk_fma_f32 v[144:145], v[38:39], v[176:177], v[144:145] op_sel:[1,0,0]
	v_pk_fma_f32 v[138:139], v[40:41], v[176:177], v[138:139] op_sel_hi:[0,1,1]
	v_cvt_f32_f16_sdwa v175, v3 dst_sel:DWORD dst_unused:UNUSED_PAD src0_sel:WORD_1
	v_cvt_f32_f16_e32 v174, v3
	v_pk_fma_f32 v[148:149], v[66:67], v[178:179], v[148:149] op_sel_hi:[0,1,1]
	v_pk_fma_f32 v[152:153], v[66:67], v[178:179], v[152:153] op_sel:[1,0,0]
	v_pk_fma_f32 v[146:147], v[68:69], v[178:179], v[146:147] op_sel_hi:[0,1,1]
	v_pk_fma_f32 v[140:141], v[196:197], v[178:179], v[140:141] op_sel_hi:[0,1,1]
	v_mov_b32_e32 v198, v73
	v_pk_fma_f32 v[150:151], v[42:43], v[178:179], v[150:151] op_sel_hi:[0,1,1]
	v_pk_fma_f32 v[144:145], v[42:43], v[178:179], v[144:145] op_sel:[1,0,0]
	v_pk_fma_f32 v[138:139], v[44:45], v[178:179], v[138:139] op_sel_hi:[0,1,1]
	v_cvt_f32_f16_sdwa v179, v7 dst_sel:DWORD dst_unused:UNUSED_PAD src0_sel:WORD_1
	v_cvt_f32_f16_e32 v178, v7
	v_pk_fma_f32 v[148:149], v[70:71], v[180:181], v[148:149] op_sel_hi:[0,1,1]
	v_pk_fma_f32 v[152:153], v[70:71], v[180:181], v[152:153] op_sel:[1,0,0]
	v_pk_fma_f32 v[146:147], v[72:73], v[180:181], v[146:147] op_sel_hi:[0,1,1]
	v_pk_fma_f32 v[140:141], v[198:199], v[180:181], v[140:141] op_sel_hi:[0,1,1]
	v_mov_b32_e32 v200, v77
	v_pk_fma_f32 v[150:151], v[46:47], v[180:181], v[150:151] op_sel_hi:[0,1,1]
	v_pk_fma_f32 v[144:145], v[46:47], v[180:181], v[144:145] op_sel:[1,0,0]
	v_pk_fma_f32 v[138:139], v[48:49], v[180:181], v[138:139] op_sel_hi:[0,1,1]
	v_cvt_f32_f16_sdwa v181, v11 dst_sel:DWORD dst_unused:UNUSED_PAD src0_sel:WORD_1
	v_cvt_f32_f16_e32 v180, v11
	v_pk_fma_f32 v[148:149], v[74:75], v[188:189], v[148:149] op_sel_hi:[0,1,1]
	v_pk_fma_f32 v[152:153], v[74:75], v[188:189], v[152:153] op_sel:[1,0,0]
	v_pk_fma_f32 v[146:147], v[76:77], v[188:189], v[146:147] op_sel_hi:[0,1,1]
	v_pk_fma_f32 v[140:141], v[200:201], v[188:189], v[140:141] op_sel_hi:[0,1,1]
	v_pk_fma_f32 v[150:151], v[50:51], v[188:189], v[150:151] op_sel_hi:[0,1,1]
	v_pk_fma_f32 v[144:145], v[50:51], v[188:189], v[144:145] op_sel:[1,0,0]
	v_pk_fma_f32 v[138:139], v[52:53], v[188:189], v[138:139] op_sel_hi:[0,1,1]
	s_waitcnt lgkmcnt(0)
	v_mov_b32_e32 v176, v57
	v_cvt_f32_f16_sdwa v189, v15 dst_sel:DWORD dst_unused:UNUSED_PAD src0_sel:WORD_1
	v_cvt_f32_f16_e32 v188, v15
	v_pk_fma_f32 v[2:3], v[56:57], v[192:193], v[138:139] op_sel_hi:[0,1,1]
	v_pk_fma_f32 v[138:139], v[176:177], v[192:193], v[190:191] op_sel_hi:[0,1,1]
	v_pk_fma_f32 v[132:133], v[156:157], v[174:175], v[132:133] op_sel_hi:[0,1,1]
	v_cvt_f32_f16_sdwa v191, v23 dst_sel:DWORD dst_unused:UNUSED_PAD src0_sel:WORD_1
	v_cvt_f32_f16_e32 v190, v23
	v_pk_fma_f32 v[14:15], v[6:7], v[178:179], v[132:133] op_sel_hi:[0,1,1]
	v_mov_b32_e32 v202, v81
	v_pk_fma_f32 v[14:15], v[10:11], v[180:181], v[14:15] op_sel_hi:[0,1,1]
	v_pk_fma_f32 v[148:149], v[78:79], v[192:193], v[148:149] op_sel_hi:[0,1,1]
	v_pk_fma_f32 v[152:153], v[78:79], v[192:193], v[152:153] op_sel:[1,0,0]
	v_pk_fma_f32 v[146:147], v[80:81], v[192:193], v[146:147] op_sel_hi:[0,1,1]
	v_pk_fma_f32 v[140:141], v[202:203], v[192:193], v[140:141] op_sel_hi:[0,1,1]
	v_pk_fma_f32 v[150:151], v[54:55], v[192:193], v[150:151] op_sel_hi:[0,1,1]
	v_pk_fma_f32 v[144:145], v[54:55], v[192:193], v[144:145] op_sel:[1,0,0]
	v_pk_fma_f32 v[14:15], v[22:23], v[188:189], v[14:15] op_sel_hi:[0,1,1]
	v_cvt_f32_f16_sdwa v193, v27 dst_sel:DWORD dst_unused:UNUSED_PAD src0_sel:WORD_1
	v_cvt_f32_f16_e32 v192, v27
	v_pk_fma_f32 v[26:27], v[58:59], v[174:175], v[134:135] op_sel:[1,0,0]
	v_pk_fma_f32 v[134:135], v[34:35], v[174:175], v[136:137] op_sel_hi:[0,1,1]
	v_cvt_f32_f16_sdwa v137, v4 dst_sel:DWORD dst_unused:UNUSED_PAD src0_sel:WORD_1
	v_cvt_f32_f16_e32 v136, v4
	v_pk_fma_f32 v[132:133], v[158:159], v[190:191], v[14:15] op_sel_hi:[0,1,1]
	v_pk_fma_f32 v[14:15], v[58:59], v[174:175], v[142:143] op_sel_hi:[0,1,1]
	v_cvt_f32_f16_sdwa v143, v8 dst_sel:DWORD dst_unused:UNUSED_PAD src0_sel:WORD_1
	v_cvt_f32_f16_e32 v142, v8
	v_pk_fma_f32 v[128:129], v[60:61], v[174:175], v[128:129] op_sel_hi:[0,1,1]
	v_pk_fma_f32 v[120:121], v[154:155], v[174:175], v[120:121] op_sel_hi:[0,1,1]
	v_pk_fma_f32 v[130:131], v[34:35], v[174:175], v[130:131] op_sel:[1,0,0]
	v_pk_fma_f32 v[122:123], v[36:37], v[174:175], v[122:123] op_sel_hi:[0,1,1]
	v_cvt_f32_f16_sdwa v175, v12 dst_sel:DWORD dst_unused:UNUSED_PAD src0_sel:WORD_1
	v_cvt_f32_f16_e32 v174, v12
	v_pk_fma_f32 v[14:15], v[62:63], v[178:179], v[14:15] op_sel_hi:[0,1,1]
	v_pk_fma_f32 v[26:27], v[62:63], v[178:179], v[26:27] op_sel:[1,0,0]
	v_pk_fma_f32 v[128:129], v[64:65], v[178:179], v[128:129] op_sel_hi:[0,1,1]
	v_pk_fma_f32 v[120:121], v[194:195], v[178:179], v[120:121] op_sel_hi:[0,1,1]
	v_pk_fma_f32 v[134:135], v[38:39], v[178:179], v[134:135] op_sel_hi:[0,1,1]
	v_pk_fma_f32 v[130:131], v[38:39], v[178:179], v[130:131] op_sel:[1,0,0]
	v_pk_fma_f32 v[122:123], v[40:41], v[178:179], v[122:123] op_sel_hi:[0,1,1]
	v_cvt_f32_f16_sdwa v179, v16 dst_sel:DWORD dst_unused:UNUSED_PAD src0_sel:WORD_1
	v_cvt_f32_f16_e32 v178, v16
	v_pk_fma_f32 v[14:15], v[66:67], v[180:181], v[14:15] op_sel_hi:[0,1,1]
; __device__ __forceinline__ void dsa_item(const KP& p, int b, int tile, char* smem) {
;     ...
; #pragma unroll
;         for (int i = 0; i < 8; ++i) {
;           const int pos = (g8 * 8 + i) * 8 + rs;
;           const f32x4 pa = *(const f32x4*)&pbuf[pos * 8];
;           const f32x4 pb = *(const f32x4*)&pbuf[pos * 8 + 4];
;           float vf[8];
; #pragma unroll
;           for (int e = 0; e < 8; ++e) vf[e] = (float)vv[i][e];
; #pragma unroll
;           for (int e = 0; e < 8; ++e) {
;             acc[0][e] += pa[0] * vf[e]; acc[1][e] += pa[1] * vf[e]; acc[2][e] += pa[2] * vf[e]; acc[3][e] += pa[3] * vf[e];
;             acc[4][e] += pb[0] * vf[e]; acc[5][e] += pb[1] * vf[e]; acc[6][e] += pb[2] * vf[e]; acc[7][e] += pb[3] * vf[e];
;           }
	v_pk_fma_f32 v[26:27], v[66:67], v[180:181], v[26:27] op_sel:[1,0,0]
	v_pk_fma_f32 v[128:129], v[68:69], v[180:181], v[128:129] op_sel_hi:[0,1,1]
	v_pk_fma_f32 v[120:121], v[196:197], v[180:181], v[120:121] op_sel_hi:[0,1,1]
	v_pk_fma_f32 v[134:135], v[42:43], v[180:181], v[134:135] op_sel_hi:[0,1,1]
	v_pk_fma_f32 v[130:131], v[42:43], v[180:181], v[130:131] op_sel:[1,0,0]
	v_pk_fma_f32 v[122:123], v[44:45], v[180:181], v[122:123] op_sel_hi:[0,1,1]
	v_cvt_f32_f16_sdwa v181, v24 dst_sel:DWORD dst_unused:UNUSED_PAD src0_sel:WORD_1
	v_cvt_f32_f16_e32 v180, v24
	v_pk_fma_f32 v[106:107], v[36:37], v[136:137], v[106:107] op_sel_hi:[0,1,1]
	v_pk_fma_f32 v[14:15], v[70:71], v[188:189], v[14:15] op_sel_hi:[0,1,1]
	v_pk_fma_f32 v[26:27], v[70:71], v[188:189], v[26:27] op_sel:[1,0,0]
	v_pk_fma_f32 v[128:129], v[72:73], v[188:189], v[128:129] op_sel_hi:[0,1,1]
	v_pk_fma_f32 v[120:121], v[198:199], v[188:189], v[120:121] op_sel_hi:[0,1,1]
	v_pk_fma_f32 v[134:135], v[46:47], v[188:189], v[134:135] op_sel_hi:[0,1,1]
	v_pk_fma_f32 v[130:131], v[46:47], v[188:189], v[130:131] op_sel:[1,0,0]
	v_pk_fma_f32 v[122:123], v[48:49], v[188:189], v[122:123] op_sel_hi:[0,1,1]
	v_pk_fma_f32 v[114:115], v[156:157], v[136:137], v[114:115] op_sel_hi:[0,1,1]
	v_cvt_f32_f16_sdwa v189, v28 dst_sel:DWORD dst_unused:UNUSED_PAD src0_sel:WORD_1
	v_cvt_f32_f16_e32 v188, v28
	v_pk_fma_f32 v[124:125], v[58:59], v[136:137], v[124:125] op_sel_hi:[0,1,1]
	v_pk_fma_f32 v[116:117], v[58:59], v[136:137], v[116:117] op_sel:[1,0,0]
	v_pk_fma_f32 v[110:111], v[60:61], v[136:137], v[110:111] op_sel_hi:[0,1,1]
	v_pk_fma_f32 v[104:105], v[154:155], v[136:137], v[104:105] op_sel_hi:[0,1,1]
	v_pk_fma_f32 v[118:119], v[34:35], v[136:137], v[118:119] op_sel_hi:[0,1,1]
	v_pk_fma_f32 v[112:113], v[34:35], v[136:137], v[112:113] op_sel:[1,0,0]
	v_pk_fma_f32 v[106:107], v[40:41], v[142:143], v[106:107] op_sel_hi:[0,1,1]
	v_cvt_f32_f16_sdwa v137, v5 dst_sel:DWORD dst_unused:UNUSED_PAD src0_sel:WORD_1
	v_cvt_f32_f16_e32 v136, v5
	v_pk_fma_f32 v[106:107], v[44:45], v[174:175], v[106:107] op_sel_hi:[0,1,1]
	v_pk_fma_f32 v[106:107], v[48:49], v[178:179], v[106:107] op_sel_hi:[0,1,1]
	v_pk_fma_f32 v[4:5], v[52:53], v[180:181], v[106:107] op_sel_hi:[0,1,1]
	v_pk_fma_f32 v[106:107], v[56:57], v[188:189], v[4:5] op_sel_hi:[0,1,1]
	v_pk_fma_f32 v[4:5], v[156:157], v[136:137], v[98:99] op_sel_hi:[0,1,1]
	v_cvt_f32_f16_sdwa v99, v9 dst_sel:DWORD dst_unused:UNUSED_PAD src0_sel:WORD_1
	v_cvt_f32_f16_e32 v98, v9
	v_cvt_f32_f16_sdwa v9, v13 dst_sel:DWORD dst_unused:UNUSED_PAD src0_sel:WORD_1
	v_cvt_f32_f16_e32 v8, v13
	v_cvt_f32_f16_sdwa v13, v17 dst_sel:DWORD dst_unused:UNUSED_PAD src0_sel:WORD_1
	v_cvt_f32_f16_e32 v12, v17
	v_cvt_f32_f16_sdwa v17, v25 dst_sel:DWORD dst_unused:UNUSED_PAD src0_sel:WORD_1
	v_cvt_f32_f16_e32 v16, v25
	v_pk_fma_f32 v[4:5], v[6:7], v[98:99], v[4:5] op_sel_hi:[0,1,1]
	v_pk_fma_f32 v[114:115], v[6:7], v[142:143], v[114:115] op_sel_hi:[0,1,1]
	v_pk_fma_f32 v[4:5], v[10:11], v[8:9], v[4:5] op_sel_hi:[0,1,1]
	v_pk_fma_f32 v[114:115], v[10:11], v[174:175], v[114:115] op_sel_hi:[0,1,1]
	v_pk_fma_f32 v[4:5], v[22:23], v[12:13], v[4:5] op_sel_hi:[0,1,1]
	v_pk_fma_f32 v[114:115], v[22:23], v[178:179], v[114:115] op_sel_hi:[0,1,1]
	v_pk_fma_f32 v[22:23], v[158:159], v[16:17], v[4:5] op_sel_hi:[0,1,1]
	v_pk_fma_f32 v[4:5], v[58:59], v[136:137], v[108:109] op_sel_hi:[0,1,1]
	v_cvt_f32_f16_sdwa v25, v29 dst_sel:DWORD dst_unused:UNUSED_PAD src0_sel:WORD_1
	v_cvt_f32_f16_e32 v24, v29
	v_pk_fma_f32 v[4:5], v[62:63], v[98:99], v[4:5] op_sel_hi:[0,1,1]
	v_pk_fma_f32 v[4:5], v[66:67], v[8:9], v[4:5] op_sel_hi:[0,1,1]
	v_pk_fma_f32 v[4:5], v[70:71], v[12:13], v[4:5] op_sel_hi:[0,1,1]
	v_pk_fma_f32 v[4:5], v[74:75], v[16:17], v[4:5] op_sel_hi:[0,1,1]
	v_pk_fma_f32 v[28:29], v[78:79], v[24:25], v[4:5] op_sel_hi:[0,1,1]
	v_pk_fma_f32 v[4:5], v[58:59], v[136:137], v[100:101] op_sel:[1,0,0]
	v_pk_fma_f32 v[124:125], v[62:63], v[142:143], v[124:125] op_sel_hi:[0,1,1]
	v_pk_fma_f32 v[4:5], v[62:63], v[98:99], v[4:5] op_sel:[1,0,0]
	v_pk_fma_f32 v[116:117], v[62:63], v[142:143], v[116:117] op_sel:[1,0,0]
	v_pk_fma_f32 v[4:5], v[66:67], v[8:9], v[4:5] op_sel:[1,0,0]
	v_pk_fma_f32 v[110:111], v[64:65], v[142:143], v[110:111] op_sel_hi:[0,1,1]
	v_pk_fma_f32 v[4:5], v[70:71], v[12:13], v[4:5] op_sel:[1,0,0]
	v_pk_fma_f32 v[118:119], v[38:39], v[142:143], v[118:119] op_sel_hi:[0,1,1]
	v_pk_fma_f32 v[4:5], v[74:75], v[16:17], v[4:5] op_sel:[1,0,0]
	v_pk_fma_f32 v[112:113], v[38:39], v[142:143], v[112:113] op_sel:[1,0,0]
	v_pk_fma_f32 v[58:59], v[78:79], v[24:25], v[4:5] op_sel:[1,0,0]
	v_pk_fma_f32 v[4:5], v[60:61], v[136:137], v[94:95] op_sel_hi:[0,1,1]
	v_pk_fma_f32 v[4:5], v[64:65], v[98:99], v[4:5] op_sel_hi:[0,1,1]
	v_pk_fma_f32 v[4:5], v[68:69], v[8:9], v[4:5] op_sel_hi:[0,1,1]
	v_pk_fma_f32 v[4:5], v[72:73], v[12:13], v[4:5] op_sel_hi:[0,1,1]
	v_pk_fma_f32 v[4:5], v[76:77], v[16:17], v[4:5] op_sel_hi:[0,1,1]
	v_pk_fma_f32 v[60:61], v[80:81], v[24:25], v[4:5] op_sel_hi:[0,1,1]
	v_pk_fma_f32 v[4:5], v[154:155], v[136:137], v[90:91] op_sel_hi:[0,1,1]
	v_pk_fma_f32 v[4:5], v[194:195], v[98:99], v[4:5] op_sel_hi:[0,1,1]
	v_pk_fma_f32 v[4:5], v[196:197], v[8:9], v[4:5] op_sel_hi:[0,1,1]
	v_pk_fma_f32 v[4:5], v[198:199], v[12:13], v[4:5] op_sel_hi:[0,1,1]
	v_pk_fma_f32 v[4:5], v[200:201], v[16:17], v[4:5] op_sel_hi:[0,1,1]
	v_pk_fma_f32 v[62:63], v[202:203], v[24:25], v[4:5] op_sel_hi:[0,1,1]
	v_pk_fma_f32 v[4:5], v[34:35], v[136:137], v[102:103] op_sel_hi:[0,1,1]
	v_pk_fma_f32 v[4:5], v[38:39], v[98:99], v[4:5] op_sel_hi:[0,1,1]
	v_pk_fma_f32 v[4:5], v[42:43], v[8:9], v[4:5] op_sel_hi:[0,1,1]
	v_pk_fma_f32 v[4:5], v[46:47], v[12:13], v[4:5] op_sel_hi:[0,1,1]
	v_pk_fma_f32 v[4:5], v[50:51], v[16:17], v[4:5] op_sel_hi:[0,1,1]
	v_pk_fma_f32 v[64:65], v[54:55], v[24:25], v[4:5] op_sel_hi:[0,1,1]
	v_pk_fma_f32 v[4:5], v[34:35], v[136:137], v[96:97] op_sel:[1,0,0]
	v_pk_fma_f32 v[118:119], v[42:43], v[174:175], v[118:119] op_sel_hi:[0,1,1]
	v_pk_fma_f32 v[4:5], v[38:39], v[98:99], v[4:5] op_sel:[1,0,0]
	v_pk_fma_f32 v[112:113], v[42:43], v[174:175], v[112:113] op_sel:[1,0,0]
	v_pk_fma_f32 v[4:5], v[42:43], v[8:9], v[4:5] op_sel:[1,0,0]
	v_pk_fma_f32 v[118:119], v[46:47], v[178:179], v[118:119] op_sel_hi:[0,1,1]
	v_pk_fma_f32 v[4:5], v[46:47], v[12:13], v[4:5] op_sel:[1,0,0]
	v_pk_fma_f32 v[112:113], v[46:47], v[178:179], v[112:113] op_sel:[1,0,0]
	v_pk_fma_f32 v[4:5], v[50:51], v[16:17], v[4:5] op_sel:[1,0,0]
	s_waitcnt vmcnt(9)
; __device__ __forceinline__ void dsa_item(const KP& p, int b, int tile, char* smem) {
;     ...
; #pragma unroll
;         for (int i = 0; i < 8; ++i) {
;           const int pos = (g8 * 8 + i) * 8 + rs;
;           const f32x4 pa = *(const f32x4*)&pbuf[pos * 8];
;           const f32x4 pb = *(const f32x4*)&pbuf[pos * 8 + 4];
;           float vf[8];
; #pragma unroll
;           for (int e = 0; e < 8; ++e) vf[e] = (float)vv[i][e];
; #pragma unroll
;           for (int e = 0; e < 8; ++e) {
;             acc[0][e] += pa[0] * vf[e]; acc[1][e] += pa[1] * vf[e]; acc[2][e] += pa[2] * vf[e]; acc[3][e] += pa[3] * vf[e];
;             acc[4][e] += pb[0] * vf[e]; acc[5][e] += pb[1] * vf[e]; acc[6][e] += pb[2] * vf[e]; acc[7][e] += pb[3] * vf[e];
;           }
	v_cvt_f32_f16_sdwa v43, v19 dst_sel:DWORD dst_unused:UNUSED_PAD src0_sel:WORD_1
	v_pk_fma_f32 v[34:35], v[54:55], v[24:25], v[4:5] op_sel:[1,0,0]
	v_pk_fma_f32 v[4:5], v[36:37], v[136:137], v[92:93] op_sel_hi:[0,1,1]
	v_pk_fma_f32 v[4:5], v[40:41], v[98:99], v[4:5] op_sel_hi:[0,1,1]
	v_pk_fma_f32 v[4:5], v[44:45], v[8:9], v[4:5] op_sel_hi:[0,1,1]
	v_pk_fma_f32 v[4:5], v[48:49], v[12:13], v[4:5] op_sel_hi:[0,1,1]
	v_pk_fma_f32 v[4:5], v[52:53], v[16:17], v[4:5] op_sel_hi:[0,1,1]
	v_pk_fma_f32 v[12:13], v[56:57], v[24:25], v[4:5] op_sel_hi:[0,1,1]
	ds_read_b128 v[4:7], v172 offset:1536
	ds_read_b128 v[8:11], v172 offset:1552
	v_pk_fma_f32 v[24:25], v[176:177], v[24:25], v[22:23] op_sel_hi:[0,1,1]
	v_cvt_f32_f16_sdwa v37, v18 dst_sel:DWORD dst_unused:UNUSED_PAD src0_sel:WORD_1
	v_cvt_f32_f16_e32 v36, v18
	v_cvt_f32_f16_e32 v42, v19
	v_cvt_f32_f16_sdwa v45, v20 dst_sel:DWORD dst_unused:UNUSED_PAD src0_sel:WORD_1
	v_cvt_f32_f16_e32 v44, v20
	v_cvt_f32_f16_sdwa v47, v21 dst_sel:DWORD dst_unused:UNUSED_PAD src0_sel:WORD_1
	v_cvt_f32_f16_e32 v46, v21
	ds_read_b128 v[16:19], v172 offset:1792
	ds_read_b128 v[20:23], v172 offset:1808
	s_waitcnt vmcnt(8)
	v_cvt_f32_f16_e32 v48, v30
	v_cvt_f32_f16_sdwa v49, v30 dst_sel:DWORD dst_unused:UNUSED_PAD src0_sel:WORD_1
	v_pk_fma_f32 v[124:125], v[66:67], v[174:175], v[124:125] op_sel_hi:[0,1,1]
	v_pk_fma_f32 v[116:117], v[66:67], v[174:175], v[116:117] op_sel:[1,0,0]
	v_pk_fma_f32 v[110:111], v[68:69], v[174:175], v[110:111] op_sel_hi:[0,1,1]
	v_pk_fma_f32 v[104:105], v[194:195], v[142:143], v[104:105] op_sel_hi:[0,1,1]
	v_cvt_f32_f16_e32 v30, v31
	v_cvt_f32_f16_sdwa v31, v31 dst_sel:DWORD dst_unused:UNUSED_PAD src0_sel:WORD_1
	v_pk_fma_f32 v[14:15], v[74:75], v[190:191], v[14:15] op_sel_hi:[0,1,1]
	v_pk_fma_f32 v[26:27], v[74:75], v[190:191], v[26:27] op_sel:[1,0,0]
	v_pk_fma_f32 v[128:129], v[76:77], v[190:191], v[128:129] op_sel_hi:[0,1,1]
	v_pk_fma_f32 v[134:135], v[50:51], v[190:191], v[134:135] op_sel_hi:[0,1,1]
	v_pk_fma_f32 v[130:131], v[50:51], v[190:191], v[130:131] op_sel:[1,0,0]
	v_pk_fma_f32 v[124:125], v[70:71], v[178:179], v[124:125] op_sel_hi:[0,1,1]
	v_pk_fma_f32 v[116:117], v[70:71], v[178:179], v[116:117] op_sel:[1,0,0]
	v_pk_fma_f32 v[110:111], v[72:73], v[178:179], v[110:111] op_sel_hi:[0,1,1]
	v_pk_fma_f32 v[104:105], v[196:197], v[174:175], v[104:105] op_sel_hi:[0,1,1]
	v_pk_fma_f32 v[118:119], v[50:51], v[180:181], v[118:119] op_sel_hi:[0,1,1]
	v_pk_fma_f32 v[112:113], v[50:51], v[180:181], v[112:113] op_sel:[1,0,0]
	v_cvt_f32_f16_e32 v50, v32
	v_cvt_f32_f16_sdwa v51, v32 dst_sel:DWORD dst_unused:UNUSED_PAD src0_sel:WORD_1
	v_pk_fma_f32 v[14:15], v[78:79], v[192:193], v[14:15] op_sel_hi:[0,1,1]
	v_pk_fma_f32 v[26:27], v[78:79], v[192:193], v[26:27] op_sel:[1,0,0]
	v_pk_fma_f32 v[128:129], v[80:81], v[192:193], v[128:129] op_sel_hi:[0,1,1]
	v_pk_fma_f32 v[120:121], v[200:201], v[190:191], v[120:121] op_sel_hi:[0,1,1]
	v_pk_fma_f32 v[122:123], v[52:53], v[190:191], v[122:123] op_sel_hi:[0,1,1]
	v_pk_fma_f32 v[124:125], v[74:75], v[180:181], v[124:125] op_sel_hi:[0,1,1]
	v_pk_fma_f32 v[116:117], v[74:75], v[180:181], v[116:117] op_sel:[1,0,0]
	v_pk_fma_f32 v[110:111], v[76:77], v[180:181], v[110:111] op_sel_hi:[0,1,1]
	v_pk_fma_f32 v[104:105], v[198:199], v[178:179], v[104:105] op_sel_hi:[0,1,1]
	s_waitcnt lgkmcnt(3)
	v_mov_b32_e32 v38, v7
	s_waitcnt lgkmcnt(2)
	v_mov_b32_e32 v40, v11
	v_cvt_f32_f16_e32 v32, v33
	v_cvt_f32_f16_sdwa v33, v33 dst_sel:DWORD dst_unused:UNUSED_PAD src0_sel:WORD_1
	v_pk_fma_f32 v[2:3], v[10:11], v[36:37], v[2:3] op_sel_hi:[0,1,1]
	v_pk_fma_f32 v[120:121], v[202:203], v[192:193], v[120:121] op_sel_hi:[0,1,1]
	v_pk_fma_f32 v[134:135], v[54:55], v[192:193], v[134:135] op_sel_hi:[0,1,1]
	v_pk_fma_f32 v[130:131], v[54:55], v[192:193], v[130:131] op_sel:[1,0,0]
	v_pk_fma_f32 v[122:123], v[56:57], v[192:193], v[122:123] op_sel_hi:[0,1,1]
	v_pk_fma_f32 v[132:133], v[176:177], v[192:193], v[132:133] op_sel_hi:[0,1,1]
	v_pk_fma_f32 v[114:115], v[158:159], v[180:181], v[114:115] op_sel_hi:[0,1,1]
	v_pk_fma_f32 v[124:125], v[78:79], v[188:189], v[124:125] op_sel_hi:[0,1,1]
	v_pk_fma_f32 v[116:117], v[78:79], v[188:189], v[116:117] op_sel:[1,0,0]
	v_pk_fma_f32 v[110:111], v[80:81], v[188:189], v[110:111] op_sel_hi:[0,1,1]
	v_pk_fma_f32 v[104:105], v[200:201], v[180:181], v[104:105] op_sel_hi:[0,1,1]
	v_pk_fma_f32 v[118:119], v[54:55], v[188:189], v[118:119] op_sel_hi:[0,1,1]
	v_pk_fma_f32 v[112:113], v[54:55], v[188:189], v[112:113] op_sel:[1,0,0]
	v_pk_fma_f32 v[52:53], v[4:5], v[36:37], v[148:149] op_sel_hi:[0,1,1]
	v_pk_fma_f32 v[54:55], v[4:5], v[36:37], v[152:153] op_sel:[1,0,0]
	v_pk_fma_f32 v[56:57], v[6:7], v[36:37], v[146:147] op_sel_hi:[0,1,1]
	v_pk_fma_f32 v[66:67], v[38:39], v[36:37], v[140:141] op_sel_hi:[0,1,1]
	v_pk_fma_f32 v[68:69], v[8:9], v[36:37], v[150:151] op_sel_hi:[0,1,1]
	v_pk_fma_f32 v[70:71], v[8:9], v[36:37], v[144:145] op_sel:[1,0,0]
	v_pk_fma_f32 v[36:37], v[40:41], v[36:37], v[138:139] op_sel_hi:[0,1,1]
	s_waitcnt lgkmcnt(1)
	v_mov_b32_e32 v72, v19
	s_waitcnt lgkmcnt(0)
; __device__ __forceinline__ void dsa_item(const KP& p, int b, int tile, char* smem) {
;     ...
;       for (int g8 = 0; g8 < 4; ++g8) {
;         h8 vv[8];
; #pragma unroll
;         for (int i = 0; i < 8; ++i) {
;           const int pos = (g8 * 8 + i) * 8 + rs;
;           const int s = (pos < nsel) ? (int)sel[tk * 256 + pos] : 0;
;           vv[i] = *(const h8*)(ub + (size_t)s * NU + C_BV + dc * 8);
;         }
; #pragma unroll
;         for (int i = 0; i < 8; ++i) {
;           const int pos = (g8 * 8 + i) * 8 + rs;
;           const f32x4 pa = *(const f32x4*)&pbuf[pos * 8];
;           const f32x4 pb = *(const f32x4*)&pbuf[pos * 8 + 4];
;           float vf[8];
; #pragma unroll
;           for (int e = 0; e < 8; ++e) vf[e] = (float)vv[i][e];
; #pragma unroll
;           for (int e = 0; e < 8; ++e) {
;             acc[0][e] += pa[0] * vf[e]; acc[1][e] += pa[1] * vf[e]; acc[2][e] += pa[2] * vf[e]; acc[3][e] += pa[3] * vf[e];
;             acc[4][e] += pb[0] * vf[e]; acc[5][e] += pb[1] * vf[e]; acc[6][e] += pb[2] * vf[e]; acc[7][e] += pb[3] * vf[e];
;           }
	v_mov_b32_e32 v74, v23
	v_pk_fma_f32 v[138:139], v[22:23], v[48:49], v[2:3] op_sel_hi:[0,1,1]
	v_pk_fma_f32 v[2:3], v[4:5], v[42:43], v[14:15] op_sel_hi:[0,1,1]
	v_pk_fma_f32 v[14:15], v[4:5], v[42:43], v[26:27] op_sel:[1,0,0]
	v_pk_fma_f32 v[26:27], v[6:7], v[42:43], v[128:129] op_sel_hi:[0,1,1]
	v_pk_fma_f32 v[104:105], v[202:203], v[188:189], v[104:105] op_sel_hi:[0,1,1]
	v_pk_fma_f32 v[114:115], v[176:177], v[188:189], v[114:115] op_sel_hi:[0,1,1]
	v_pk_fma_f32 v[154:155], v[16:17], v[48:49], v[52:53] op_sel_hi:[0,1,1]
	v_pk_fma_f32 v[152:153], v[16:17], v[48:49], v[54:55] op_sel:[1,0,0]
	v_pk_fma_f32 v[146:147], v[18:19], v[48:49], v[56:57] op_sel_hi:[0,1,1]
	v_pk_fma_f32 v[140:141], v[72:73], v[48:49], v[66:67] op_sel_hi:[0,1,1]
	v_pk_fma_f32 v[150:151], v[20:21], v[48:49], v[68:69] op_sel_hi:[0,1,1]
	v_pk_fma_f32 v[144:145], v[20:21], v[48:49], v[70:71] op_sel:[1,0,0]
	v_pk_fma_f32 v[148:149], v[74:75], v[48:49], v[36:37] op_sel_hi:[0,1,1]
	v_pk_fma_f32 v[36:37], v[38:39], v[42:43], v[120:121] op_sel_hi:[0,1,1]
	v_pk_fma_f32 v[48:49], v[8:9], v[42:43], v[134:135] op_sel_hi:[0,1,1]
	v_pk_fma_f32 v[52:53], v[8:9], v[42:43], v[130:131] op_sel:[1,0,0]
	v_pk_fma_f32 v[54:55], v[10:11], v[42:43], v[122:123] op_sel_hi:[0,1,1]
	v_pk_fma_f32 v[42:43], v[40:41], v[42:43], v[132:133] op_sel_hi:[0,1,1]
	v_pk_fma_f32 v[142:143], v[16:17], v[30:31], v[2:3] op_sel_hi:[0,1,1]
	v_pk_fma_f32 v[134:135], v[16:17], v[30:31], v[14:15] op_sel:[1,0,0]
	v_pk_fma_f32 v[128:129], v[18:19], v[30:31], v[26:27] op_sel_hi:[0,1,1]
	v_pk_fma_f32 v[2:3], v[4:5], v[44:45], v[124:125] op_sel_hi:[0,1,1]
	v_pk_fma_f32 v[14:15], v[4:5], v[44:45], v[116:117] op_sel:[1,0,0]
	v_pk_fma_f32 v[26:27], v[6:7], v[44:45], v[110:111] op_sel_hi:[0,1,1]
	v_pk_fma_f32 v[120:121], v[72:73], v[30:31], v[36:37] op_sel_hi:[0,1,1]
	v_pk_fma_f32 v[136:137], v[20:21], v[30:31], v[48:49] op_sel_hi:[0,1,1]
	v_pk_fma_f32 v[130:131], v[20:21], v[30:31], v[52:53] op_sel:[1,0,0]
	v_pk_fma_f32 v[122:123], v[22:23], v[30:31], v[54:55] op_sel_hi:[0,1,1]
	v_pk_fma_f32 v[132:133], v[74:75], v[30:31], v[42:43] op_sel_hi:[0,1,1]
	v_pk_fma_f32 v[30:31], v[38:39], v[44:45], v[104:105] op_sel_hi:[0,1,1]
	v_pk_fma_f32 v[36:37], v[8:9], v[44:45], v[118:119] op_sel_hi:[0,1,1]
	v_pk_fma_f32 v[42:43], v[8:9], v[44:45], v[112:113] op_sel:[1,0,0]
	v_pk_fma_f32 v[48:49], v[10:11], v[44:45], v[106:107] op_sel_hi:[0,1,1]
	v_pk_fma_f32 v[44:45], v[40:41], v[44:45], v[114:115] op_sel_hi:[0,1,1]
	v_pk_fma_f32 v[124:125], v[16:17], v[50:51], v[2:3] op_sel_hi:[0,1,1]
	v_pk_fma_f32 v[116:117], v[16:17], v[50:51], v[14:15] op_sel:[1,0,0]
	v_pk_fma_f32 v[110:111], v[18:19], v[50:51], v[26:27] op_sel_hi:[0,1,1]
	v_pk_fma_f32 v[2:3], v[4:5], v[46:47], v[28:29] op_sel_hi:[0,1,1]
	v_pk_fma_f32 v[4:5], v[4:5], v[46:47], v[58:59] op_sel:[1,0,0]
	v_pk_fma_f32 v[6:7], v[6:7], v[46:47], v[60:61] op_sel_hi:[0,1,1]
	v_pk_fma_f32 v[14:15], v[38:39], v[46:47], v[62:63] op_sel_hi:[0,1,1]
	v_pk_fma_f32 v[26:27], v[8:9], v[46:47], v[64:65] op_sel_hi:[0,1,1]
	v_pk_fma_f32 v[8:9], v[8:9], v[46:47], v[34:35] op_sel:[1,0,0]
	v_pk_fma_f32 v[10:11], v[10:11], v[46:47], v[12:13] op_sel_hi:[0,1,1]
	v_pk_fma_f32 v[12:13], v[40:41], v[46:47], v[24:25] op_sel_hi:[0,1,1]
	v_pk_fma_f32 v[104:105], v[72:73], v[50:51], v[30:31] op_sel_hi:[0,1,1]
	v_pk_fma_f32 v[118:119], v[20:21], v[50:51], v[36:37] op_sel_hi:[0,1,1]
	v_pk_fma_f32 v[112:113], v[20:21], v[50:51], v[42:43] op_sel:[1,0,0]
	v_pk_fma_f32 v[106:107], v[22:23], v[50:51], v[48:49] op_sel_hi:[0,1,1]
	v_pk_fma_f32 v[114:115], v[74:75], v[50:51], v[44:45] op_sel_hi:[0,1,1]
	v_pk_fma_f32 v[108:109], v[16:17], v[32:33], v[2:3] op_sel_hi:[0,1,1]
	v_pk_fma_f32 v[100:101], v[16:17], v[32:33], v[4:5] op_sel:[1,0,0]
	v_pk_fma_f32 v[94:95], v[18:19], v[32:33], v[6:7] op_sel_hi:[0,1,1]
	v_pk_fma_f32 v[90:91], v[72:73], v[32:33], v[14:15] op_sel_hi:[0,1,1]
	v_pk_fma_f32 v[102:103], v[20:21], v[32:33], v[26:27] op_sel_hi:[0,1,1]
	v_pk_fma_f32 v[96:97], v[20:21], v[32:33], v[8:9] op_sel:[1,0,0]
	v_pk_fma_f32 v[92:93], v[22:23], v[32:33], v[10:11] op_sel_hi:[0,1,1]
	v_pk_fma_f32 v[98:99], v[74:75], v[32:33], v[12:13] op_sel_hi:[0,1,1]
	v_add_u32_e32 v172, 0x800, v172
	v_lshlrev_b32_e32 v35, 8, v159
	v_lshl_add_u32 v35, v165, 2, v35
	v_add_u32_e32 v35, 0xcc00, v35
	ds_read_b32 v2, v35 offset:512
	ds_read_b32 v6, v35 offset:544
	ds_read_b32 v10, v35 offset:576
	ds_read_b32 v14, v35 offset:608
	ds_read_b32 v22, v35 offset:640
	ds_read_b32 v26, v35 offset:672
	ds_read_b32 v18, v35 offset:704
	ds_read_b32 v30, v35 offset:736
	s_waitcnt lgkmcnt(4)
	v_add_u32_e32 v2, v2, v0
	global_load_dwordx4 v[2:5], v2, s[2:3]
	v_add_u32_e32 v6, v6, v0
	global_load_dwordx4 v[6:9], v6, s[2:3]
	v_add_u32_e32 v10, v10, v0
	global_load_dwordx4 v[10:13], v10, s[2:3]
	v_add_u32_e32 v14, v14, v0
	global_load_dwordx4 v[14:17], v14, s[2:3]
	s_waitcnt lgkmcnt(0)
	v_add_u32_e32 v22, v22, v0
	global_load_dwordx4 v[22:25], v22, s[2:3]
	v_add_u32_e32 v26, v26, v0
	global_load_dwordx4 v[26:29], v26, s[2:3]
	v_add_u32_e32 v18, v18, v0
	global_load_dwordx4 v[18:21], v18, s[2:3]
	v_add_u32_e32 v30, v30, v0
	global_load_dwordx4 v[30:33], v30, s[2:3]
	s_waitcnt vmcnt(15)
	v_cvt_f32_f16_sdwa v175, v204 dst_sel:DWORD dst_unused:UNUSED_PAD src0_sel:WORD_1
	v_cvt_f32_f16_e32 v174, v204
	s_waitcnt vmcnt(14)
	v_cvt_f32_f16_sdwa v177, v208 dst_sel:DWORD dst_unused:UNUSED_PAD src0_sel:WORD_1
	v_cvt_f32_f16_e32 v176, v208
	ds_read_b128 v[58:61], v172
	ds_read_b128 v[34:37], v172 offset:16
	ds_read_b128 v[62:65], v172 offset:256
	ds_read_b128 v[38:41], v172 offset:272
	ds_read_b128 v[66:69], v172 offset:512
	ds_read_b128 v[42:45], v172 offset:528
	ds_read_b128 v[70:73], v172 offset:768
	ds_read_b128 v[46:49], v172 offset:784
	ds_read_b128 v[74:77], v172 offset:1024
	ds_read_b128 v[50:53], v172 offset:1040
	s_waitcnt vmcnt(13)
; __device__ __forceinline__ void dsa_item(const KP& p, int b, int tile, char* smem) {
;     ...
; #pragma unroll
;         for (int i = 0; i < 8; ++i) {
;           const int pos = (g8 * 8 + i) * 8 + rs;
;           const f32x4 pa = *(const f32x4*)&pbuf[pos * 8];
;           const f32x4 pb = *(const f32x4*)&pbuf[pos * 8 + 4];
;           float vf[8];
; #pragma unroll
;           for (int e = 0; e < 8; ++e) vf[e] = (float)vv[i][e];
; #pragma unroll
;           for (int e = 0; e < 8; ++e) {
;             acc[0][e] += pa[0] * vf[e]; acc[1][e] += pa[1] * vf[e]; acc[2][e] += pa[2] * vf[e]; acc[3][e] += pa[3] * vf[e];
;             acc[4][e] += pb[0] * vf[e]; acc[5][e] += pb[1] * vf[e]; acc[6][e] += pb[2] * vf[e]; acc[7][e] += pb[3] * vf[e];
;           }
	v_cvt_f32_f16_sdwa v179, v212 dst_sel:DWORD dst_unused:UNUSED_PAD src0_sel:WORD_1
	v_cvt_f32_f16_e32 v178, v212
	s_waitcnt lgkmcnt(8)
	v_mov_b32_e32 v156, v37
	s_waitcnt vmcnt(12)
	v_cvt_f32_f16_sdwa v181, v216 dst_sel:DWORD dst_unused:UNUSED_PAD src0_sel:WORD_1
	v_cvt_f32_f16_e32 v180, v216
	v_pk_fma_f32 v[148:149], v[156:157], v[174:175], v[148:149] op_sel_hi:[0,1,1]
	s_waitcnt lgkmcnt(6)
	v_mov_b32_e32 v208, v41
	s_waitcnt vmcnt(11)
	v_cvt_f32_f16_sdwa v189, v224 dst_sel:DWORD dst_unused:UNUSED_PAD src0_sel:WORD_1
	v_cvt_f32_f16_e32 v188, v224
	v_pk_fma_f32 v[148:149], v[208:209], v[176:177], v[148:149] op_sel_hi:[0,1,1]
	s_waitcnt lgkmcnt(4)
	v_mov_b32_e32 v212, v45
	v_pk_fma_f32 v[148:149], v[212:213], v[178:179], v[148:149] op_sel_hi:[0,1,1]
	s_waitcnt lgkmcnt(2)
	v_mov_b32_e32 v224, v49
	v_pk_fma_f32 v[148:149], v[224:225], v[180:181], v[148:149] op_sel_hi:[0,1,1]
	s_waitcnt lgkmcnt(0)
	v_mov_b32_e32 v158, v53
	ds_read_b128 v[78:81], v172 offset:1280
	ds_read_b128 v[54:57], v172 offset:1296
	v_pk_fma_f32 v[190:191], v[158:159], v[188:189], v[148:149] op_sel_hi:[0,1,1]
	v_pk_fma_f32 v[148:149], v[58:59], v[174:175], v[154:155] op_sel_hi:[0,1,1]
	v_mov_b32_e32 v154, v61
	v_pk_fma_f32 v[152:153], v[58:59], v[174:175], v[152:153] op_sel:[1,0,0]
	v_pk_fma_f32 v[146:147], v[60:61], v[174:175], v[146:147] op_sel_hi:[0,1,1]
	v_pk_fma_f32 v[140:141], v[154:155], v[174:175], v[140:141] op_sel_hi:[0,1,1]
	v_mov_b32_e32 v194, v65
	v_pk_fma_f32 v[150:151], v[34:35], v[174:175], v[150:151] op_sel_hi:[0,1,1]
	v_pk_fma_f32 v[144:145], v[34:35], v[174:175], v[144:145] op_sel:[1,0,0]
	v_pk_fma_f32 v[138:139], v[36:37], v[174:175], v[138:139] op_sel_hi:[0,1,1]
	s_waitcnt vmcnt(10)
	v_cvt_f32_f16_sdwa v193, v228 dst_sel:DWORD dst_unused:UNUSED_PAD src0_sel:WORD_1
	v_cvt_f32_f16_e32 v192, v228
	v_pk_fma_f32 v[148:149], v[62:63], v[176:177], v[148:149] op_sel_hi:[0,1,1]
	v_pk_fma_f32 v[152:153], v[62:63], v[176:177], v[152:153] op_sel:[1,0,0]
	v_pk_fma_f32 v[146:147], v[64:65], v[176:177], v[146:147] op_sel_hi:[0,1,1]
	v_pk_fma_f32 v[140:141], v[194:195], v[176:177], v[140:141] op_sel_hi:[0,1,1]
	v_mov_b32_e32 v196, v69
	v_pk_fma_f32 v[150:151], v[38:39], v[176:177], v[150:151] op_sel_hi:[0,1,1]
	v_pk_fma_f32 v[144:145], v[38:39], v[176:177], v[144:145] op_sel:[1,0,0]
	v_pk_fma_f32 v[138:139], v[40:41], v[176:177], v[138:139] op_sel_hi:[0,1,1]
	v_cvt_f32_f16_sdwa v175, v205 dst_sel:DWORD dst_unused:UNUSED_PAD src0_sel:WORD_1
	v_cvt_f32_f16_e32 v174, v205
	v_pk_fma_f32 v[148:149], v[66:67], v[178:179], v[148:149] op_sel_hi:[0,1,1]
	v_pk_fma_f32 v[152:153], v[66:67], v[178:179], v[152:153] op_sel:[1,0,0]
	v_pk_fma_f32 v[146:147], v[68:69], v[178:179], v[146:147] op_sel_hi:[0,1,1]
	v_pk_fma_f32 v[140:141], v[196:197], v[178:179], v[140:141] op_sel_hi:[0,1,1]
	v_mov_b32_e32 v198, v73
	v_pk_fma_f32 v[150:151], v[42:43], v[178:179], v[150:151] op_sel_hi:[0,1,1]
	v_pk_fma_f32 v[144:145], v[42:43], v[178:179], v[144:145] op_sel:[1,0,0]
	v_pk_fma_f32 v[138:139], v[44:45], v[178:179], v[138:139] op_sel_hi:[0,1,1]
	v_cvt_f32_f16_sdwa v179, v209 dst_sel:DWORD dst_unused:UNUSED_PAD src0_sel:WORD_1
	v_cvt_f32_f16_e32 v178, v209
	v_pk_fma_f32 v[148:149], v[70:71], v[180:181], v[148:149] op_sel_hi:[0,1,1]
	v_pk_fma_f32 v[152:153], v[70:71], v[180:181], v[152:153] op_sel:[1,0,0]
	v_pk_fma_f32 v[146:147], v[72:73], v[180:181], v[146:147] op_sel_hi:[0,1,1]
	v_pk_fma_f32 v[140:141], v[198:199], v[180:181], v[140:141] op_sel_hi:[0,1,1]
	v_mov_b32_e32 v200, v77
	v_pk_fma_f32 v[150:151], v[46:47], v[180:181], v[150:151] op_sel_hi:[0,1,1]
	v_pk_fma_f32 v[144:145], v[46:47], v[180:181], v[144:145] op_sel:[1,0,0]
	v_pk_fma_f32 v[138:139], v[48:49], v[180:181], v[138:139] op_sel_hi:[0,1,1]
	v_cvt_f32_f16_sdwa v181, v213 dst_sel:DWORD dst_unused:UNUSED_PAD src0_sel:WORD_1
	v_cvt_f32_f16_e32 v180, v213
	v_pk_fma_f32 v[148:149], v[74:75], v[188:189], v[148:149] op_sel_hi:[0,1,1]
	v_pk_fma_f32 v[152:153], v[74:75], v[188:189], v[152:153] op_sel:[1,0,0]
	v_pk_fma_f32 v[146:147], v[76:77], v[188:189], v[146:147] op_sel_hi:[0,1,1]
	v_pk_fma_f32 v[140:141], v[200:201], v[188:189], v[140:141] op_sel_hi:[0,1,1]
	v_pk_fma_f32 v[150:151], v[50:51], v[188:189], v[150:151] op_sel_hi:[0,1,1]
	v_pk_fma_f32 v[144:145], v[50:51], v[188:189], v[144:145] op_sel:[1,0,0]
	v_pk_fma_f32 v[138:139], v[52:53], v[188:189], v[138:139] op_sel_hi:[0,1,1]
	s_waitcnt lgkmcnt(0)
; __device__ __forceinline__ void dsa_item(const KP& p, int b, int tile, char* smem) {
;     ...
; #pragma unroll
;         for (int i = 0; i < 8; ++i) {
;           const int pos = (g8 * 8 + i) * 8 + rs;
;           const f32x4 pa = *(const f32x4*)&pbuf[pos * 8];
;           const f32x4 pb = *(const f32x4*)&pbuf[pos * 8 + 4];
;           float vf[8];
; #pragma unroll
;           for (int e = 0; e < 8; ++e) vf[e] = (float)vv[i][e];
; #pragma unroll
;           for (int e = 0; e < 8; ++e) {
;             acc[0][e] += pa[0] * vf[e]; acc[1][e] += pa[1] * vf[e]; acc[2][e] += pa[2] * vf[e]; acc[3][e] += pa[3] * vf[e];
;             acc[4][e] += pb[0] * vf[e]; acc[5][e] += pb[1] * vf[e]; acc[6][e] += pb[2] * vf[e]; acc[7][e] += pb[3] * vf[e];
;           }
	v_mov_b32_e32 v176, v57
	v_cvt_f32_f16_sdwa v189, v217 dst_sel:DWORD dst_unused:UNUSED_PAD src0_sel:WORD_1
	v_cvt_f32_f16_e32 v188, v217
	v_pk_fma_f32 v[204:205], v[56:57], v[192:193], v[138:139] op_sel_hi:[0,1,1]
	v_pk_fma_f32 v[138:139], v[176:177], v[192:193], v[190:191] op_sel_hi:[0,1,1]
	v_pk_fma_f32 v[132:133], v[156:157], v[174:175], v[132:133] op_sel_hi:[0,1,1]
	v_cvt_f32_f16_sdwa v191, v225 dst_sel:DWORD dst_unused:UNUSED_PAD src0_sel:WORD_1
	v_cvt_f32_f16_e32 v190, v225
	v_pk_fma_f32 v[216:217], v[208:209], v[178:179], v[132:133] op_sel_hi:[0,1,1]
	v_mov_b32_e32 v202, v81
	v_pk_fma_f32 v[216:217], v[212:213], v[180:181], v[216:217] op_sel_hi:[0,1,1]
	v_pk_fma_f32 v[148:149], v[78:79], v[192:193], v[148:149] op_sel_hi:[0,1,1]
	v_pk_fma_f32 v[152:153], v[78:79], v[192:193], v[152:153] op_sel:[1,0,0]
	v_pk_fma_f32 v[146:147], v[80:81], v[192:193], v[146:147] op_sel_hi:[0,1,1]
	v_pk_fma_f32 v[140:141], v[202:203], v[192:193], v[140:141] op_sel_hi:[0,1,1]
	v_pk_fma_f32 v[150:151], v[54:55], v[192:193], v[150:151] op_sel_hi:[0,1,1]
	v_pk_fma_f32 v[144:145], v[54:55], v[192:193], v[144:145] op_sel:[1,0,0]
	v_pk_fma_f32 v[216:217], v[224:225], v[188:189], v[216:217] op_sel_hi:[0,1,1]
	v_cvt_f32_f16_sdwa v193, v229 dst_sel:DWORD dst_unused:UNUSED_PAD src0_sel:WORD_1
	v_cvt_f32_f16_e32 v192, v229
	v_pk_fma_f32 v[228:229], v[58:59], v[174:175], v[134:135] op_sel:[1,0,0]
	v_pk_fma_f32 v[134:135], v[34:35], v[174:175], v[136:137] op_sel_hi:[0,1,1]
	v_cvt_f32_f16_sdwa v137, v206 dst_sel:DWORD dst_unused:UNUSED_PAD src0_sel:WORD_1
	v_cvt_f32_f16_e32 v136, v206
	v_pk_fma_f32 v[132:133], v[158:159], v[190:191], v[216:217] op_sel_hi:[0,1,1]
	v_pk_fma_f32 v[216:217], v[58:59], v[174:175], v[142:143] op_sel_hi:[0,1,1]
	v_cvt_f32_f16_sdwa v143, v210 dst_sel:DWORD dst_unused:UNUSED_PAD src0_sel:WORD_1
	v_cvt_f32_f16_e32 v142, v210
	v_pk_fma_f32 v[128:129], v[60:61], v[174:175], v[128:129] op_sel_hi:[0,1,1]
	v_pk_fma_f32 v[120:121], v[154:155], v[174:175], v[120:121] op_sel_hi:[0,1,1]
	v_pk_fma_f32 v[130:131], v[34:35], v[174:175], v[130:131] op_sel:[1,0,0]
	v_pk_fma_f32 v[122:123], v[36:37], v[174:175], v[122:123] op_sel_hi:[0,1,1]
	v_cvt_f32_f16_sdwa v175, v214 dst_sel:DWORD dst_unused:UNUSED_PAD src0_sel:WORD_1
	v_cvt_f32_f16_e32 v174, v214
	v_pk_fma_f32 v[216:217], v[62:63], v[178:179], v[216:217] op_sel_hi:[0,1,1]
	v_pk_fma_f32 v[228:229], v[62:63], v[178:179], v[228:229] op_sel:[1,0,0]
	v_pk_fma_f32 v[128:129], v[64:65], v[178:179], v[128:129] op_sel_hi:[0,1,1]
	v_pk_fma_f32 v[120:121], v[194:195], v[178:179], v[120:121] op_sel_hi:[0,1,1]
	v_pk_fma_f32 v[134:135], v[38:39], v[178:179], v[134:135] op_sel_hi:[0,1,1]
	v_pk_fma_f32 v[130:131], v[38:39], v[178:179], v[130:131] op_sel:[1,0,0]
	v_pk_fma_f32 v[122:123], v[40:41], v[178:179], v[122:123] op_sel_hi:[0,1,1]
	v_cvt_f32_f16_sdwa v179, v218 dst_sel:DWORD dst_unused:UNUSED_PAD src0_sel:WORD_1
	v_cvt_f32_f16_e32 v178, v218
	v_pk_fma_f32 v[216:217], v[66:67], v[180:181], v[216:217] op_sel_hi:[0,1,1]
	v_pk_fma_f32 v[228:229], v[66:67], v[180:181], v[228:229] op_sel:[1,0,0]
	v_pk_fma_f32 v[128:129], v[68:69], v[180:181], v[128:129] op_sel_hi:[0,1,1]
	v_pk_fma_f32 v[120:121], v[196:197], v[180:181], v[120:121] op_sel_hi:[0,1,1]
	v_pk_fma_f32 v[134:135], v[42:43], v[180:181], v[134:135] op_sel_hi:[0,1,1]
	v_pk_fma_f32 v[130:131], v[42:43], v[180:181], v[130:131] op_sel:[1,0,0]
	v_pk_fma_f32 v[122:123], v[44:45], v[180:181], v[122:123] op_sel_hi:[0,1,1]
	v_cvt_f32_f16_sdwa v181, v226 dst_sel:DWORD dst_unused:UNUSED_PAD src0_sel:WORD_1
	v_cvt_f32_f16_e32 v180, v226
	v_pk_fma_f32 v[106:107], v[36:37], v[136:137], v[106:107] op_sel_hi:[0,1,1]
	v_pk_fma_f32 v[216:217], v[70:71], v[188:189], v[216:217] op_sel_hi:[0,1,1]
	v_pk_fma_f32 v[228:229], v[70:71], v[188:189], v[228:229] op_sel:[1,0,0]
	v_pk_fma_f32 v[128:129], v[72:73], v[188:189], v[128:129] op_sel_hi:[0,1,1]
	v_pk_fma_f32 v[120:121], v[198:199], v[188:189], v[120:121] op_sel_hi:[0,1,1]
	v_pk_fma_f32 v[134:135], v[46:47], v[188:189], v[134:135] op_sel_hi:[0,1,1]
	v_pk_fma_f32 v[130:131], v[46:47], v[188:189], v[130:131] op_sel:[1,0,0]
	v_pk_fma_f32 v[122:123], v[48:49], v[188:189], v[122:123] op_sel_hi:[0,1,1]
	v_pk_fma_f32 v[114:115], v[156:157], v[136:137], v[114:115] op_sel_hi:[0,1,1]
	v_cvt_f32_f16_sdwa v189, v230 dst_sel:DWORD dst_unused:UNUSED_PAD src0_sel:WORD_1
	v_cvt_f32_f16_e32 v188, v230
	v_pk_fma_f32 v[124:125], v[58:59], v[136:137], v[124:125] op_sel_hi:[0,1,1]
	v_pk_fma_f32 v[116:117], v[58:59], v[136:137], v[116:117] op_sel:[1,0,0]
	v_pk_fma_f32 v[110:111], v[60:61], v[136:137], v[110:111] op_sel_hi:[0,1,1]
	v_pk_fma_f32 v[104:105], v[154:155], v[136:137], v[104:105] op_sel_hi:[0,1,1]
	v_pk_fma_f32 v[118:119], v[34:35], v[136:137], v[118:119] op_sel_hi:[0,1,1]
	v_pk_fma_f32 v[112:113], v[34:35], v[136:137], v[112:113] op_sel:[1,0,0]
	v_pk_fma_f32 v[106:107], v[40:41], v[142:143], v[106:107] op_sel_hi:[0,1,1]
	v_cvt_f32_f16_sdwa v137, v207 dst_sel:DWORD dst_unused:UNUSED_PAD src0_sel:WORD_1
	v_cvt_f32_f16_e32 v136, v207
	v_pk_fma_f32 v[106:107], v[44:45], v[174:175], v[106:107] op_sel_hi:[0,1,1]
	v_pk_fma_f32 v[106:107], v[48:49], v[178:179], v[106:107] op_sel_hi:[0,1,1]
	v_pk_fma_f32 v[206:207], v[52:53], v[180:181], v[106:107] op_sel_hi:[0,1,1]
	v_pk_fma_f32 v[106:107], v[56:57], v[188:189], v[206:207] op_sel_hi:[0,1,1]
	v_pk_fma_f32 v[206:207], v[156:157], v[136:137], v[98:99] op_sel_hi:[0,1,1]
	v_cvt_f32_f16_sdwa v99, v211 dst_sel:DWORD dst_unused:UNUSED_PAD src0_sel:WORD_1
	v_cvt_f32_f16_e32 v98, v211
	v_cvt_f32_f16_sdwa v211, v215 dst_sel:DWORD dst_unused:UNUSED_PAD src0_sel:WORD_1
	v_cvt_f32_f16_e32 v210, v215
; __device__ __forceinline__ void dsa_item(const KP& p, int b, int tile, char* smem) {
;     ...
; #pragma unroll
;         for (int i = 0; i < 8; ++i) {
;           const int pos = (g8 * 8 + i) * 8 + rs;
;           const f32x4 pa = *(const f32x4*)&pbuf[pos * 8];
;           const f32x4 pb = *(const f32x4*)&pbuf[pos * 8 + 4];
;           float vf[8];
; #pragma unroll
;           for (int e = 0; e < 8; ++e) vf[e] = (float)vv[i][e];
; #pragma unroll
;           for (int e = 0; e < 8; ++e) {
;             acc[0][e] += pa[0] * vf[e]; acc[1][e] += pa[1] * vf[e]; acc[2][e] += pa[2] * vf[e]; acc[3][e] += pa[3] * vf[e];
;             acc[4][e] += pb[0] * vf[e]; acc[5][e] += pb[1] * vf[e]; acc[6][e] += pb[2] * vf[e]; acc[7][e] += pb[3] * vf[e];
;           }
	v_cvt_f32_f16_sdwa v215, v219 dst_sel:DWORD dst_unused:UNUSED_PAD src0_sel:WORD_1
	v_cvt_f32_f16_e32 v214, v219
	v_cvt_f32_f16_sdwa v219, v227 dst_sel:DWORD dst_unused:UNUSED_PAD src0_sel:WORD_1
	v_cvt_f32_f16_e32 v218, v227
	v_pk_fma_f32 v[206:207], v[208:209], v[98:99], v[206:207] op_sel_hi:[0,1,1]
	v_pk_fma_f32 v[114:115], v[208:209], v[142:143], v[114:115] op_sel_hi:[0,1,1]
	v_pk_fma_f32 v[206:207], v[212:213], v[210:211], v[206:207] op_sel_hi:[0,1,1]
	v_pk_fma_f32 v[114:115], v[212:213], v[174:175], v[114:115] op_sel_hi:[0,1,1]
	v_pk_fma_f32 v[206:207], v[224:225], v[214:215], v[206:207] op_sel_hi:[0,1,1]
	v_pk_fma_f32 v[114:115], v[224:225], v[178:179], v[114:115] op_sel_hi:[0,1,1]
	v_pk_fma_f32 v[224:225], v[158:159], v[218:219], v[206:207] op_sel_hi:[0,1,1]
	v_pk_fma_f32 v[206:207], v[58:59], v[136:137], v[108:109] op_sel_hi:[0,1,1]
	v_cvt_f32_f16_sdwa v227, v231 dst_sel:DWORD dst_unused:UNUSED_PAD src0_sel:WORD_1
	v_cvt_f32_f16_e32 v226, v231
	v_pk_fma_f32 v[206:207], v[62:63], v[98:99], v[206:207] op_sel_hi:[0,1,1]
	v_pk_fma_f32 v[206:207], v[66:67], v[210:211], v[206:207] op_sel_hi:[0,1,1]
	v_pk_fma_f32 v[206:207], v[70:71], v[214:215], v[206:207] op_sel_hi:[0,1,1]
	v_pk_fma_f32 v[206:207], v[74:75], v[218:219], v[206:207] op_sel_hi:[0,1,1]
	v_pk_fma_f32 v[230:231], v[78:79], v[226:227], v[206:207] op_sel_hi:[0,1,1]
	v_pk_fma_f32 v[206:207], v[58:59], v[136:137], v[100:101] op_sel:[1,0,0]
	v_pk_fma_f32 v[124:125], v[62:63], v[142:143], v[124:125] op_sel_hi:[0,1,1]
	v_pk_fma_f32 v[206:207], v[62:63], v[98:99], v[206:207] op_sel:[1,0,0]
	v_pk_fma_f32 v[116:117], v[62:63], v[142:143], v[116:117] op_sel:[1,0,0]
	v_pk_fma_f32 v[206:207], v[66:67], v[210:211], v[206:207] op_sel:[1,0,0]
	v_pk_fma_f32 v[110:111], v[64:65], v[142:143], v[110:111] op_sel_hi:[0,1,1]
	v_pk_fma_f32 v[206:207], v[70:71], v[214:215], v[206:207] op_sel:[1,0,0]
	v_pk_fma_f32 v[118:119], v[38:39], v[142:143], v[118:119] op_sel_hi:[0,1,1]
	v_pk_fma_f32 v[206:207], v[74:75], v[218:219], v[206:207] op_sel:[1,0,0]
	v_pk_fma_f32 v[112:113], v[38:39], v[142:143], v[112:113] op_sel:[1,0,0]
	v_pk_fma_f32 v[58:59], v[78:79], v[226:227], v[206:207] op_sel:[1,0,0]
	v_pk_fma_f32 v[206:207], v[60:61], v[136:137], v[94:95] op_sel_hi:[0,1,1]
	v_pk_fma_f32 v[206:207], v[64:65], v[98:99], v[206:207] op_sel_hi:[0,1,1]
	v_pk_fma_f32 v[206:207], v[68:69], v[210:211], v[206:207] op_sel_hi:[0,1,1]
	v_pk_fma_f32 v[206:207], v[72:73], v[214:215], v[206:207] op_sel_hi:[0,1,1]
	v_pk_fma_f32 v[206:207], v[76:77], v[218:219], v[206:207] op_sel_hi:[0,1,1]
	v_pk_fma_f32 v[60:61], v[80:81], v[226:227], v[206:207] op_sel_hi:[0,1,1]
	v_pk_fma_f32 v[206:207], v[154:155], v[136:137], v[90:91] op_sel_hi:[0,1,1]
	v_pk_fma_f32 v[206:207], v[194:195], v[98:99], v[206:207] op_sel_hi:[0,1,1]
	v_pk_fma_f32 v[206:207], v[196:197], v[210:211], v[206:207] op_sel_hi:[0,1,1]
	v_pk_fma_f32 v[206:207], v[198:199], v[214:215], v[206:207] op_sel_hi:[0,1,1]
	v_pk_fma_f32 v[206:207], v[200:201], v[218:219], v[206:207] op_sel_hi:[0,1,1]
	v_pk_fma_f32 v[62:63], v[202:203], v[226:227], v[206:207] op_sel_hi:[0,1,1]
	v_pk_fma_f32 v[206:207], v[34:35], v[136:137], v[102:103] op_sel_hi:[0,1,1]
	v_pk_fma_f32 v[206:207], v[38:39], v[98:99], v[206:207] op_sel_hi:[0,1,1]
	v_pk_fma_f32 v[206:207], v[42:43], v[210:211], v[206:207] op_sel_hi:[0,1,1]
	v_pk_fma_f32 v[206:207], v[46:47], v[214:215], v[206:207] op_sel_hi:[0,1,1]
	v_pk_fma_f32 v[206:207], v[50:51], v[218:219], v[206:207] op_sel_hi:[0,1,1]
	v_pk_fma_f32 v[64:65], v[54:55], v[226:227], v[206:207] op_sel_hi:[0,1,1]
	v_pk_fma_f32 v[206:207], v[34:35], v[136:137], v[96:97] op_sel:[1,0,0]
	v_pk_fma_f32 v[118:119], v[42:43], v[174:175], v[118:119] op_sel_hi:[0,1,1]
	v_pk_fma_f32 v[206:207], v[38:39], v[98:99], v[206:207] op_sel:[1,0,0]
	v_pk_fma_f32 v[112:113], v[42:43], v[174:175], v[112:113] op_sel:[1,0,0]
	v_pk_fma_f32 v[206:207], v[42:43], v[210:211], v[206:207] op_sel:[1,0,0]
	v_pk_fma_f32 v[118:119], v[46:47], v[178:179], v[118:119] op_sel_hi:[0,1,1]
	v_pk_fma_f32 v[206:207], v[46:47], v[214:215], v[206:207] op_sel:[1,0,0]
	v_pk_fma_f32 v[112:113], v[46:47], v[178:179], v[112:113] op_sel:[1,0,0]
	v_pk_fma_f32 v[206:207], v[50:51], v[218:219], v[206:207] op_sel:[1,0,0]
	s_waitcnt vmcnt(9)
	v_cvt_f32_f16_sdwa v43, v221 dst_sel:DWORD dst_unused:UNUSED_PAD src0_sel:WORD_1
	v_pk_fma_f32 v[34:35], v[54:55], v[226:227], v[206:207] op_sel:[1,0,0]
	v_pk_fma_f32 v[206:207], v[36:37], v[136:137], v[92:93] op_sel_hi:[0,1,1]
	v_pk_fma_f32 v[206:207], v[40:41], v[98:99], v[206:207] op_sel_hi:[0,1,1]
	v_pk_fma_f32 v[206:207], v[44:45], v[210:211], v[206:207] op_sel_hi:[0,1,1]
	v_pk_fma_f32 v[206:207], v[48:49], v[214:215], v[206:207] op_sel_hi:[0,1,1]
	v_pk_fma_f32 v[206:207], v[52:53], v[218:219], v[206:207] op_sel_hi:[0,1,1]
	v_pk_fma_f32 v[214:215], v[56:57], v[226:227], v[206:207] op_sel_hi:[0,1,1]
	ds_read_b128 v[206:209], v172 offset:1536
	ds_read_b128 v[210:213], v172 offset:1552
	v_pk_fma_f32 v[226:227], v[176:177], v[226:227], v[224:225] op_sel_hi:[0,1,1]
	v_cvt_f32_f16_sdwa v37, v220 dst_sel:DWORD dst_unused:UNUSED_PAD src0_sel:WORD_1
	v_cvt_f32_f16_e32 v36, v220
	v_cvt_f32_f16_e32 v42, v221
	v_cvt_f32_f16_sdwa v45, v222 dst_sel:DWORD dst_unused:UNUSED_PAD src0_sel:WORD_1
	v_cvt_f32_f16_e32 v44, v222
	v_cvt_f32_f16_sdwa v47, v223 dst_sel:DWORD dst_unused:UNUSED_PAD src0_sel:WORD_1
	v_cvt_f32_f16_e32 v46, v223
	ds_read_b128 v[218:221], v172 offset:1792
	ds_read_b128 v[222:225], v172 offset:1808
	s_waitcnt vmcnt(8)
; __device__ __forceinline__ void dsa_item(const KP& p, int b, int tile, char* smem) {
;     ...
; #pragma unroll
;         for (int i = 0; i < 8; ++i) {
;           const int pos = (g8 * 8 + i) * 8 + rs;
;           const f32x4 pa = *(const f32x4*)&pbuf[pos * 8];
;           const f32x4 pb = *(const f32x4*)&pbuf[pos * 8 + 4];
;           float vf[8];
; #pragma unroll
;           for (int e = 0; e < 8; ++e) vf[e] = (float)vv[i][e];
; #pragma unroll
;           for (int e = 0; e < 8; ++e) {
;             acc[0][e] += pa[0] * vf[e]; acc[1][e] += pa[1] * vf[e]; acc[2][e] += pa[2] * vf[e]; acc[3][e] += pa[3] * vf[e];
;             acc[4][e] += pb[0] * vf[e]; acc[5][e] += pb[1] * vf[e]; acc[6][e] += pb[2] * vf[e]; acc[7][e] += pb[3] * vf[e];
;           }
	v_cvt_f32_f16_e32 v48, v232
	v_cvt_f32_f16_sdwa v49, v232 dst_sel:DWORD dst_unused:UNUSED_PAD src0_sel:WORD_1
	v_pk_fma_f32 v[124:125], v[66:67], v[174:175], v[124:125] op_sel_hi:[0,1,1]
	v_pk_fma_f32 v[116:117], v[66:67], v[174:175], v[116:117] op_sel:[1,0,0]
	v_pk_fma_f32 v[110:111], v[68:69], v[174:175], v[110:111] op_sel_hi:[0,1,1]
	v_pk_fma_f32 v[104:105], v[194:195], v[142:143], v[104:105] op_sel_hi:[0,1,1]
	v_cvt_f32_f16_e32 v232, v233
	v_cvt_f32_f16_sdwa v233, v233 dst_sel:DWORD dst_unused:UNUSED_PAD src0_sel:WORD_1
	v_pk_fma_f32 v[216:217], v[74:75], v[190:191], v[216:217] op_sel_hi:[0,1,1]
	v_pk_fma_f32 v[228:229], v[74:75], v[190:191], v[228:229] op_sel:[1,0,0]
	v_pk_fma_f32 v[128:129], v[76:77], v[190:191], v[128:129] op_sel_hi:[0,1,1]
	v_pk_fma_f32 v[134:135], v[50:51], v[190:191], v[134:135] op_sel_hi:[0,1,1]
	v_pk_fma_f32 v[130:131], v[50:51], v[190:191], v[130:131] op_sel:[1,0,0]
	v_pk_fma_f32 v[124:125], v[70:71], v[178:179], v[124:125] op_sel_hi:[0,1,1]
	v_pk_fma_f32 v[116:117], v[70:71], v[178:179], v[116:117] op_sel:[1,0,0]
	v_pk_fma_f32 v[110:111], v[72:73], v[178:179], v[110:111] op_sel_hi:[0,1,1]
	v_pk_fma_f32 v[104:105], v[196:197], v[174:175], v[104:105] op_sel_hi:[0,1,1]
	v_pk_fma_f32 v[118:119], v[50:51], v[180:181], v[118:119] op_sel_hi:[0,1,1]
	v_pk_fma_f32 v[112:113], v[50:51], v[180:181], v[112:113] op_sel:[1,0,0]
	v_cvt_f32_f16_e32 v50, v234
	v_cvt_f32_f16_sdwa v51, v234 dst_sel:DWORD dst_unused:UNUSED_PAD src0_sel:WORD_1
	v_pk_fma_f32 v[216:217], v[78:79], v[192:193], v[216:217] op_sel_hi:[0,1,1]
	v_pk_fma_f32 v[228:229], v[78:79], v[192:193], v[228:229] op_sel:[1,0,0]
	v_pk_fma_f32 v[128:129], v[80:81], v[192:193], v[128:129] op_sel_hi:[0,1,1]
	v_pk_fma_f32 v[120:121], v[200:201], v[190:191], v[120:121] op_sel_hi:[0,1,1]
	v_pk_fma_f32 v[122:123], v[52:53], v[190:191], v[122:123] op_sel_hi:[0,1,1]
	v_pk_fma_f32 v[124:125], v[74:75], v[180:181], v[124:125] op_sel_hi:[0,1,1]
	v_pk_fma_f32 v[116:117], v[74:75], v[180:181], v[116:117] op_sel:[1,0,0]
	v_pk_fma_f32 v[110:111], v[76:77], v[180:181], v[110:111] op_sel_hi:[0,1,1]
	v_pk_fma_f32 v[104:105], v[198:199], v[178:179], v[104:105] op_sel_hi:[0,1,1]
	s_waitcnt lgkmcnt(3)
	v_mov_b32_e32 v38, v209
	s_waitcnt lgkmcnt(2)
	v_mov_b32_e32 v40, v213
	v_cvt_f32_f16_e32 v234, v235
	v_cvt_f32_f16_sdwa v235, v235 dst_sel:DWORD dst_unused:UNUSED_PAD src0_sel:WORD_1
	v_pk_fma_f32 v[204:205], v[212:213], v[36:37], v[204:205] op_sel_hi:[0,1,1]
	v_pk_fma_f32 v[120:121], v[202:203], v[192:193], v[120:121] op_sel_hi:[0,1,1]
	v_pk_fma_f32 v[134:135], v[54:55], v[192:193], v[134:135] op_sel_hi:[0,1,1]
	v_pk_fma_f32 v[130:131], v[54:55], v[192:193], v[130:131] op_sel:[1,0,0]
	v_pk_fma_f32 v[122:123], v[56:57], v[192:193], v[122:123] op_sel_hi:[0,1,1]
	v_pk_fma_f32 v[132:133], v[176:177], v[192:193], v[132:133] op_sel_hi:[0,1,1]
	v_pk_fma_f32 v[114:115], v[158:159], v[180:181], v[114:115] op_sel_hi:[0,1,1]
	v_pk_fma_f32 v[124:125], v[78:79], v[188:189], v[124:125] op_sel_hi:[0,1,1]
	v_pk_fma_f32 v[116:117], v[78:79], v[188:189], v[116:117] op_sel:[1,0,0]
	v_pk_fma_f32 v[110:111], v[80:81], v[188:189], v[110:111] op_sel_hi:[0,1,1]
	v_pk_fma_f32 v[104:105], v[200:201], v[180:181], v[104:105] op_sel_hi:[0,1,1]
	v_pk_fma_f32 v[118:119], v[54:55], v[188:189], v[118:119] op_sel_hi:[0,1,1]
	v_pk_fma_f32 v[112:113], v[54:55], v[188:189], v[112:113] op_sel:[1,0,0]
	v_pk_fma_f32 v[52:53], v[206:207], v[36:37], v[148:149] op_sel_hi:[0,1,1]
	v_pk_fma_f32 v[54:55], v[206:207], v[36:37], v[152:153] op_sel:[1,0,0]
	v_pk_fma_f32 v[56:57], v[208:209], v[36:37], v[146:147] op_sel_hi:[0,1,1]
	v_pk_fma_f32 v[66:67], v[38:39], v[36:37], v[140:141] op_sel_hi:[0,1,1]
	v_pk_fma_f32 v[68:69], v[210:211], v[36:37], v[150:151] op_sel_hi:[0,1,1]
	v_pk_fma_f32 v[70:71], v[210:211], v[36:37], v[144:145] op_sel:[1,0,0]
	v_pk_fma_f32 v[36:37], v[40:41], v[36:37], v[138:139] op_sel_hi:[0,1,1]
	s_waitcnt lgkmcnt(1)
	v_mov_b32_e32 v72, v221
	s_waitcnt lgkmcnt(0)
	v_mov_b32_e32 v74, v225
	v_pk_fma_f32 v[138:139], v[224:225], v[48:49], v[204:205] op_sel_hi:[0,1,1]
	v_pk_fma_f32 v[204:205], v[206:207], v[42:43], v[216:217] op_sel_hi:[0,1,1]
	v_pk_fma_f32 v[216:217], v[206:207], v[42:43], v[228:229] op_sel:[1,0,0]
	v_pk_fma_f32 v[228:229], v[208:209], v[42:43], v[128:129] op_sel_hi:[0,1,1]
	v_pk_fma_f32 v[104:105], v[202:203], v[188:189], v[104:105] op_sel_hi:[0,1,1]
	v_pk_fma_f32 v[114:115], v[176:177], v[188:189], v[114:115] op_sel_hi:[0,1,1]
	v_pk_fma_f32 v[154:155], v[218:219], v[48:49], v[52:53] op_sel_hi:[0,1,1]
	v_pk_fma_f32 v[152:153], v[218:219], v[48:49], v[54:55] op_sel:[1,0,0]
	v_pk_fma_f32 v[146:147], v[220:221], v[48:49], v[56:57] op_sel_hi:[0,1,1]
	v_pk_fma_f32 v[140:141], v[72:73], v[48:49], v[66:67] op_sel_hi:[0,1,1]
	v_pk_fma_f32 v[150:151], v[222:223], v[48:49], v[68:69] op_sel_hi:[0,1,1]
	v_pk_fma_f32 v[144:145], v[222:223], v[48:49], v[70:71] op_sel:[1,0,0]
	v_pk_fma_f32 v[148:149], v[74:75], v[48:49], v[36:37] op_sel_hi:[0,1,1]
	v_pk_fma_f32 v[36:37], v[38:39], v[42:43], v[120:121] op_sel_hi:[0,1,1]
	v_pk_fma_f32 v[48:49], v[210:211], v[42:43], v[134:135] op_sel_hi:[0,1,1]
	v_pk_fma_f32 v[52:53], v[210:211], v[42:43], v[130:131] op_sel:[1,0,0]
	v_pk_fma_f32 v[54:55], v[212:213], v[42:43], v[122:123] op_sel_hi:[0,1,1]
	v_pk_fma_f32 v[42:43], v[40:41], v[42:43], v[132:133] op_sel_hi:[0,1,1]
	v_pk_fma_f32 v[142:143], v[218:219], v[232:233], v[204:205] op_sel_hi:[0,1,1]
	v_pk_fma_f32 v[134:135], v[218:219], v[232:233], v[216:217] op_sel:[1,0,0]
	v_pk_fma_f32 v[128:129], v[220:221], v[232:233], v[228:229] op_sel_hi:[0,1,1]
	v_pk_fma_f32 v[204:205], v[206:207], v[44:45], v[124:125] op_sel_hi:[0,1,1]
; __device__ __forceinline__ void dsa_item(const KP& p, int b, int tile, char* smem) {
;     ...
;       for (int g8 = 0; g8 < 4; ++g8) {
;         h8 vv[8];
; #pragma unroll
;         for (int i = 0; i < 8; ++i) {
;           const int pos = (g8 * 8 + i) * 8 + rs;
;           const int s = (pos < nsel) ? (int)sel[tk * 256 + pos] : 0;
;           vv[i] = *(const h8*)(ub + (size_t)s * NU + C_BV + dc * 8);
;         }
; #pragma unroll
;         for (int i = 0; i < 8; ++i) {
;           const int pos = (g8 * 8 + i) * 8 + rs;
;           const f32x4 pa = *(const f32x4*)&pbuf[pos * 8];
;           const f32x4 pb = *(const f32x4*)&pbuf[pos * 8 + 4];
;           float vf[8];
; #pragma unroll
;           for (int e = 0; e < 8; ++e) vf[e] = (float)vv[i][e];
; #pragma unroll
;           for (int e = 0; e < 8; ++e) {
;             acc[0][e] += pa[0] * vf[e]; acc[1][e] += pa[1] * vf[e]; acc[2][e] += pa[2] * vf[e]; acc[3][e] += pa[3] * vf[e];
;             acc[4][e] += pb[0] * vf[e]; acc[5][e] += pb[1] * vf[e]; acc[6][e] += pb[2] * vf[e]; acc[7][e] += pb[3] * vf[e];
;           }
	v_pk_fma_f32 v[216:217], v[206:207], v[44:45], v[116:117] op_sel:[1,0,0]
	v_pk_fma_f32 v[228:229], v[208:209], v[44:45], v[110:111] op_sel_hi:[0,1,1]
	v_pk_fma_f32 v[120:121], v[72:73], v[232:233], v[36:37] op_sel_hi:[0,1,1]
	v_pk_fma_f32 v[136:137], v[222:223], v[232:233], v[48:49] op_sel_hi:[0,1,1]
	v_pk_fma_f32 v[130:131], v[222:223], v[232:233], v[52:53] op_sel:[1,0,0]
	v_pk_fma_f32 v[122:123], v[224:225], v[232:233], v[54:55] op_sel_hi:[0,1,1]
	v_pk_fma_f32 v[132:133], v[74:75], v[232:233], v[42:43] op_sel_hi:[0,1,1]
	v_pk_fma_f32 v[232:233], v[38:39], v[44:45], v[104:105] op_sel_hi:[0,1,1]
	v_pk_fma_f32 v[36:37], v[210:211], v[44:45], v[118:119] op_sel_hi:[0,1,1]
	v_pk_fma_f32 v[42:43], v[210:211], v[44:45], v[112:113] op_sel:[1,0,0]
	v_pk_fma_f32 v[48:49], v[212:213], v[44:45], v[106:107] op_sel_hi:[0,1,1]
	v_pk_fma_f32 v[44:45], v[40:41], v[44:45], v[114:115] op_sel_hi:[0,1,1]
	v_pk_fma_f32 v[124:125], v[218:219], v[50:51], v[204:205] op_sel_hi:[0,1,1]
	v_pk_fma_f32 v[116:117], v[218:219], v[50:51], v[216:217] op_sel:[1,0,0]
	v_pk_fma_f32 v[110:111], v[220:221], v[50:51], v[228:229] op_sel_hi:[0,1,1]
	v_pk_fma_f32 v[204:205], v[206:207], v[46:47], v[230:231] op_sel_hi:[0,1,1]
	v_pk_fma_f32 v[206:207], v[206:207], v[46:47], v[58:59] op_sel:[1,0,0]
	v_pk_fma_f32 v[208:209], v[208:209], v[46:47], v[60:61] op_sel_hi:[0,1,1]
	v_pk_fma_f32 v[216:217], v[38:39], v[46:47], v[62:63] op_sel_hi:[0,1,1]
	v_pk_fma_f32 v[228:229], v[210:211], v[46:47], v[64:65] op_sel_hi:[0,1,1]
	v_pk_fma_f32 v[210:211], v[210:211], v[46:47], v[34:35] op_sel:[1,0,0]
	v_pk_fma_f32 v[212:213], v[212:213], v[46:47], v[214:215] op_sel_hi:[0,1,1]
	v_pk_fma_f32 v[214:215], v[40:41], v[46:47], v[226:227] op_sel_hi:[0,1,1]
	v_pk_fma_f32 v[104:105], v[72:73], v[50:51], v[232:233] op_sel_hi:[0,1,1]
	v_pk_fma_f32 v[118:119], v[222:223], v[50:51], v[36:37] op_sel_hi:[0,1,1]
	v_pk_fma_f32 v[112:113], v[222:223], v[50:51], v[42:43] op_sel:[1,0,0]
	v_pk_fma_f32 v[106:107], v[224:225], v[50:51], v[48:49] op_sel_hi:[0,1,1]
	v_pk_fma_f32 v[114:115], v[74:75], v[50:51], v[44:45] op_sel_hi:[0,1,1]
	v_pk_fma_f32 v[108:109], v[218:219], v[234:235], v[204:205] op_sel_hi:[0,1,1]
	v_pk_fma_f32 v[100:101], v[218:219], v[234:235], v[206:207] op_sel:[1,0,0]
	v_pk_fma_f32 v[94:95], v[220:221], v[234:235], v[208:209] op_sel_hi:[0,1,1]
	v_pk_fma_f32 v[90:91], v[72:73], v[234:235], v[216:217] op_sel_hi:[0,1,1]
	v_pk_fma_f32 v[102:103], v[222:223], v[234:235], v[228:229] op_sel_hi:[0,1,1]
	v_pk_fma_f32 v[96:97], v[222:223], v[234:235], v[210:211] op_sel:[1,0,0]
	v_pk_fma_f32 v[92:93], v[224:225], v[234:235], v[212:213] op_sel_hi:[0,1,1]
	v_pk_fma_f32 v[98:99], v[74:75], v[234:235], v[214:215] op_sel_hi:[0,1,1]
	v_add_u32_e32 v172, 0x800, v172
	v_lshlrev_b32_e32 v35, 8, v159
	v_lshl_add_u32 v35, v165, 2, v35
	v_add_u32_e32 v35, 0xcc00, v35
	ds_read_b32 v204, v35 offset:768
	ds_read_b32 v208, v35 offset:800
	ds_read_b32 v212, v35 offset:832
	ds_read_b32 v216, v35 offset:864
	ds_read_b32 v224, v35 offset:896
	ds_read_b32 v228, v35 offset:928
	ds_read_b32 v220, v35 offset:960
	ds_read_b32 v232, v35 offset:992
	s_waitcnt lgkmcnt(4)
	v_add_u32_e32 v204, v204, v0
	global_load_dwordx4 v[204:207], v204, s[2:3]
	v_add_u32_e32 v208, v208, v0
	global_load_dwordx4 v[208:211], v208, s[2:3]
	v_add_u32_e32 v212, v212, v0
	global_load_dwordx4 v[212:215], v212, s[2:3]
	v_add_u32_e32 v216, v216, v0
	global_load_dwordx4 v[216:219], v216, s[2:3]
	s_waitcnt lgkmcnt(0)
	v_add_u32_e32 v224, v224, v0
	global_load_dwordx4 v[224:227], v224, s[2:3]
	v_add_u32_e32 v228, v228, v0
	global_load_dwordx4 v[228:231], v228, s[2:3]
	v_add_u32_e32 v220, v220, v0
	global_load_dwordx4 v[220:223], v220, s[2:3]
	v_add_u32_e32 v232, v232, v0
	global_load_dwordx4 v[232:235], v232, s[2:3]
	s_waitcnt vmcnt(15)
	v_cvt_f32_f16_sdwa v175, v2 dst_sel:DWORD dst_unused:UNUSED_PAD src0_sel:WORD_1
	v_cvt_f32_f16_e32 v174, v2
	s_waitcnt vmcnt(14)
	v_cvt_f32_f16_sdwa v177, v6 dst_sel:DWORD dst_unused:UNUSED_PAD src0_sel:WORD_1
	v_cvt_f32_f16_e32 v176, v6
	ds_read_b128 v[58:61], v172
	ds_read_b128 v[34:37], v172 offset:16
	ds_read_b128 v[62:65], v172 offset:256
	ds_read_b128 v[38:41], v172 offset:272
	ds_read_b128 v[66:69], v172 offset:512
	ds_read_b128 v[42:45], v172 offset:528
	ds_read_b128 v[70:73], v172 offset:768
	ds_read_b128 v[46:49], v172 offset:784
	ds_read_b128 v[74:77], v172 offset:1024
	ds_read_b128 v[50:53], v172 offset:1040
	s_waitcnt vmcnt(13)
	v_cvt_f32_f16_sdwa v179, v10 dst_sel:DWORD dst_unused:UNUSED_PAD src0_sel:WORD_1
	v_cvt_f32_f16_e32 v178, v10
	s_waitcnt lgkmcnt(8)
	v_mov_b32_e32 v156, v37
	s_waitcnt vmcnt(12)
	v_cvt_f32_f16_sdwa v181, v14 dst_sel:DWORD dst_unused:UNUSED_PAD src0_sel:WORD_1
	v_cvt_f32_f16_e32 v180, v14
	v_pk_fma_f32 v[148:149], v[156:157], v[174:175], v[148:149] op_sel_hi:[0,1,1]
	s_waitcnt lgkmcnt(6)
	v_mov_b32_e32 v6, v41
	s_waitcnt vmcnt(11)
	v_cvt_f32_f16_sdwa v189, v22 dst_sel:DWORD dst_unused:UNUSED_PAD src0_sel:WORD_1
	v_cvt_f32_f16_e32 v188, v22
	v_pk_fma_f32 v[148:149], v[6:7], v[176:177], v[148:149] op_sel_hi:[0,1,1]
	s_waitcnt lgkmcnt(4)
	v_mov_b32_e32 v10, v45
	v_pk_fma_f32 v[148:149], v[10:11], v[178:179], v[148:149] op_sel_hi:[0,1,1]
	s_waitcnt lgkmcnt(2)
	v_mov_b32_e32 v22, v49
	v_pk_fma_f32 v[148:149], v[22:23], v[180:181], v[148:149] op_sel_hi:[0,1,1]
	s_waitcnt lgkmcnt(0)
; __device__ __forceinline__ void dsa_item(const KP& p, int b, int tile, char* smem) {
;     ...
; #pragma unroll
;         for (int i = 0; i < 8; ++i) {
;           const int pos = (g8 * 8 + i) * 8 + rs;
;           const f32x4 pa = *(const f32x4*)&pbuf[pos * 8];
;           const f32x4 pb = *(const f32x4*)&pbuf[pos * 8 + 4];
;           float vf[8];
; #pragma unroll
;           for (int e = 0; e < 8; ++e) vf[e] = (float)vv[i][e];
; #pragma unroll
;           for (int e = 0; e < 8; ++e) {
;             acc[0][e] += pa[0] * vf[e]; acc[1][e] += pa[1] * vf[e]; acc[2][e] += pa[2] * vf[e]; acc[3][e] += pa[3] * vf[e];
;             acc[4][e] += pb[0] * vf[e]; acc[5][e] += pb[1] * vf[e]; acc[6][e] += pb[2] * vf[e]; acc[7][e] += pb[3] * vf[e];
;           }
	v_mov_b32_e32 v158, v53
	ds_read_b128 v[78:81], v172 offset:1280
	ds_read_b128 v[54:57], v172 offset:1296
	v_pk_fma_f32 v[190:191], v[158:159], v[188:189], v[148:149] op_sel_hi:[0,1,1]
	v_pk_fma_f32 v[148:149], v[58:59], v[174:175], v[154:155] op_sel_hi:[0,1,1]
	v_mov_b32_e32 v154, v61
	v_pk_fma_f32 v[152:153], v[58:59], v[174:175], v[152:153] op_sel:[1,0,0]
	v_pk_fma_f32 v[146:147], v[60:61], v[174:175], v[146:147] op_sel_hi:[0,1,1]
	v_pk_fma_f32 v[140:141], v[154:155], v[174:175], v[140:141] op_sel_hi:[0,1,1]
	v_mov_b32_e32 v194, v65
	v_pk_fma_f32 v[150:151], v[34:35], v[174:175], v[150:151] op_sel_hi:[0,1,1]
	v_pk_fma_f32 v[144:145], v[34:35], v[174:175], v[144:145] op_sel:[1,0,0]
	v_pk_fma_f32 v[138:139], v[36:37], v[174:175], v[138:139] op_sel_hi:[0,1,1]
	s_waitcnt vmcnt(10)
	v_cvt_f32_f16_sdwa v193, v26 dst_sel:DWORD dst_unused:UNUSED_PAD src0_sel:WORD_1
	v_cvt_f32_f16_e32 v192, v26
	v_pk_fma_f32 v[148:149], v[62:63], v[176:177], v[148:149] op_sel_hi:[0,1,1]
	v_pk_fma_f32 v[152:153], v[62:63], v[176:177], v[152:153] op_sel:[1,0,0]
	v_pk_fma_f32 v[146:147], v[64:65], v[176:177], v[146:147] op_sel_hi:[0,1,1]
	v_pk_fma_f32 v[140:141], v[194:195], v[176:177], v[140:141] op_sel_hi:[0,1,1]
	v_mov_b32_e32 v196, v69
	v_pk_fma_f32 v[150:151], v[38:39], v[176:177], v[150:151] op_sel_hi:[0,1,1]
	v_pk_fma_f32 v[144:145], v[38:39], v[176:177], v[144:145] op_sel:[1,0,0]
	v_pk_fma_f32 v[138:139], v[40:41], v[176:177], v[138:139] op_sel_hi:[0,1,1]
	v_cvt_f32_f16_sdwa v175, v3 dst_sel:DWORD dst_unused:UNUSED_PAD src0_sel:WORD_1
	v_cvt_f32_f16_e32 v174, v3
	v_pk_fma_f32 v[148:149], v[66:67], v[178:179], v[148:149] op_sel_hi:[0,1,1]
	v_pk_fma_f32 v[152:153], v[66:67], v[178:179], v[152:153] op_sel:[1,0,0]
	v_pk_fma_f32 v[146:147], v[68:69], v[178:179], v[146:147] op_sel_hi:[0,1,1]
	v_pk_fma_f32 v[140:141], v[196:197], v[178:179], v[140:141] op_sel_hi:[0,1,1]
	v_mov_b32_e32 v198, v73
	v_pk_fma_f32 v[150:151], v[42:43], v[178:179], v[150:151] op_sel_hi:[0,1,1]
	v_pk_fma_f32 v[144:145], v[42:43], v[178:179], v[144:145] op_sel:[1,0,0]
	v_pk_fma_f32 v[138:139], v[44:45], v[178:179], v[138:139] op_sel_hi:[0,1,1]
	v_cvt_f32_f16_sdwa v179, v7 dst_sel:DWORD dst_unused:UNUSED_PAD src0_sel:WORD_1
	v_cvt_f32_f16_e32 v178, v7
	v_pk_fma_f32 v[148:149], v[70:71], v[180:181], v[148:149] op_sel_hi:[0,1,1]
	v_pk_fma_f32 v[152:153], v[70:71], v[180:181], v[152:153] op_sel:[1,0,0]
	v_pk_fma_f32 v[146:147], v[72:73], v[180:181], v[146:147] op_sel_hi:[0,1,1]
	v_pk_fma_f32 v[140:141], v[198:199], v[180:181], v[140:141] op_sel_hi:[0,1,1]
	v_mov_b32_e32 v200, v77
	v_pk_fma_f32 v[150:151], v[46:47], v[180:181], v[150:151] op_sel_hi:[0,1,1]
	v_pk_fma_f32 v[144:145], v[46:47], v[180:181], v[144:145] op_sel:[1,0,0]
	v_pk_fma_f32 v[138:139], v[48:49], v[180:181], v[138:139] op_sel_hi:[0,1,1]
	v_cvt_f32_f16_sdwa v181, v11 dst_sel:DWORD dst_unused:UNUSED_PAD src0_sel:WORD_1
	v_cvt_f32_f16_e32 v180, v11
	v_pk_fma_f32 v[148:149], v[74:75], v[188:189], v[148:149] op_sel_hi:[0,1,1]
	v_pk_fma_f32 v[152:153], v[74:75], v[188:189], v[152:153] op_sel:[1,0,0]
	v_pk_fma_f32 v[146:147], v[76:77], v[188:189], v[146:147] op_sel_hi:[0,1,1]
	v_pk_fma_f32 v[140:141], v[200:201], v[188:189], v[140:141] op_sel_hi:[0,1,1]
	v_pk_fma_f32 v[150:151], v[50:51], v[188:189], v[150:151] op_sel_hi:[0,1,1]
	v_pk_fma_f32 v[144:145], v[50:51], v[188:189], v[144:145] op_sel:[1,0,0]
	v_pk_fma_f32 v[138:139], v[52:53], v[188:189], v[138:139] op_sel_hi:[0,1,1]
	s_waitcnt lgkmcnt(0)
	v_mov_b32_e32 v176, v57
	v_cvt_f32_f16_sdwa v189, v15 dst_sel:DWORD dst_unused:UNUSED_PAD src0_sel:WORD_1
	v_cvt_f32_f16_e32 v188, v15
	v_pk_fma_f32 v[2:3], v[56:57], v[192:193], v[138:139] op_sel_hi:[0,1,1]
	v_pk_fma_f32 v[138:139], v[176:177], v[192:193], v[190:191] op_sel_hi:[0,1,1]
	v_pk_fma_f32 v[132:133], v[156:157], v[174:175], v[132:133] op_sel_hi:[0,1,1]
	v_cvt_f32_f16_sdwa v191, v23 dst_sel:DWORD dst_unused:UNUSED_PAD src0_sel:WORD_1
	v_cvt_f32_f16_e32 v190, v23
	v_pk_fma_f32 v[14:15], v[6:7], v[178:179], v[132:133] op_sel_hi:[0,1,1]
	v_mov_b32_e32 v202, v81
	v_pk_fma_f32 v[14:15], v[10:11], v[180:181], v[14:15] op_sel_hi:[0,1,1]
	v_pk_fma_f32 v[148:149], v[78:79], v[192:193], v[148:149] op_sel_hi:[0,1,1]
	v_pk_fma_f32 v[152:153], v[78:79], v[192:193], v[152:153] op_sel:[1,0,0]
	v_pk_fma_f32 v[146:147], v[80:81], v[192:193], v[146:147] op_sel_hi:[0,1,1]
	v_pk_fma_f32 v[140:141], v[202:203], v[192:193], v[140:141] op_sel_hi:[0,1,1]
	v_pk_fma_f32 v[150:151], v[54:55], v[192:193], v[150:151] op_sel_hi:[0,1,1]
	v_pk_fma_f32 v[144:145], v[54:55], v[192:193], v[144:145] op_sel:[1,0,0]
	v_pk_fma_f32 v[14:15], v[22:23], v[188:189], v[14:15] op_sel_hi:[0,1,1]
	v_cvt_f32_f16_sdwa v193, v27 dst_sel:DWORD dst_unused:UNUSED_PAD src0_sel:WORD_1
	v_cvt_f32_f16_e32 v192, v27
	v_pk_fma_f32 v[26:27], v[58:59], v[174:175], v[134:135] op_sel:[1,0,0]
	v_pk_fma_f32 v[134:135], v[34:35], v[174:175], v[136:137] op_sel_hi:[0,1,1]
	v_cvt_f32_f16_sdwa v137, v4 dst_sel:DWORD dst_unused:UNUSED_PAD src0_sel:WORD_1
	v_cvt_f32_f16_e32 v136, v4
	v_pk_fma_f32 v[132:133], v[158:159], v[190:191], v[14:15] op_sel_hi:[0,1,1]
	v_pk_fma_f32 v[14:15], v[58:59], v[174:175], v[142:143] op_sel_hi:[0,1,1]
	v_cvt_f32_f16_sdwa v143, v8 dst_sel:DWORD dst_unused:UNUSED_PAD src0_sel:WORD_1
	v_cvt_f32_f16_e32 v142, v8
	v_pk_fma_f32 v[128:129], v[60:61], v[174:175], v[128:129] op_sel_hi:[0,1,1]
	v_pk_fma_f32 v[120:121], v[154:155], v[174:175], v[120:121] op_sel_hi:[0,1,1]
	v_pk_fma_f32 v[130:131], v[34:35], v[174:175], v[130:131] op_sel:[1,0,0]
	v_pk_fma_f32 v[122:123], v[36:37], v[174:175], v[122:123] op_sel_hi:[0,1,1]
	v_cvt_f32_f16_sdwa v175, v12 dst_sel:DWORD dst_unused:UNUSED_PAD src0_sel:WORD_1
; __device__ __forceinline__ void dsa_item(const KP& p, int b, int tile, char* smem) {
;     ...
; #pragma unroll
;         for (int i = 0; i < 8; ++i) {
;           const int pos = (g8 * 8 + i) * 8 + rs;
;           const f32x4 pa = *(const f32x4*)&pbuf[pos * 8];
;           const f32x4 pb = *(const f32x4*)&pbuf[pos * 8 + 4];
;           float vf[8];
; #pragma unroll
;           for (int e = 0; e < 8; ++e) vf[e] = (float)vv[i][e];
; #pragma unroll
;           for (int e = 0; e < 8; ++e) {
;             acc[0][e] += pa[0] * vf[e]; acc[1][e] += pa[1] * vf[e]; acc[2][e] += pa[2] * vf[e]; acc[3][e] += pa[3] * vf[e];
;             acc[4][e] += pb[0] * vf[e]; acc[5][e] += pb[1] * vf[e]; acc[6][e] += pb[2] * vf[e]; acc[7][e] += pb[3] * vf[e];
;           }
	v_cvt_f32_f16_e32 v174, v12
	v_pk_fma_f32 v[14:15], v[62:63], v[178:179], v[14:15] op_sel_hi:[0,1,1]
	v_pk_fma_f32 v[26:27], v[62:63], v[178:179], v[26:27] op_sel:[1,0,0]
	v_pk_fma_f32 v[128:129], v[64:65], v[178:179], v[128:129] op_sel_hi:[0,1,1]
	v_pk_fma_f32 v[120:121], v[194:195], v[178:179], v[120:121] op_sel_hi:[0,1,1]
	v_pk_fma_f32 v[134:135], v[38:39], v[178:179], v[134:135] op_sel_hi:[0,1,1]
	v_pk_fma_f32 v[130:131], v[38:39], v[178:179], v[130:131] op_sel:[1,0,0]
	v_pk_fma_f32 v[122:123], v[40:41], v[178:179], v[122:123] op_sel_hi:[0,1,1]
	v_cvt_f32_f16_sdwa v179, v16 dst_sel:DWORD dst_unused:UNUSED_PAD src0_sel:WORD_1
	v_cvt_f32_f16_e32 v178, v16
	v_pk_fma_f32 v[14:15], v[66:67], v[180:181], v[14:15] op_sel_hi:[0,1,1]
	v_pk_fma_f32 v[26:27], v[66:67], v[180:181], v[26:27] op_sel:[1,0,0]
	v_pk_fma_f32 v[128:129], v[68:69], v[180:181], v[128:129] op_sel_hi:[0,1,1]
	v_pk_fma_f32 v[120:121], v[196:197], v[180:181], v[120:121] op_sel_hi:[0,1,1]
	v_pk_fma_f32 v[134:135], v[42:43], v[180:181], v[134:135] op_sel_hi:[0,1,1]
	v_pk_fma_f32 v[130:131], v[42:43], v[180:181], v[130:131] op_sel:[1,0,0]
	v_pk_fma_f32 v[122:123], v[44:45], v[180:181], v[122:123] op_sel_hi:[0,1,1]
	v_cvt_f32_f16_sdwa v181, v24 dst_sel:DWORD dst_unused:UNUSED_PAD src0_sel:WORD_1
	v_cvt_f32_f16_e32 v180, v24
	v_pk_fma_f32 v[106:107], v[36:37], v[136:137], v[106:107] op_sel_hi:[0,1,1]
	v_pk_fma_f32 v[14:15], v[70:71], v[188:189], v[14:15] op_sel_hi:[0,1,1]
	v_pk_fma_f32 v[26:27], v[70:71], v[188:189], v[26:27] op_sel:[1,0,0]
	v_pk_fma_f32 v[128:129], v[72:73], v[188:189], v[128:129] op_sel_hi:[0,1,1]
	v_pk_fma_f32 v[120:121], v[198:199], v[188:189], v[120:121] op_sel_hi:[0,1,1]
	v_pk_fma_f32 v[134:135], v[46:47], v[188:189], v[134:135] op_sel_hi:[0,1,1]
	v_pk_fma_f32 v[130:131], v[46:47], v[188:189], v[130:131] op_sel:[1,0,0]
	v_pk_fma_f32 v[122:123], v[48:49], v[188:189], v[122:123] op_sel_hi:[0,1,1]
	v_pk_fma_f32 v[114:115], v[156:157], v[136:137], v[114:115] op_sel_hi:[0,1,1]
	v_cvt_f32_f16_sdwa v189, v28 dst_sel:DWORD dst_unused:UNUSED_PAD src0_sel:WORD_1
	v_cvt_f32_f16_e32 v188, v28
	v_pk_fma_f32 v[124:125], v[58:59], v[136:137], v[124:125] op_sel_hi:[0,1,1]
	v_pk_fma_f32 v[116:117], v[58:59], v[136:137], v[116:117] op_sel:[1,0,0]
	v_pk_fma_f32 v[110:111], v[60:61], v[136:137], v[110:111] op_sel_hi:[0,1,1]
	v_pk_fma_f32 v[104:105], v[154:155], v[136:137], v[104:105] op_sel_hi:[0,1,1]
	v_pk_fma_f32 v[118:119], v[34:35], v[136:137], v[118:119] op_sel_hi:[0,1,1]
	v_pk_fma_f32 v[112:113], v[34:35], v[136:137], v[112:113] op_sel:[1,0,0]
	v_pk_fma_f32 v[106:107], v[40:41], v[142:143], v[106:107] op_sel_hi:[0,1,1]
	v_cvt_f32_f16_sdwa v137, v5 dst_sel:DWORD dst_unused:UNUSED_PAD src0_sel:WORD_1
	v_cvt_f32_f16_e32 v136, v5
	v_pk_fma_f32 v[106:107], v[44:45], v[174:175], v[106:107] op_sel_hi:[0,1,1]
	v_pk_fma_f32 v[106:107], v[48:49], v[178:179], v[106:107] op_sel_hi:[0,1,1]
	v_pk_fma_f32 v[4:5], v[52:53], v[180:181], v[106:107] op_sel_hi:[0,1,1]
	v_pk_fma_f32 v[106:107], v[56:57], v[188:189], v[4:5] op_sel_hi:[0,1,1]
	v_pk_fma_f32 v[4:5], v[156:157], v[136:137], v[98:99] op_sel_hi:[0,1,1]
	v_cvt_f32_f16_sdwa v99, v9 dst_sel:DWORD dst_unused:UNUSED_PAD src0_sel:WORD_1
	v_cvt_f32_f16_e32 v98, v9
	v_cvt_f32_f16_sdwa v9, v13 dst_sel:DWORD dst_unused:UNUSED_PAD src0_sel:WORD_1
	v_cvt_f32_f16_e32 v8, v13
	v_cvt_f32_f16_sdwa v13, v17 dst_sel:DWORD dst_unused:UNUSED_PAD src0_sel:WORD_1
	v_cvt_f32_f16_e32 v12, v17
	v_cvt_f32_f16_sdwa v17, v25 dst_sel:DWORD dst_unused:UNUSED_PAD src0_sel:WORD_1
	v_cvt_f32_f16_e32 v16, v25
	v_pk_fma_f32 v[4:5], v[6:7], v[98:99], v[4:5] op_sel_hi:[0,1,1]
	v_pk_fma_f32 v[114:115], v[6:7], v[142:143], v[114:115] op_sel_hi:[0,1,1]
	v_pk_fma_f32 v[4:5], v[10:11], v[8:9], v[4:5] op_sel_hi:[0,1,1]
	v_pk_fma_f32 v[114:115], v[10:11], v[174:175], v[114:115] op_sel_hi:[0,1,1]
	v_pk_fma_f32 v[4:5], v[22:23], v[12:13], v[4:5] op_sel_hi:[0,1,1]
	v_pk_fma_f32 v[114:115], v[22:23], v[178:179], v[114:115] op_sel_hi:[0,1,1]
	v_pk_fma_f32 v[22:23], v[158:159], v[16:17], v[4:5] op_sel_hi:[0,1,1]
	v_pk_fma_f32 v[4:5], v[58:59], v[136:137], v[108:109] op_sel_hi:[0,1,1]
	v_cvt_f32_f16_sdwa v25, v29 dst_sel:DWORD dst_unused:UNUSED_PAD src0_sel:WORD_1
	v_cvt_f32_f16_e32 v24, v29
	v_pk_fma_f32 v[4:5], v[62:63], v[98:99], v[4:5] op_sel_hi:[0,1,1]
	v_pk_fma_f32 v[4:5], v[66:67], v[8:9], v[4:5] op_sel_hi:[0,1,1]
	v_pk_fma_f32 v[4:5], v[70:71], v[12:13], v[4:5] op_sel_hi:[0,1,1]
	v_pk_fma_f32 v[4:5], v[74:75], v[16:17], v[4:5] op_sel_hi:[0,1,1]
	v_pk_fma_f32 v[28:29], v[78:79], v[24:25], v[4:5] op_sel_hi:[0,1,1]
	v_pk_fma_f32 v[4:5], v[58:59], v[136:137], v[100:101] op_sel:[1,0,0]
	v_pk_fma_f32 v[124:125], v[62:63], v[142:143], v[124:125] op_sel_hi:[0,1,1]
	v_pk_fma_f32 v[4:5], v[62:63], v[98:99], v[4:5] op_sel:[1,0,0]
	v_pk_fma_f32 v[116:117], v[62:63], v[142:143], v[116:117] op_sel:[1,0,0]
	v_pk_fma_f32 v[4:5], v[66:67], v[8:9], v[4:5] op_sel:[1,0,0]
	v_pk_fma_f32 v[110:111], v[64:65], v[142:143], v[110:111] op_sel_hi:[0,1,1]
	v_pk_fma_f32 v[4:5], v[70:71], v[12:13], v[4:5] op_sel:[1,0,0]
	v_pk_fma_f32 v[118:119], v[38:39], v[142:143], v[118:119] op_sel_hi:[0,1,1]
	v_pk_fma_f32 v[4:5], v[74:75], v[16:17], v[4:5] op_sel:[1,0,0]
	v_pk_fma_f32 v[112:113], v[38:39], v[142:143], v[112:113] op_sel:[1,0,0]
	v_pk_fma_f32 v[58:59], v[78:79], v[24:25], v[4:5] op_sel:[1,0,0]
	v_pk_fma_f32 v[4:5], v[60:61], v[136:137], v[94:95] op_sel_hi:[0,1,1]
	v_pk_fma_f32 v[4:5], v[64:65], v[98:99], v[4:5] op_sel_hi:[0,1,1]
	v_pk_fma_f32 v[4:5], v[68:69], v[8:9], v[4:5] op_sel_hi:[0,1,1]
	v_pk_fma_f32 v[4:5], v[72:73], v[12:13], v[4:5] op_sel_hi:[0,1,1]
	v_pk_fma_f32 v[4:5], v[76:77], v[16:17], v[4:5] op_sel_hi:[0,1,1]
; __device__ __forceinline__ void dsa_item(const KP& p, int b, int tile, char* smem) {
;     ...
; #pragma unroll
;         for (int i = 0; i < 8; ++i) {
;           const int pos = (g8 * 8 + i) * 8 + rs;
;           const f32x4 pa = *(const f32x4*)&pbuf[pos * 8];
;           const f32x4 pb = *(const f32x4*)&pbuf[pos * 8 + 4];
;           float vf[8];
; #pragma unroll
;           for (int e = 0; e < 8; ++e) vf[e] = (float)vv[i][e];
; #pragma unroll
;           for (int e = 0; e < 8; ++e) {
;             acc[0][e] += pa[0] * vf[e]; acc[1][e] += pa[1] * vf[e]; acc[2][e] += pa[2] * vf[e]; acc[3][e] += pa[3] * vf[e];
;             acc[4][e] += pb[0] * vf[e]; acc[5][e] += pb[1] * vf[e]; acc[6][e] += pb[2] * vf[e]; acc[7][e] += pb[3] * vf[e];
;           }
	v_pk_fma_f32 v[60:61], v[80:81], v[24:25], v[4:5] op_sel_hi:[0,1,1]
	v_pk_fma_f32 v[4:5], v[154:155], v[136:137], v[90:91] op_sel_hi:[0,1,1]
	v_pk_fma_f32 v[4:5], v[194:195], v[98:99], v[4:5] op_sel_hi:[0,1,1]
	v_pk_fma_f32 v[4:5], v[196:197], v[8:9], v[4:5] op_sel_hi:[0,1,1]
	v_pk_fma_f32 v[4:5], v[198:199], v[12:13], v[4:5] op_sel_hi:[0,1,1]
	v_pk_fma_f32 v[4:5], v[200:201], v[16:17], v[4:5] op_sel_hi:[0,1,1]
	v_pk_fma_f32 v[62:63], v[202:203], v[24:25], v[4:5] op_sel_hi:[0,1,1]
	v_pk_fma_f32 v[4:5], v[34:35], v[136:137], v[102:103] op_sel_hi:[0,1,1]
	v_pk_fma_f32 v[4:5], v[38:39], v[98:99], v[4:5] op_sel_hi:[0,1,1]
	v_pk_fma_f32 v[4:5], v[42:43], v[8:9], v[4:5] op_sel_hi:[0,1,1]
	v_pk_fma_f32 v[4:5], v[46:47], v[12:13], v[4:5] op_sel_hi:[0,1,1]
	v_pk_fma_f32 v[4:5], v[50:51], v[16:17], v[4:5] op_sel_hi:[0,1,1]
	v_pk_fma_f32 v[64:65], v[54:55], v[24:25], v[4:5] op_sel_hi:[0,1,1]
	v_pk_fma_f32 v[4:5], v[34:35], v[136:137], v[96:97] op_sel:[1,0,0]
	v_pk_fma_f32 v[118:119], v[42:43], v[174:175], v[118:119] op_sel_hi:[0,1,1]
	v_pk_fma_f32 v[4:5], v[38:39], v[98:99], v[4:5] op_sel:[1,0,0]
	v_pk_fma_f32 v[112:113], v[42:43], v[174:175], v[112:113] op_sel:[1,0,0]
	v_pk_fma_f32 v[4:5], v[42:43], v[8:9], v[4:5] op_sel:[1,0,0]
	v_pk_fma_f32 v[118:119], v[46:47], v[178:179], v[118:119] op_sel_hi:[0,1,1]
	v_pk_fma_f32 v[4:5], v[46:47], v[12:13], v[4:5] op_sel:[1,0,0]
	v_pk_fma_f32 v[112:113], v[46:47], v[178:179], v[112:113] op_sel:[1,0,0]
	v_pk_fma_f32 v[4:5], v[50:51], v[16:17], v[4:5] op_sel:[1,0,0]
	s_waitcnt vmcnt(9)
	v_cvt_f32_f16_sdwa v43, v19 dst_sel:DWORD dst_unused:UNUSED_PAD src0_sel:WORD_1
	v_pk_fma_f32 v[34:35], v[54:55], v[24:25], v[4:5] op_sel:[1,0,0]
	v_pk_fma_f32 v[4:5], v[36:37], v[136:137], v[92:93] op_sel_hi:[0,1,1]
	v_pk_fma_f32 v[4:5], v[40:41], v[98:99], v[4:5] op_sel_hi:[0,1,1]
	v_pk_fma_f32 v[4:5], v[44:45], v[8:9], v[4:5] op_sel_hi:[0,1,1]
	v_pk_fma_f32 v[4:5], v[48:49], v[12:13], v[4:5] op_sel_hi:[0,1,1]
	v_pk_fma_f32 v[4:5], v[52:53], v[16:17], v[4:5] op_sel_hi:[0,1,1]
	v_pk_fma_f32 v[12:13], v[56:57], v[24:25], v[4:5] op_sel_hi:[0,1,1]
	ds_read_b128 v[4:7], v172 offset:1536
	ds_read_b128 v[8:11], v172 offset:1552
	v_pk_fma_f32 v[24:25], v[176:177], v[24:25], v[22:23] op_sel_hi:[0,1,1]
	v_cvt_f32_f16_sdwa v37, v18 dst_sel:DWORD dst_unused:UNUSED_PAD src0_sel:WORD_1
	v_cvt_f32_f16_e32 v36, v18
	v_cvt_f32_f16_e32 v42, v19
	v_cvt_f32_f16_sdwa v45, v20 dst_sel:DWORD dst_unused:UNUSED_PAD src0_sel:WORD_1
	v_cvt_f32_f16_e32 v44, v20
	v_cvt_f32_f16_sdwa v47, v21 dst_sel:DWORD dst_unused:UNUSED_PAD src0_sel:WORD_1
	v_cvt_f32_f16_e32 v46, v21
	ds_read_b128 v[16:19], v172 offset:1792
	ds_read_b128 v[20:23], v172 offset:1808
	s_waitcnt vmcnt(8)
	v_cvt_f32_f16_e32 v48, v30
	v_cvt_f32_f16_sdwa v49, v30 dst_sel:DWORD dst_unused:UNUSED_PAD src0_sel:WORD_1
	v_pk_fma_f32 v[124:125], v[66:67], v[174:175], v[124:125] op_sel_hi:[0,1,1]
	v_pk_fma_f32 v[116:117], v[66:67], v[174:175], v[116:117] op_sel:[1,0,0]
	v_pk_fma_f32 v[110:111], v[68:69], v[174:175], v[110:111] op_sel_hi:[0,1,1]
	v_pk_fma_f32 v[104:105], v[194:195], v[142:143], v[104:105] op_sel_hi:[0,1,1]
	v_cvt_f32_f16_e32 v30, v31
	v_cvt_f32_f16_sdwa v31, v31 dst_sel:DWORD dst_unused:UNUSED_PAD src0_sel:WORD_1
	v_pk_fma_f32 v[14:15], v[74:75], v[190:191], v[14:15] op_sel_hi:[0,1,1]
	v_pk_fma_f32 v[26:27], v[74:75], v[190:191], v[26:27] op_sel:[1,0,0]
	v_pk_fma_f32 v[128:129], v[76:77], v[190:191], v[128:129] op_sel_hi:[0,1,1]
	v_pk_fma_f32 v[134:135], v[50:51], v[190:191], v[134:135] op_sel_hi:[0,1,1]
	v_pk_fma_f32 v[130:131], v[50:51], v[190:191], v[130:131] op_sel:[1,0,0]
	v_pk_fma_f32 v[124:125], v[70:71], v[178:179], v[124:125] op_sel_hi:[0,1,1]
	v_pk_fma_f32 v[116:117], v[70:71], v[178:179], v[116:117] op_sel:[1,0,0]
	v_pk_fma_f32 v[110:111], v[72:73], v[178:179], v[110:111] op_sel_hi:[0,1,1]
	v_pk_fma_f32 v[104:105], v[196:197], v[174:175], v[104:105] op_sel_hi:[0,1,1]
	v_pk_fma_f32 v[118:119], v[50:51], v[180:181], v[118:119] op_sel_hi:[0,1,1]
	v_pk_fma_f32 v[112:113], v[50:51], v[180:181], v[112:113] op_sel:[1,0,0]
	v_cvt_f32_f16_e32 v50, v32
	v_cvt_f32_f16_sdwa v51, v32 dst_sel:DWORD dst_unused:UNUSED_PAD src0_sel:WORD_1
	v_pk_fma_f32 v[14:15], v[78:79], v[192:193], v[14:15] op_sel_hi:[0,1,1]
	v_pk_fma_f32 v[26:27], v[78:79], v[192:193], v[26:27] op_sel:[1,0,0]
	v_pk_fma_f32 v[128:129], v[80:81], v[192:193], v[128:129] op_sel_hi:[0,1,1]
	v_pk_fma_f32 v[120:121], v[200:201], v[190:191], v[120:121] op_sel_hi:[0,1,1]
	v_pk_fma_f32 v[122:123], v[52:53], v[190:191], v[122:123] op_sel_hi:[0,1,1]
	v_pk_fma_f32 v[124:125], v[74:75], v[180:181], v[124:125] op_sel_hi:[0,1,1]
	v_pk_fma_f32 v[116:117], v[74:75], v[180:181], v[116:117] op_sel:[1,0,0]
	v_pk_fma_f32 v[110:111], v[76:77], v[180:181], v[110:111] op_sel_hi:[0,1,1]
	v_pk_fma_f32 v[104:105], v[198:199], v[178:179], v[104:105] op_sel_hi:[0,1,1]
	s_waitcnt lgkmcnt(3)
	v_mov_b32_e32 v38, v7
	s_waitcnt lgkmcnt(2)
; __device__ __forceinline__ void dsa_item(const KP& p, int b, int tile, char* smem) {
;     ...
; #pragma unroll
;         for (int i = 0; i < 8; ++i) {
;           const int pos = (g8 * 8 + i) * 8 + rs;
;           const f32x4 pa = *(const f32x4*)&pbuf[pos * 8];
;           const f32x4 pb = *(const f32x4*)&pbuf[pos * 8 + 4];
;           float vf[8];
; #pragma unroll
;           for (int e = 0; e < 8; ++e) vf[e] = (float)vv[i][e];
; #pragma unroll
;           for (int e = 0; e < 8; ++e) {
;             acc[0][e] += pa[0] * vf[e]; acc[1][e] += pa[1] * vf[e]; acc[2][e] += pa[2] * vf[e]; acc[3][e] += pa[3] * vf[e];
;             acc[4][e] += pb[0] * vf[e]; acc[5][e] += pb[1] * vf[e]; acc[6][e] += pb[2] * vf[e]; acc[7][e] += pb[3] * vf[e];
;           }
	v_mov_b32_e32 v40, v11
	v_cvt_f32_f16_e32 v32, v33
	v_cvt_f32_f16_sdwa v33, v33 dst_sel:DWORD dst_unused:UNUSED_PAD src0_sel:WORD_1
	v_pk_fma_f32 v[2:3], v[10:11], v[36:37], v[2:3] op_sel_hi:[0,1,1]
	v_pk_fma_f32 v[120:121], v[202:203], v[192:193], v[120:121] op_sel_hi:[0,1,1]
	v_pk_fma_f32 v[134:135], v[54:55], v[192:193], v[134:135] op_sel_hi:[0,1,1]
	v_pk_fma_f32 v[130:131], v[54:55], v[192:193], v[130:131] op_sel:[1,0,0]
	v_pk_fma_f32 v[122:123], v[56:57], v[192:193], v[122:123] op_sel_hi:[0,1,1]
	v_pk_fma_f32 v[132:133], v[176:177], v[192:193], v[132:133] op_sel_hi:[0,1,1]
	v_pk_fma_f32 v[114:115], v[158:159], v[180:181], v[114:115] op_sel_hi:[0,1,1]
	v_pk_fma_f32 v[124:125], v[78:79], v[188:189], v[124:125] op_sel_hi:[0,1,1]
	v_pk_fma_f32 v[116:117], v[78:79], v[188:189], v[116:117] op_sel:[1,0,0]
	v_pk_fma_f32 v[110:111], v[80:81], v[188:189], v[110:111] op_sel_hi:[0,1,1]
	v_pk_fma_f32 v[104:105], v[200:201], v[180:181], v[104:105] op_sel_hi:[0,1,1]
	v_pk_fma_f32 v[118:119], v[54:55], v[188:189], v[118:119] op_sel_hi:[0,1,1]
	v_pk_fma_f32 v[112:113], v[54:55], v[188:189], v[112:113] op_sel:[1,0,0]
	v_pk_fma_f32 v[52:53], v[4:5], v[36:37], v[148:149] op_sel_hi:[0,1,1]
	v_pk_fma_f32 v[54:55], v[4:5], v[36:37], v[152:153] op_sel:[1,0,0]
	v_pk_fma_f32 v[56:57], v[6:7], v[36:37], v[146:147] op_sel_hi:[0,1,1]
	v_pk_fma_f32 v[66:67], v[38:39], v[36:37], v[140:141] op_sel_hi:[0,1,1]
	v_pk_fma_f32 v[68:69], v[8:9], v[36:37], v[150:151] op_sel_hi:[0,1,1]
	v_pk_fma_f32 v[70:71], v[8:9], v[36:37], v[144:145] op_sel:[1,0,0]
	v_pk_fma_f32 v[36:37], v[40:41], v[36:37], v[138:139] op_sel_hi:[0,1,1]
	s_waitcnt lgkmcnt(1)
	v_mov_b32_e32 v72, v19
	s_waitcnt lgkmcnt(0)
	v_mov_b32_e32 v74, v23
	v_pk_fma_f32 v[138:139], v[22:23], v[48:49], v[2:3] op_sel_hi:[0,1,1]
	v_pk_fma_f32 v[2:3], v[4:5], v[42:43], v[14:15] op_sel_hi:[0,1,1]
	v_pk_fma_f32 v[14:15], v[4:5], v[42:43], v[26:27] op_sel:[1,0,0]
	v_pk_fma_f32 v[26:27], v[6:7], v[42:43], v[128:129] op_sel_hi:[0,1,1]
	v_pk_fma_f32 v[104:105], v[202:203], v[188:189], v[104:105] op_sel_hi:[0,1,1]
	v_pk_fma_f32 v[114:115], v[176:177], v[188:189], v[114:115] op_sel_hi:[0,1,1]
	v_pk_fma_f32 v[154:155], v[16:17], v[48:49], v[52:53] op_sel_hi:[0,1,1]
	v_pk_fma_f32 v[152:153], v[16:17], v[48:49], v[54:55] op_sel:[1,0,0]
	v_pk_fma_f32 v[146:147], v[18:19], v[48:49], v[56:57] op_sel_hi:[0,1,1]
	v_pk_fma_f32 v[140:141], v[72:73], v[48:49], v[66:67] op_sel_hi:[0,1,1]
	v_pk_fma_f32 v[150:151], v[20:21], v[48:49], v[68:69] op_sel_hi:[0,1,1]
	v_pk_fma_f32 v[144:145], v[20:21], v[48:49], v[70:71] op_sel:[1,0,0]
	v_pk_fma_f32 v[148:149], v[74:75], v[48:49], v[36:37] op_sel_hi:[0,1,1]
	v_pk_fma_f32 v[36:37], v[38:39], v[42:43], v[120:121] op_sel_hi:[0,1,1]
	v_pk_fma_f32 v[48:49], v[8:9], v[42:43], v[134:135] op_sel_hi:[0,1,1]
	v_pk_fma_f32 v[52:53], v[8:9], v[42:43], v[130:131] op_sel:[1,0,0]
	v_pk_fma_f32 v[54:55], v[10:11], v[42:43], v[122:123] op_sel_hi:[0,1,1]
	v_pk_fma_f32 v[42:43], v[40:41], v[42:43], v[132:133] op_sel_hi:[0,1,1]
	v_pk_fma_f32 v[142:143], v[16:17], v[30:31], v[2:3] op_sel_hi:[0,1,1]
	v_pk_fma_f32 v[134:135], v[16:17], v[30:31], v[14:15] op_sel:[1,0,0]
	v_pk_fma_f32 v[128:129], v[18:19], v[30:31], v[26:27] op_sel_hi:[0,1,1]
	v_pk_fma_f32 v[2:3], v[4:5], v[44:45], v[124:125] op_sel_hi:[0,1,1]
	v_pk_fma_f32 v[14:15], v[4:5], v[44:45], v[116:117] op_sel:[1,0,0]
	v_pk_fma_f32 v[26:27], v[6:7], v[44:45], v[110:111] op_sel_hi:[0,1,1]
	v_pk_fma_f32 v[120:121], v[72:73], v[30:31], v[36:37] op_sel_hi:[0,1,1]
	v_pk_fma_f32 v[136:137], v[20:21], v[30:31], v[48:49] op_sel_hi:[0,1,1]
	v_pk_fma_f32 v[130:131], v[20:21], v[30:31], v[52:53] op_sel:[1,0,0]
	v_pk_fma_f32 v[122:123], v[22:23], v[30:31], v[54:55] op_sel_hi:[0,1,1]
	v_pk_fma_f32 v[132:133], v[74:75], v[30:31], v[42:43] op_sel_hi:[0,1,1]
	v_pk_fma_f32 v[30:31], v[38:39], v[44:45], v[104:105] op_sel_hi:[0,1,1]
	v_pk_fma_f32 v[36:37], v[8:9], v[44:45], v[118:119] op_sel_hi:[0,1,1]
	v_pk_fma_f32 v[42:43], v[8:9], v[44:45], v[112:113] op_sel:[1,0,0]
	v_pk_fma_f32 v[48:49], v[10:11], v[44:45], v[106:107] op_sel_hi:[0,1,1]
	v_pk_fma_f32 v[44:45], v[40:41], v[44:45], v[114:115] op_sel_hi:[0,1,1]
	v_pk_fma_f32 v[124:125], v[16:17], v[50:51], v[2:3] op_sel_hi:[0,1,1]
	v_pk_fma_f32 v[116:117], v[16:17], v[50:51], v[14:15] op_sel:[1,0,0]
	v_pk_fma_f32 v[110:111], v[18:19], v[50:51], v[26:27] op_sel_hi:[0,1,1]
	v_pk_fma_f32 v[2:3], v[4:5], v[46:47], v[28:29] op_sel_hi:[0,1,1]
	v_pk_fma_f32 v[4:5], v[4:5], v[46:47], v[58:59] op_sel:[1,0,0]
	v_pk_fma_f32 v[6:7], v[6:7], v[46:47], v[60:61] op_sel_hi:[0,1,1]
	v_pk_fma_f32 v[14:15], v[38:39], v[46:47], v[62:63] op_sel_hi:[0,1,1]
	v_pk_fma_f32 v[26:27], v[8:9], v[46:47], v[64:65] op_sel_hi:[0,1,1]
	v_pk_fma_f32 v[8:9], v[8:9], v[46:47], v[34:35] op_sel:[1,0,0]
	v_pk_fma_f32 v[10:11], v[10:11], v[46:47], v[12:13] op_sel_hi:[0,1,1]
	v_pk_fma_f32 v[12:13], v[40:41], v[46:47], v[24:25] op_sel_hi:[0,1,1]
	v_pk_fma_f32 v[104:105], v[72:73], v[50:51], v[30:31] op_sel_hi:[0,1,1]
	v_pk_fma_f32 v[118:119], v[20:21], v[50:51], v[36:37] op_sel_hi:[0,1,1]
	v_pk_fma_f32 v[112:113], v[20:21], v[50:51], v[42:43] op_sel:[1,0,0]
	v_pk_fma_f32 v[106:107], v[22:23], v[50:51], v[48:49] op_sel_hi:[0,1,1]
	v_pk_fma_f32 v[114:115], v[74:75], v[50:51], v[44:45] op_sel_hi:[0,1,1]
	v_pk_fma_f32 v[108:109], v[16:17], v[32:33], v[2:3] op_sel_hi:[0,1,1]
	v_pk_fma_f32 v[100:101], v[16:17], v[32:33], v[4:5] op_sel:[1,0,0]
	v_pk_fma_f32 v[94:95], v[18:19], v[32:33], v[6:7] op_sel_hi:[0,1,1]
	v_pk_fma_f32 v[90:91], v[72:73], v[32:33], v[14:15] op_sel_hi:[0,1,1]
	v_pk_fma_f32 v[102:103], v[20:21], v[32:33], v[26:27] op_sel_hi:[0,1,1]
	v_pk_fma_f32 v[96:97], v[20:21], v[32:33], v[8:9] op_sel:[1,0,0]
	v_pk_fma_f32 v[92:93], v[22:23], v[32:33], v[10:11] op_sel_hi:[0,1,1]
	v_pk_fma_f32 v[98:99], v[74:75], v[32:33], v[12:13] op_sel_hi:[0,1,1]
	v_add_u32_e32 v172, 0x800, v172
	s_waitcnt vmcnt(7)
; __device__ __forceinline__ void dsa_item(const KP& p, int b, int tile, char* smem) {
;     ...
; #pragma unroll
;         for (int i = 0; i < 8; ++i) {
;           const int pos = (g8 * 8 + i) * 8 + rs;
;           const f32x4 pa = *(const f32x4*)&pbuf[pos * 8];
;           const f32x4 pb = *(const f32x4*)&pbuf[pos * 8 + 4];
;           float vf[8];
; #pragma unroll
;           for (int e = 0; e < 8; ++e) vf[e] = (float)vv[i][e];
; #pragma unroll
;           for (int e = 0; e < 8; ++e) {
;             acc[0][e] += pa[0] * vf[e]; acc[1][e] += pa[1] * vf[e]; acc[2][e] += pa[2] * vf[e]; acc[3][e] += pa[3] * vf[e];
;             acc[4][e] += pb[0] * vf[e]; acc[5][e] += pb[1] * vf[e]; acc[6][e] += pb[2] * vf[e]; acc[7][e] += pb[3] * vf[e];
;           }
	v_cvt_f32_f16_sdwa v175, v204 dst_sel:DWORD dst_unused:UNUSED_PAD src0_sel:WORD_1
	v_cvt_f32_f16_e32 v174, v204
	s_waitcnt vmcnt(6)
	v_cvt_f32_f16_sdwa v177, v208 dst_sel:DWORD dst_unused:UNUSED_PAD src0_sel:WORD_1
	v_cvt_f32_f16_e32 v176, v208
	ds_read_b128 v[58:61], v172
	ds_read_b128 v[34:37], v172 offset:16
	ds_read_b128 v[62:65], v172 offset:256
	ds_read_b128 v[38:41], v172 offset:272
	ds_read_b128 v[66:69], v172 offset:512
	ds_read_b128 v[42:45], v172 offset:528
	ds_read_b128 v[70:73], v172 offset:768
	ds_read_b128 v[46:49], v172 offset:784
	ds_read_b128 v[74:77], v172 offset:1024
	ds_read_b128 v[50:53], v172 offset:1040
	s_waitcnt vmcnt(5)
	v_cvt_f32_f16_sdwa v179, v212 dst_sel:DWORD dst_unused:UNUSED_PAD src0_sel:WORD_1
	v_cvt_f32_f16_e32 v178, v212
	s_waitcnt lgkmcnt(8)
	v_mov_b32_e32 v156, v37
	s_waitcnt vmcnt(4)
	v_cvt_f32_f16_sdwa v181, v216 dst_sel:DWORD dst_unused:UNUSED_PAD src0_sel:WORD_1
	v_cvt_f32_f16_e32 v180, v216
	v_pk_fma_f32 v[148:149], v[156:157], v[174:175], v[148:149] op_sel_hi:[0,1,1]
	s_waitcnt lgkmcnt(6)
	v_mov_b32_e32 v208, v41
	s_waitcnt vmcnt(3)
	v_cvt_f32_f16_sdwa v189, v224 dst_sel:DWORD dst_unused:UNUSED_PAD src0_sel:WORD_1
	v_cvt_f32_f16_e32 v188, v224
	v_pk_fma_f32 v[148:149], v[208:209], v[176:177], v[148:149] op_sel_hi:[0,1,1]
	s_waitcnt lgkmcnt(4)
	v_mov_b32_e32 v212, v45
	v_pk_fma_f32 v[148:149], v[212:213], v[178:179], v[148:149] op_sel_hi:[0,1,1]
	s_waitcnt lgkmcnt(2)
	v_mov_b32_e32 v224, v49
	v_pk_fma_f32 v[148:149], v[224:225], v[180:181], v[148:149] op_sel_hi:[0,1,1]
	s_waitcnt lgkmcnt(0)
	v_mov_b32_e32 v158, v53
	ds_read_b128 v[78:81], v172 offset:1280
	ds_read_b128 v[54:57], v172 offset:1296
	v_pk_fma_f32 v[190:191], v[158:159], v[188:189], v[148:149] op_sel_hi:[0,1,1]
	v_pk_fma_f32 v[148:149], v[58:59], v[174:175], v[154:155] op_sel_hi:[0,1,1]
	v_mov_b32_e32 v154, v61
	v_pk_fma_f32 v[152:153], v[58:59], v[174:175], v[152:153] op_sel:[1,0,0]
	v_pk_fma_f32 v[146:147], v[60:61], v[174:175], v[146:147] op_sel_hi:[0,1,1]
	v_pk_fma_f32 v[140:141], v[154:155], v[174:175], v[140:141] op_sel_hi:[0,1,1]
	v_mov_b32_e32 v194, v65
	v_pk_fma_f32 v[150:151], v[34:35], v[174:175], v[150:151] op_sel_hi:[0,1,1]
	v_pk_fma_f32 v[144:145], v[34:35], v[174:175], v[144:145] op_sel:[1,0,0]
	v_pk_fma_f32 v[138:139], v[36:37], v[174:175], v[138:139] op_sel_hi:[0,1,1]
	s_waitcnt vmcnt(2)
	v_cvt_f32_f16_sdwa v193, v228 dst_sel:DWORD dst_unused:UNUSED_PAD src0_sel:WORD_1
	v_cvt_f32_f16_e32 v192, v228
	v_pk_fma_f32 v[148:149], v[62:63], v[176:177], v[148:149] op_sel_hi:[0,1,1]
	v_pk_fma_f32 v[152:153], v[62:63], v[176:177], v[152:153] op_sel:[1,0,0]
	v_pk_fma_f32 v[146:147], v[64:65], v[176:177], v[146:147] op_sel_hi:[0,1,1]
	v_pk_fma_f32 v[140:141], v[194:195], v[176:177], v[140:141] op_sel_hi:[0,1,1]
	v_mov_b32_e32 v196, v69
	v_pk_fma_f32 v[150:151], v[38:39], v[176:177], v[150:151] op_sel_hi:[0,1,1]
	v_pk_fma_f32 v[144:145], v[38:39], v[176:177], v[144:145] op_sel:[1,0,0]
	v_pk_fma_f32 v[138:139], v[40:41], v[176:177], v[138:139] op_sel_hi:[0,1,1]
	v_cvt_f32_f16_sdwa v175, v205 dst_sel:DWORD dst_unused:UNUSED_PAD src0_sel:WORD_1
	v_cvt_f32_f16_e32 v174, v205
	v_pk_fma_f32 v[148:149], v[66:67], v[178:179], v[148:149] op_sel_hi:[0,1,1]
	v_pk_fma_f32 v[152:153], v[66:67], v[178:179], v[152:153] op_sel:[1,0,0]
	v_pk_fma_f32 v[146:147], v[68:69], v[178:179], v[146:147] op_sel_hi:[0,1,1]
	v_pk_fma_f32 v[140:141], v[196:197], v[178:179], v[140:141] op_sel_hi:[0,1,1]
	v_mov_b32_e32 v198, v73
	v_pk_fma_f32 v[150:151], v[42:43], v[178:179], v[150:151] op_sel_hi:[0,1,1]
	v_pk_fma_f32 v[144:145], v[42:43], v[178:179], v[144:145] op_sel:[1,0,0]
	v_pk_fma_f32 v[138:139], v[44:45], v[178:179], v[138:139] op_sel_hi:[0,1,1]
	v_cvt_f32_f16_sdwa v179, v209 dst_sel:DWORD dst_unused:UNUSED_PAD src0_sel:WORD_1
	v_cvt_f32_f16_e32 v178, v209
	v_pk_fma_f32 v[148:149], v[70:71], v[180:181], v[148:149] op_sel_hi:[0,1,1]
	v_pk_fma_f32 v[152:153], v[70:71], v[180:181], v[152:153] op_sel:[1,0,0]
	v_pk_fma_f32 v[146:147], v[72:73], v[180:181], v[146:147] op_sel_hi:[0,1,1]
	v_pk_fma_f32 v[140:141], v[198:199], v[180:181], v[140:141] op_sel_hi:[0,1,1]
	v_mov_b32_e32 v200, v77
	v_pk_fma_f32 v[150:151], v[46:47], v[180:181], v[150:151] op_sel_hi:[0,1,1]
	v_pk_fma_f32 v[144:145], v[46:47], v[180:181], v[144:145] op_sel:[1,0,0]
	v_pk_fma_f32 v[138:139], v[48:49], v[180:181], v[138:139] op_sel_hi:[0,1,1]
	v_cvt_f32_f16_sdwa v181, v213 dst_sel:DWORD dst_unused:UNUSED_PAD src0_sel:WORD_1
	v_cvt_f32_f16_e32 v180, v213
	v_pk_fma_f32 v[148:149], v[74:75], v[188:189], v[148:149] op_sel_hi:[0,1,1]
	v_pk_fma_f32 v[152:153], v[74:75], v[188:189], v[152:153] op_sel:[1,0,0]
	v_pk_fma_f32 v[146:147], v[76:77], v[188:189], v[146:147] op_sel_hi:[0,1,1]
	v_pk_fma_f32 v[140:141], v[200:201], v[188:189], v[140:141] op_sel_hi:[0,1,1]
	v_pk_fma_f32 v[150:151], v[50:51], v[188:189], v[150:151] op_sel_hi:[0,1,1]
	v_pk_fma_f32 v[144:145], v[50:51], v[188:189], v[144:145] op_sel:[1,0,0]
	v_pk_fma_f32 v[138:139], v[52:53], v[188:189], v[138:139] op_sel_hi:[0,1,1]
	s_waitcnt lgkmcnt(0)
; __device__ __forceinline__ void dsa_item(const KP& p, int b, int tile, char* smem) {
;     ...
; #pragma unroll
;         for (int i = 0; i < 8; ++i) {
;           const int pos = (g8 * 8 + i) * 8 + rs;
;           const f32x4 pa = *(const f32x4*)&pbuf[pos * 8];
;           const f32x4 pb = *(const f32x4*)&pbuf[pos * 8 + 4];
;           float vf[8];
; #pragma unroll
;           for (int e = 0; e < 8; ++e) vf[e] = (float)vv[i][e];
; #pragma unroll
;           for (int e = 0; e < 8; ++e) {
;             acc[0][e] += pa[0] * vf[e]; acc[1][e] += pa[1] * vf[e]; acc[2][e] += pa[2] * vf[e]; acc[3][e] += pa[3] * vf[e];
;             acc[4][e] += pb[0] * vf[e]; acc[5][e] += pb[1] * vf[e]; acc[6][e] += pb[2] * vf[e]; acc[7][e] += pb[3] * vf[e];
;           }
	v_mov_b32_e32 v176, v57
	v_cvt_f32_f16_sdwa v189, v217 dst_sel:DWORD dst_unused:UNUSED_PAD src0_sel:WORD_1
	v_cvt_f32_f16_e32 v188, v217
	v_pk_fma_f32 v[204:205], v[56:57], v[192:193], v[138:139] op_sel_hi:[0,1,1]
	v_pk_fma_f32 v[138:139], v[176:177], v[192:193], v[190:191] op_sel_hi:[0,1,1]
	v_pk_fma_f32 v[132:133], v[156:157], v[174:175], v[132:133] op_sel_hi:[0,1,1]
	v_cvt_f32_f16_sdwa v191, v225 dst_sel:DWORD dst_unused:UNUSED_PAD src0_sel:WORD_1
	v_cvt_f32_f16_e32 v190, v225
	v_pk_fma_f32 v[216:217], v[208:209], v[178:179], v[132:133] op_sel_hi:[0,1,1]
	v_mov_b32_e32 v202, v81
	v_pk_fma_f32 v[216:217], v[212:213], v[180:181], v[216:217] op_sel_hi:[0,1,1]
	v_pk_fma_f32 v[148:149], v[78:79], v[192:193], v[148:149] op_sel_hi:[0,1,1]
	v_pk_fma_f32 v[152:153], v[78:79], v[192:193], v[152:153] op_sel:[1,0,0]
	v_pk_fma_f32 v[146:147], v[80:81], v[192:193], v[146:147] op_sel_hi:[0,1,1]
	v_pk_fma_f32 v[140:141], v[202:203], v[192:193], v[140:141] op_sel_hi:[0,1,1]
	v_pk_fma_f32 v[150:151], v[54:55], v[192:193], v[150:151] op_sel_hi:[0,1,1]
	v_pk_fma_f32 v[144:145], v[54:55], v[192:193], v[144:145] op_sel:[1,0,0]
	v_pk_fma_f32 v[216:217], v[224:225], v[188:189], v[216:217] op_sel_hi:[0,1,1]
	v_cvt_f32_f16_sdwa v193, v229 dst_sel:DWORD dst_unused:UNUSED_PAD src0_sel:WORD_1
	v_cvt_f32_f16_e32 v192, v229
	v_pk_fma_f32 v[228:229], v[58:59], v[174:175], v[134:135] op_sel:[1,0,0]
	v_pk_fma_f32 v[134:135], v[34:35], v[174:175], v[136:137] op_sel_hi:[0,1,1]
	v_cvt_f32_f16_sdwa v137, v206 dst_sel:DWORD dst_unused:UNUSED_PAD src0_sel:WORD_1
	v_cvt_f32_f16_e32 v136, v206
	v_pk_fma_f32 v[132:133], v[158:159], v[190:191], v[216:217] op_sel_hi:[0,1,1]
	v_pk_fma_f32 v[216:217], v[58:59], v[174:175], v[142:143] op_sel_hi:[0,1,1]
	v_cvt_f32_f16_sdwa v143, v210 dst_sel:DWORD dst_unused:UNUSED_PAD src0_sel:WORD_1
	v_cvt_f32_f16_e32 v142, v210
	v_pk_fma_f32 v[128:129], v[60:61], v[174:175], v[128:129] op_sel_hi:[0,1,1]
	v_pk_fma_f32 v[120:121], v[154:155], v[174:175], v[120:121] op_sel_hi:[0,1,1]
	v_pk_fma_f32 v[130:131], v[34:35], v[174:175], v[130:131] op_sel:[1,0,0]
	v_pk_fma_f32 v[122:123], v[36:37], v[174:175], v[122:123] op_sel_hi:[0,1,1]
	v_cvt_f32_f16_sdwa v175, v214 dst_sel:DWORD dst_unused:UNUSED_PAD src0_sel:WORD_1
	v_cvt_f32_f16_e32 v174, v214
	v_pk_fma_f32 v[216:217], v[62:63], v[178:179], v[216:217] op_sel_hi:[0,1,1]
	v_pk_fma_f32 v[228:229], v[62:63], v[178:179], v[228:229] op_sel:[1,0,0]
	v_pk_fma_f32 v[128:129], v[64:65], v[178:179], v[128:129] op_sel_hi:[0,1,1]
	v_pk_fma_f32 v[120:121], v[194:195], v[178:179], v[120:121] op_sel_hi:[0,1,1]
	v_pk_fma_f32 v[134:135], v[38:39], v[178:179], v[134:135] op_sel_hi:[0,1,1]
	v_pk_fma_f32 v[130:131], v[38:39], v[178:179], v[130:131] op_sel:[1,0,0]
	v_pk_fma_f32 v[122:123], v[40:41], v[178:179], v[122:123] op_sel_hi:[0,1,1]
	v_cvt_f32_f16_sdwa v179, v218 dst_sel:DWORD dst_unused:UNUSED_PAD src0_sel:WORD_1
	v_cvt_f32_f16_e32 v178, v218
	v_pk_fma_f32 v[216:217], v[66:67], v[180:181], v[216:217] op_sel_hi:[0,1,1]
	v_pk_fma_f32 v[228:229], v[66:67], v[180:181], v[228:229] op_sel:[1,0,0]
	v_pk_fma_f32 v[128:129], v[68:69], v[180:181], v[128:129] op_sel_hi:[0,1,1]
	v_pk_fma_f32 v[120:121], v[196:197], v[180:181], v[120:121] op_sel_hi:[0,1,1]
	v_pk_fma_f32 v[134:135], v[42:43], v[180:181], v[134:135] op_sel_hi:[0,1,1]
	v_pk_fma_f32 v[130:131], v[42:43], v[180:181], v[130:131] op_sel:[1,0,0]
	v_pk_fma_f32 v[122:123], v[44:45], v[180:181], v[122:123] op_sel_hi:[0,1,1]
	v_cvt_f32_f16_sdwa v181, v226 dst_sel:DWORD dst_unused:UNUSED_PAD src0_sel:WORD_1
	v_cvt_f32_f16_e32 v180, v226
	v_pk_fma_f32 v[106:107], v[36:37], v[136:137], v[106:107] op_sel_hi:[0,1,1]
	v_pk_fma_f32 v[216:217], v[70:71], v[188:189], v[216:217] op_sel_hi:[0,1,1]
	v_pk_fma_f32 v[228:229], v[70:71], v[188:189], v[228:229] op_sel:[1,0,0]
	v_pk_fma_f32 v[128:129], v[72:73], v[188:189], v[128:129] op_sel_hi:[0,1,1]
	v_pk_fma_f32 v[120:121], v[198:199], v[188:189], v[120:121] op_sel_hi:[0,1,1]
	v_pk_fma_f32 v[134:135], v[46:47], v[188:189], v[134:135] op_sel_hi:[0,1,1]
	v_pk_fma_f32 v[130:131], v[46:47], v[188:189], v[130:131] op_sel:[1,0,0]
	v_pk_fma_f32 v[122:123], v[48:49], v[188:189], v[122:123] op_sel_hi:[0,1,1]
	v_pk_fma_f32 v[114:115], v[156:157], v[136:137], v[114:115] op_sel_hi:[0,1,1]
	v_cvt_f32_f16_sdwa v189, v230 dst_sel:DWORD dst_unused:UNUSED_PAD src0_sel:WORD_1
	v_cvt_f32_f16_e32 v188, v230
	v_pk_fma_f32 v[124:125], v[58:59], v[136:137], v[124:125] op_sel_hi:[0,1,1]
	v_pk_fma_f32 v[116:117], v[58:59], v[136:137], v[116:117] op_sel:[1,0,0]
	v_pk_fma_f32 v[110:111], v[60:61], v[136:137], v[110:111] op_sel_hi:[0,1,1]
	v_pk_fma_f32 v[104:105], v[154:155], v[136:137], v[104:105] op_sel_hi:[0,1,1]
	v_pk_fma_f32 v[118:119], v[34:35], v[136:137], v[118:119] op_sel_hi:[0,1,1]
	v_pk_fma_f32 v[112:113], v[34:35], v[136:137], v[112:113] op_sel:[1,0,0]
	v_pk_fma_f32 v[106:107], v[40:41], v[142:143], v[106:107] op_sel_hi:[0,1,1]
	v_cvt_f32_f16_sdwa v137, v207 dst_sel:DWORD dst_unused:UNUSED_PAD src0_sel:WORD_1
	v_cvt_f32_f16_e32 v136, v207
	v_pk_fma_f32 v[106:107], v[44:45], v[174:175], v[106:107] op_sel_hi:[0,1,1]
	v_pk_fma_f32 v[106:107], v[48:49], v[178:179], v[106:107] op_sel_hi:[0,1,1]
	v_pk_fma_f32 v[206:207], v[52:53], v[180:181], v[106:107] op_sel_hi:[0,1,1]
	v_pk_fma_f32 v[106:107], v[56:57], v[188:189], v[206:207] op_sel_hi:[0,1,1]
	v_pk_fma_f32 v[206:207], v[156:157], v[136:137], v[98:99] op_sel_hi:[0,1,1]
	v_cvt_f32_f16_sdwa v99, v211 dst_sel:DWORD dst_unused:UNUSED_PAD src0_sel:WORD_1
	v_cvt_f32_f16_e32 v98, v211
	v_cvt_f32_f16_sdwa v211, v215 dst_sel:DWORD dst_unused:UNUSED_PAD src0_sel:WORD_1
	v_cvt_f32_f16_e32 v210, v215
; __device__ __forceinline__ void dsa_item(const KP& p, int b, int tile, char* smem) {
;     ...
;       for (int g8 = 0; g8 < 4; ++g8) {
;         h8 vv[8];
; #pragma unroll
;         for (int i = 0; i < 8; ++i) {
;           const int pos = (g8 * 8 + i) * 8 + rs;
;           const int s = (pos < nsel) ? (int)sel[tk * 256 + pos] : 0;
;           vv[i] = *(const h8*)(ub + (size_t)s * NU + C_BV + dc * 8);
;         }
; #pragma unroll
;         for (int i = 0; i < 8; ++i) {
;           const int pos = (g8 * 8 + i) * 8 + rs;
;           const f32x4 pa = *(const f32x4*)&pbuf[pos * 8];
;           const f32x4 pb = *(const f32x4*)&pbuf[pos * 8 + 4];
;           float vf[8];
; #pragma unroll
;           for (int e = 0; e < 8; ++e) vf[e] = (float)vv[i][e];
; #pragma unroll
;           for (int e = 0; e < 8; ++e) {
;             acc[0][e] += pa[0] * vf[e]; acc[1][e] += pa[1] * vf[e]; acc[2][e] += pa[2] * vf[e]; acc[3][e] += pa[3] * vf[e];
;             acc[4][e] += pb[0] * vf[e]; acc[5][e] += pb[1] * vf[e]; acc[6][e] += pb[2] * vf[e]; acc[7][e] += pb[3] * vf[e];
;           }
;         }
	v_cvt_f32_f16_sdwa v215, v219 dst_sel:DWORD dst_unused:UNUSED_PAD src0_sel:WORD_1
	v_cvt_f32_f16_e32 v214, v219
	v_cvt_f32_f16_sdwa v219, v227 dst_sel:DWORD dst_unused:UNUSED_PAD src0_sel:WORD_1
	v_cvt_f32_f16_e32 v218, v227
	v_pk_fma_f32 v[206:207], v[208:209], v[98:99], v[206:207] op_sel_hi:[0,1,1]
	v_pk_fma_f32 v[114:115], v[208:209], v[142:143], v[114:115] op_sel_hi:[0,1,1]
	v_pk_fma_f32 v[206:207], v[212:213], v[210:211], v[206:207] op_sel_hi:[0,1,1]
	v_pk_fma_f32 v[114:115], v[212:213], v[174:175], v[114:115] op_sel_hi:[0,1,1]
	v_pk_fma_f32 v[206:207], v[224:225], v[214:215], v[206:207] op_sel_hi:[0,1,1]
	v_pk_fma_f32 v[114:115], v[224:225], v[178:179], v[114:115] op_sel_hi:[0,1,1]
	v_pk_fma_f32 v[224:225], v[158:159], v[218:219], v[206:207] op_sel_hi:[0,1,1]
	v_pk_fma_f32 v[206:207], v[58:59], v[136:137], v[108:109] op_sel_hi:[0,1,1]
	v_cvt_f32_f16_sdwa v227, v231 dst_sel:DWORD dst_unused:UNUSED_PAD src0_sel:WORD_1
	v_cvt_f32_f16_e32 v226, v231
	v_pk_fma_f32 v[206:207], v[62:63], v[98:99], v[206:207] op_sel_hi:[0,1,1]
	v_pk_fma_f32 v[206:207], v[66:67], v[210:211], v[206:207] op_sel_hi:[0,1,1]
	v_pk_fma_f32 v[206:207], v[70:71], v[214:215], v[206:207] op_sel_hi:[0,1,1]
	v_pk_fma_f32 v[206:207], v[74:75], v[218:219], v[206:207] op_sel_hi:[0,1,1]
	v_pk_fma_f32 v[230:231], v[78:79], v[226:227], v[206:207] op_sel_hi:[0,1,1]
	v_pk_fma_f32 v[206:207], v[58:59], v[136:137], v[100:101] op_sel:[1,0,0]
	v_pk_fma_f32 v[124:125], v[62:63], v[142:143], v[124:125] op_sel_hi:[0,1,1]
	v_pk_fma_f32 v[206:207], v[62:63], v[98:99], v[206:207] op_sel:[1,0,0]
	v_pk_fma_f32 v[116:117], v[62:63], v[142:143], v[116:117] op_sel:[1,0,0]
	v_pk_fma_f32 v[206:207], v[66:67], v[210:211], v[206:207] op_sel:[1,0,0]
	v_pk_fma_f32 v[110:111], v[64:65], v[142:143], v[110:111] op_sel_hi:[0,1,1]
	v_pk_fma_f32 v[206:207], v[70:71], v[214:215], v[206:207] op_sel:[1,0,0]
	v_pk_fma_f32 v[118:119], v[38:39], v[142:143], v[118:119] op_sel_hi:[0,1,1]
	v_pk_fma_f32 v[206:207], v[74:75], v[218:219], v[206:207] op_sel:[1,0,0]
	v_pk_fma_f32 v[112:113], v[38:39], v[142:143], v[112:113] op_sel:[1,0,0]
	v_pk_fma_f32 v[58:59], v[78:79], v[226:227], v[206:207] op_sel:[1,0,0]
	v_pk_fma_f32 v[206:207], v[60:61], v[136:137], v[94:95] op_sel_hi:[0,1,1]
	v_pk_fma_f32 v[206:207], v[64:65], v[98:99], v[206:207] op_sel_hi:[0,1,1]
	v_pk_fma_f32 v[206:207], v[68:69], v[210:211], v[206:207] op_sel_hi:[0,1,1]
	v_pk_fma_f32 v[206:207], v[72:73], v[214:215], v[206:207] op_sel_hi:[0,1,1]
	v_pk_fma_f32 v[206:207], v[76:77], v[218:219], v[206:207] op_sel_hi:[0,1,1]
	v_pk_fma_f32 v[60:61], v[80:81], v[226:227], v[206:207] op_sel_hi:[0,1,1]
	v_pk_fma_f32 v[206:207], v[154:155], v[136:137], v[90:91] op_sel_hi:[0,1,1]
	v_pk_fma_f32 v[206:207], v[194:195], v[98:99], v[206:207] op_sel_hi:[0,1,1]
	v_pk_fma_f32 v[206:207], v[196:197], v[210:211], v[206:207] op_sel_hi:[0,1,1]
	v_pk_fma_f32 v[206:207], v[198:199], v[214:215], v[206:207] op_sel_hi:[0,1,1]
	v_pk_fma_f32 v[206:207], v[200:201], v[218:219], v[206:207] op_sel_hi:[0,1,1]
	v_pk_fma_f32 v[62:63], v[202:203], v[226:227], v[206:207] op_sel_hi:[0,1,1]
	v_pk_fma_f32 v[206:207], v[34:35], v[136:137], v[102:103] op_sel_hi:[0,1,1]
	v_pk_fma_f32 v[206:207], v[38:39], v[98:99], v[206:207] op_sel_hi:[0,1,1]
	v_pk_fma_f32 v[206:207], v[42:43], v[210:211], v[206:207] op_sel_hi:[0,1,1]
	v_pk_fma_f32 v[206:207], v[46:47], v[214:215], v[206:207] op_sel_hi:[0,1,1]
	v_pk_fma_f32 v[206:207], v[50:51], v[218:219], v[206:207] op_sel_hi:[0,1,1]
	v_pk_fma_f32 v[64:65], v[54:55], v[226:227], v[206:207] op_sel_hi:[0,1,1]
	v_pk_fma_f32 v[206:207], v[34:35], v[136:137], v[96:97] op_sel:[1,0,0]
	v_pk_fma_f32 v[118:119], v[42:43], v[174:175], v[118:119] op_sel_hi:[0,1,1]
	v_pk_fma_f32 v[206:207], v[38:39], v[98:99], v[206:207] op_sel:[1,0,0]
	v_pk_fma_f32 v[112:113], v[42:43], v[174:175], v[112:113] op_sel:[1,0,0]
	v_pk_fma_f32 v[206:207], v[42:43], v[210:211], v[206:207] op_sel:[1,0,0]
	v_pk_fma_f32 v[118:119], v[46:47], v[178:179], v[118:119] op_sel_hi:[0,1,1]
	v_pk_fma_f32 v[206:207], v[46:47], v[214:215], v[206:207] op_sel:[1,0,0]
	v_pk_fma_f32 v[112:113], v[46:47], v[178:179], v[112:113] op_sel:[1,0,0]
	v_pk_fma_f32 v[206:207], v[50:51], v[218:219], v[206:207] op_sel:[1,0,0]
	s_waitcnt vmcnt(1)
	v_cvt_f32_f16_sdwa v43, v221 dst_sel:DWORD dst_unused:UNUSED_PAD src0_sel:WORD_1
	v_pk_fma_f32 v[34:35], v[54:55], v[226:227], v[206:207] op_sel:[1,0,0]
	v_pk_fma_f32 v[206:207], v[36:37], v[136:137], v[92:93] op_sel_hi:[0,1,1]
	v_pk_fma_f32 v[206:207], v[40:41], v[98:99], v[206:207] op_sel_hi:[0,1,1]
	v_pk_fma_f32 v[206:207], v[44:45], v[210:211], v[206:207] op_sel_hi:[0,1,1]
	v_pk_fma_f32 v[206:207], v[48:49], v[214:215], v[206:207] op_sel_hi:[0,1,1]
	v_pk_fma_f32 v[206:207], v[52:53], v[218:219], v[206:207] op_sel_hi:[0,1,1]
	v_pk_fma_f32 v[214:215], v[56:57], v[226:227], v[206:207] op_sel_hi:[0,1,1]
	ds_read_b128 v[206:209], v172 offset:1536
	ds_read_b128 v[210:213], v172 offset:1552
	v_pk_fma_f32 v[226:227], v[176:177], v[226:227], v[224:225] op_sel_hi:[0,1,1]
	v_cvt_f32_f16_sdwa v37, v220 dst_sel:DWORD dst_unused:UNUSED_PAD src0_sel:WORD_1
	v_cvt_f32_f16_e32 v36, v220
	v_cvt_f32_f16_e32 v42, v221
	v_cvt_f32_f16_sdwa v45, v222 dst_sel:DWORD dst_unused:UNUSED_PAD src0_sel:WORD_1
	v_cvt_f32_f16_e32 v44, v222
	v_cvt_f32_f16_sdwa v47, v223 dst_sel:DWORD dst_unused:UNUSED_PAD src0_sel:WORD_1
	v_cvt_f32_f16_e32 v46, v223
	ds_read_b128 v[218:221], v172 offset:1792
	ds_read_b128 v[222:225], v172 offset:1808
	s_waitcnt vmcnt(0)
; __device__ __forceinline__ void dsa_item(const KP& p, int b, int tile, char* smem) {
;     ...
;         for (int i = 0; i < 8; ++i) {
;           const int pos = (g8 * 8 + i) * 8 + rs;
;           const f32x4 pa = *(const f32x4*)&pbuf[pos * 8];
;           const f32x4 pb = *(const f32x4*)&pbuf[pos * 8 + 4];
;           float vf[8];
; #pragma unroll
;           for (int e = 0; e < 8; ++e) vf[e] = (float)vv[i][e];
; #pragma unroll
;           for (int e = 0; e < 8; ++e) {
;             acc[0][e] += pa[0] * vf[e]; acc[1][e] += pa[1] * vf[e]; acc[2][e] += pa[2] * vf[e]; acc[3][e] += pa[3] * vf[e];
;             acc[4][e] += pb[0] * vf[e]; acc[5][e] += pb[1] * vf[e]; acc[6][e] += pb[2] * vf[e]; acc[7][e] += pb[3] * vf[e];
;           }
;         }
	v_cvt_f32_f16_e32 v48, v232
	v_cvt_f32_f16_sdwa v49, v232 dst_sel:DWORD dst_unused:UNUSED_PAD src0_sel:WORD_1
	v_pk_fma_f32 v[124:125], v[66:67], v[174:175], v[124:125] op_sel_hi:[0,1,1]
	v_pk_fma_f32 v[116:117], v[66:67], v[174:175], v[116:117] op_sel:[1,0,0]
	v_pk_fma_f32 v[110:111], v[68:69], v[174:175], v[110:111] op_sel_hi:[0,1,1]
	v_pk_fma_f32 v[104:105], v[194:195], v[142:143], v[104:105] op_sel_hi:[0,1,1]
	v_cvt_f32_f16_e32 v232, v233
	v_cvt_f32_f16_sdwa v233, v233 dst_sel:DWORD dst_unused:UNUSED_PAD src0_sel:WORD_1
	v_pk_fma_f32 v[216:217], v[74:75], v[190:191], v[216:217] op_sel_hi:[0,1,1]
	v_pk_fma_f32 v[228:229], v[74:75], v[190:191], v[228:229] op_sel:[1,0,0]
	v_pk_fma_f32 v[128:129], v[76:77], v[190:191], v[128:129] op_sel_hi:[0,1,1]
	v_pk_fma_f32 v[134:135], v[50:51], v[190:191], v[134:135] op_sel_hi:[0,1,1]
	v_pk_fma_f32 v[130:131], v[50:51], v[190:191], v[130:131] op_sel:[1,0,0]
	v_pk_fma_f32 v[124:125], v[70:71], v[178:179], v[124:125] op_sel_hi:[0,1,1]
	v_pk_fma_f32 v[116:117], v[70:71], v[178:179], v[116:117] op_sel:[1,0,0]
	v_pk_fma_f32 v[110:111], v[72:73], v[178:179], v[110:111] op_sel_hi:[0,1,1]
	v_pk_fma_f32 v[104:105], v[196:197], v[174:175], v[104:105] op_sel_hi:[0,1,1]
	v_pk_fma_f32 v[118:119], v[50:51], v[180:181], v[118:119] op_sel_hi:[0,1,1]
	v_pk_fma_f32 v[112:113], v[50:51], v[180:181], v[112:113] op_sel:[1,0,0]
	v_cvt_f32_f16_e32 v50, v234
	v_cvt_f32_f16_sdwa v51, v234 dst_sel:DWORD dst_unused:UNUSED_PAD src0_sel:WORD_1
	v_pk_fma_f32 v[216:217], v[78:79], v[192:193], v[216:217] op_sel_hi:[0,1,1]
	v_pk_fma_f32 v[228:229], v[78:79], v[192:193], v[228:229] op_sel:[1,0,0]
	v_pk_fma_f32 v[128:129], v[80:81], v[192:193], v[128:129] op_sel_hi:[0,1,1]
	v_pk_fma_f32 v[120:121], v[200:201], v[190:191], v[120:121] op_sel_hi:[0,1,1]
	v_pk_fma_f32 v[122:123], v[52:53], v[190:191], v[122:123] op_sel_hi:[0,1,1]
	v_pk_fma_f32 v[124:125], v[74:75], v[180:181], v[124:125] op_sel_hi:[0,1,1]
	v_pk_fma_f32 v[116:117], v[74:75], v[180:181], v[116:117] op_sel:[1,0,0]
	v_pk_fma_f32 v[110:111], v[76:77], v[180:181], v[110:111] op_sel_hi:[0,1,1]
	v_pk_fma_f32 v[104:105], v[198:199], v[178:179], v[104:105] op_sel_hi:[0,1,1]
	s_waitcnt lgkmcnt(3)
	v_mov_b32_e32 v38, v209
	s_waitcnt lgkmcnt(2)
	v_mov_b32_e32 v40, v213
	v_cvt_f32_f16_e32 v234, v235
	v_cvt_f32_f16_sdwa v235, v235 dst_sel:DWORD dst_unused:UNUSED_PAD src0_sel:WORD_1
	v_pk_fma_f32 v[204:205], v[212:213], v[36:37], v[204:205] op_sel_hi:[0,1,1]
	v_pk_fma_f32 v[120:121], v[202:203], v[192:193], v[120:121] op_sel_hi:[0,1,1]
	v_pk_fma_f32 v[134:135], v[54:55], v[192:193], v[134:135] op_sel_hi:[0,1,1]
	v_pk_fma_f32 v[130:131], v[54:55], v[192:193], v[130:131] op_sel:[1,0,0]
	v_pk_fma_f32 v[122:123], v[56:57], v[192:193], v[122:123] op_sel_hi:[0,1,1]
	v_pk_fma_f32 v[132:133], v[176:177], v[192:193], v[132:133] op_sel_hi:[0,1,1]
	v_pk_fma_f32 v[114:115], v[158:159], v[180:181], v[114:115] op_sel_hi:[0,1,1]
	v_pk_fma_f32 v[124:125], v[78:79], v[188:189], v[124:125] op_sel_hi:[0,1,1]
	v_pk_fma_f32 v[116:117], v[78:79], v[188:189], v[116:117] op_sel:[1,0,0]
	v_pk_fma_f32 v[110:111], v[80:81], v[188:189], v[110:111] op_sel_hi:[0,1,1]
	v_pk_fma_f32 v[104:105], v[200:201], v[180:181], v[104:105] op_sel_hi:[0,1,1]
	v_pk_fma_f32 v[118:119], v[54:55], v[188:189], v[118:119] op_sel_hi:[0,1,1]
	v_pk_fma_f32 v[112:113], v[54:55], v[188:189], v[112:113] op_sel:[1,0,0]
	v_pk_fma_f32 v[52:53], v[206:207], v[36:37], v[148:149] op_sel_hi:[0,1,1]
	v_pk_fma_f32 v[54:55], v[206:207], v[36:37], v[152:153] op_sel:[1,0,0]
	v_pk_fma_f32 v[56:57], v[208:209], v[36:37], v[146:147] op_sel_hi:[0,1,1]
	v_pk_fma_f32 v[66:67], v[38:39], v[36:37], v[140:141] op_sel_hi:[0,1,1]
	v_pk_fma_f32 v[68:69], v[210:211], v[36:37], v[150:151] op_sel_hi:[0,1,1]
	v_pk_fma_f32 v[70:71], v[210:211], v[36:37], v[144:145] op_sel:[1,0,0]
	v_pk_fma_f32 v[36:37], v[40:41], v[36:37], v[138:139] op_sel_hi:[0,1,1]
	s_waitcnt lgkmcnt(1)
	v_mov_b32_e32 v72, v221
	s_waitcnt lgkmcnt(0)
; __device__ __forceinline__ void dsa_item(const KP& p, int b, int tile, char* smem) {
;     ...
;         for (int i = 0; i < 8; ++i) {
;           const int pos = (g8 * 8 + i) * 8 + rs;
;           const f32x4 pa = *(const f32x4*)&pbuf[pos * 8];
;           const f32x4 pb = *(const f32x4*)&pbuf[pos * 8 + 4];
;           float vf[8];
; #pragma unroll
;           for (int e = 0; e < 8; ++e) vf[e] = (float)vv[i][e];
; #pragma unroll
;           for (int e = 0; e < 8; ++e) {
;             acc[0][e] += pa[0] * vf[e]; acc[1][e] += pa[1] * vf[e]; acc[2][e] += pa[2] * vf[e]; acc[3][e] += pa[3] * vf[e];
;             acc[4][e] += pb[0] * vf[e]; acc[5][e] += pb[1] * vf[e]; acc[6][e] += pb[2] * vf[e]; acc[7][e] += pb[3] * vf[e];
;           }
;         }
	v_mov_b32_e32 v74, v225
	v_pk_fma_f32 v[138:139], v[224:225], v[48:49], v[204:205] op_sel_hi:[0,1,1]
	v_pk_fma_f32 v[204:205], v[206:207], v[42:43], v[216:217] op_sel_hi:[0,1,1]
	v_pk_fma_f32 v[216:217], v[206:207], v[42:43], v[228:229] op_sel:[1,0,0]
	v_pk_fma_f32 v[228:229], v[208:209], v[42:43], v[128:129] op_sel_hi:[0,1,1]
	v_pk_fma_f32 v[104:105], v[202:203], v[188:189], v[104:105] op_sel_hi:[0,1,1]
	v_pk_fma_f32 v[114:115], v[176:177], v[188:189], v[114:115] op_sel_hi:[0,1,1]
	v_pk_fma_f32 v[154:155], v[218:219], v[48:49], v[52:53] op_sel_hi:[0,1,1]
	v_pk_fma_f32 v[152:153], v[218:219], v[48:49], v[54:55] op_sel:[1,0,0]
	v_pk_fma_f32 v[146:147], v[220:221], v[48:49], v[56:57] op_sel_hi:[0,1,1]
	v_pk_fma_f32 v[140:141], v[72:73], v[48:49], v[66:67] op_sel_hi:[0,1,1]
	v_pk_fma_f32 v[150:151], v[222:223], v[48:49], v[68:69] op_sel_hi:[0,1,1]
	v_pk_fma_f32 v[144:145], v[222:223], v[48:49], v[70:71] op_sel:[1,0,0]
	v_pk_fma_f32 v[148:149], v[74:75], v[48:49], v[36:37] op_sel_hi:[0,1,1]
	v_pk_fma_f32 v[36:37], v[38:39], v[42:43], v[120:121] op_sel_hi:[0,1,1]
	v_pk_fma_f32 v[48:49], v[210:211], v[42:43], v[134:135] op_sel_hi:[0,1,1]
	v_pk_fma_f32 v[52:53], v[210:211], v[42:43], v[130:131] op_sel:[1,0,0]
	v_pk_fma_f32 v[54:55], v[212:213], v[42:43], v[122:123] op_sel_hi:[0,1,1]
	v_pk_fma_f32 v[42:43], v[40:41], v[42:43], v[132:133] op_sel_hi:[0,1,1]
	v_pk_fma_f32 v[142:143], v[218:219], v[232:233], v[204:205] op_sel_hi:[0,1,1]
	v_pk_fma_f32 v[134:135], v[218:219], v[232:233], v[216:217] op_sel:[1,0,0]
	v_pk_fma_f32 v[128:129], v[220:221], v[232:233], v[228:229] op_sel_hi:[0,1,1]
	v_pk_fma_f32 v[204:205], v[206:207], v[44:45], v[124:125] op_sel_hi:[0,1,1]
	v_pk_fma_f32 v[216:217], v[206:207], v[44:45], v[116:117] op_sel:[1,0,0]
	v_pk_fma_f32 v[228:229], v[208:209], v[44:45], v[110:111] op_sel_hi:[0,1,1]
	v_pk_fma_f32 v[120:121], v[72:73], v[232:233], v[36:37] op_sel_hi:[0,1,1]
	v_pk_fma_f32 v[136:137], v[222:223], v[232:233], v[48:49] op_sel_hi:[0,1,1]
	v_pk_fma_f32 v[130:131], v[222:223], v[232:233], v[52:53] op_sel:[1,0,0]
	v_pk_fma_f32 v[122:123], v[224:225], v[232:233], v[54:55] op_sel_hi:[0,1,1]
	v_pk_fma_f32 v[132:133], v[74:75], v[232:233], v[42:43] op_sel_hi:[0,1,1]
	v_pk_fma_f32 v[232:233], v[38:39], v[44:45], v[104:105] op_sel_hi:[0,1,1]
	v_pk_fma_f32 v[36:37], v[210:211], v[44:45], v[118:119] op_sel_hi:[0,1,1]
	v_pk_fma_f32 v[42:43], v[210:211], v[44:45], v[112:113] op_sel:[1,0,0]
	v_pk_fma_f32 v[48:49], v[212:213], v[44:45], v[106:107] op_sel_hi:[0,1,1]
	v_pk_fma_f32 v[44:45], v[40:41], v[44:45], v[114:115] op_sel_hi:[0,1,1]
	v_pk_fma_f32 v[124:125], v[218:219], v[50:51], v[204:205] op_sel_hi:[0,1,1]
	v_pk_fma_f32 v[116:117], v[218:219], v[50:51], v[216:217] op_sel:[1,0,0]
	v_pk_fma_f32 v[110:111], v[220:221], v[50:51], v[228:229] op_sel_hi:[0,1,1]
	v_pk_fma_f32 v[204:205], v[206:207], v[46:47], v[230:231] op_sel_hi:[0,1,1]
	v_pk_fma_f32 v[206:207], v[206:207], v[46:47], v[58:59] op_sel:[1,0,0]
	v_pk_fma_f32 v[208:209], v[208:209], v[46:47], v[60:61] op_sel_hi:[0,1,1]
	v_pk_fma_f32 v[216:217], v[38:39], v[46:47], v[62:63] op_sel_hi:[0,1,1]
	v_pk_fma_f32 v[228:229], v[210:211], v[46:47], v[64:65] op_sel_hi:[0,1,1]
	v_pk_fma_f32 v[210:211], v[210:211], v[46:47], v[34:35] op_sel:[1,0,0]
	v_pk_fma_f32 v[212:213], v[212:213], v[46:47], v[214:215] op_sel_hi:[0,1,1]
	v_pk_fma_f32 v[214:215], v[40:41], v[46:47], v[226:227] op_sel_hi:[0,1,1]
	v_pk_fma_f32 v[104:105], v[72:73], v[50:51], v[232:233] op_sel_hi:[0,1,1]
	v_pk_fma_f32 v[118:119], v[222:223], v[50:51], v[36:37] op_sel_hi:[0,1,1]
	v_pk_fma_f32 v[112:113], v[222:223], v[50:51], v[42:43] op_sel:[1,0,0]
	v_pk_fma_f32 v[106:107], v[224:225], v[50:51], v[48:49] op_sel_hi:[0,1,1]
	v_pk_fma_f32 v[114:115], v[74:75], v[50:51], v[44:45] op_sel_hi:[0,1,1]
	v_pk_fma_f32 v[108:109], v[218:219], v[234:235], v[204:205] op_sel_hi:[0,1,1]
	v_pk_fma_f32 v[100:101], v[218:219], v[234:235], v[206:207] op_sel:[1,0,0]
	v_pk_fma_f32 v[94:95], v[220:221], v[234:235], v[208:209] op_sel_hi:[0,1,1]
	v_pk_fma_f32 v[90:91], v[72:73], v[234:235], v[216:217] op_sel_hi:[0,1,1]
	v_pk_fma_f32 v[102:103], v[222:223], v[234:235], v[228:229] op_sel_hi:[0,1,1]
	v_pk_fma_f32 v[96:97], v[222:223], v[234:235], v[210:211] op_sel:[1,0,0]
	v_pk_fma_f32 v[92:93], v[224:225], v[234:235], v[212:213] op_sel_hi:[0,1,1]
	v_pk_fma_f32 v[98:99], v[74:75], v[234:235], v[214:215] op_sel_hi:[0,1,1]
	v_add_u32_e32 v172, 0x800, v172
	s_branch .LBB0_1424
